# barrier: cross-XCD generation word polled by every workgroup, per-XCD release hop removed; loop heads pinned to previous placement
# speedup vs baseline: 1.0167x; 1.0167x over previous
; #define PG8_STAGE(bufoff, gbase, voff) do { _Pragma("unroll") for (int _i = 0; _i < 2; ++_i) \
;         __builtin_amdgcn_global_load_lds((const unsigned*)((const char*)(gbase) + (voff)[_i]), (LAS unsigned*)(lds + (bufoff) + ldsw + _i * 8192), 16, 0, 0); } while (0)
; #define PG8_LDA(dst, b, h) do { _Pragma("unroll") for (int m = 0; m < 4; ++m) _Pragma("unroll") for (int k = 0; k < 2; ++k) dst[m][k] = *(const LAS bf16x8*)(lds + PG8_SA(b, h) + aoff + m * 2048 + k * 1024); } while (0)
; #define PG8_LDB(dst, b, h) do { _Pragma("unroll") for (int n = 0; n < 2; ++n) _Pragma("unroll") for (int k = 0; k < 2; ++k) dst[n][k] = *(const LAS bf16x8*)(lds + PG8_SB(b, h) + boff + n * 2048 + k * 1024); } while (0)
; #define PG8_MMA(ai, bj, At, Bt) do { __builtin_amdgcn_s_setprio(1); _Pragma("unroll") for (int m = 0; m < 4; ++m) _Pragma("unroll") for (int n = 0; n < 2; ++n) _Pragma("unroll") for (int k = 0; k < 2; ++k) \
;         acc[ai][bj][m][n] = __builtin_amdgcn_mfma_f32_16x16x32_bf16(Bt[n][k], At[m][k], acc[ai][bj][m][n], 0, 0, 0); __builtin_amdgcn_s_setprio(0); } while (0)
; #define PG8_WAIT_V(n) asm volatile("s_waitcnt vmcnt(" #n ")" ::: "memory")
; #define PG8_WAIT_L(n) asm volatile("s_waitcnt lgkmcnt(" #n ")" ::: "memory")
; #define PG8_BAR __builtin_amdgcn_s_barrier()
; #define PG8_SCHED __builtin_amdgcn_sched_barrier(0)
; template <class EpiT>
; __device__ __forceinline__ void gemm_phase(LAS unsigned char* lds, const Gemm g, const StaticOrder& S, const EpiT& E) {
;     ...
;         for (int t = 0; t < nt; t += 2) {
;             const bool last = (t == nt - 2);
;             const char* a1 = cA + (size_t)(t + 1) * kstep;
;             const char* a2 = last ? nA : cA + (size_t)(t + 2) * kstep; const char* b2 = last ? nB : cB + (size_t)(t + 2) * kstep;
;             const char* a3 = a2 + kstep; const char* b3 = b2 + kstep;
;             PG8_LDB(B0, 0, 0); PG8_LDB(B1, 0, 1); PG8_SCHED; PG8_LDA(At, 0, 0); PG8_STAGE(PG8_SA(1, 1), a1 + hstepA, voffA);
;             PG8_WAIT_V(8); PG8_WAIT_L(0); PG8_BAR; PG8_MMA(0, 0, At, B0); PG8_MMA(0, 1, At, B1); PG8_BAR; PG8_SCHED;
.LBB0_99:
	s_add_u32 s16, s16, 0x84080
	s_addc_u32 s17, s17, 0
	s_add_u32 s51, s18, 0x100
	v_mov_b32_e32 v0, 0
	s_addc_u32 s52, s19, 0
	s_mov_b32 s53, -2
	v_mov_b32_e32 v1, v0
	v_mov_b32_e32 v2, v0
	v_mov_b32_e32 v3, v0
	v_mov_b32_e32 v4, v0
	v_mov_b32_e32 v5, v0
	v_mov_b32_e32 v6, v0
	v_mov_b32_e32 v7, v0
	v_mov_b32_e32 v16, v0
	v_mov_b32_e32 v17, v0
	v_mov_b32_e32 v18, v0
	v_mov_b32_e32 v19, v0
	v_mov_b32_e32 v20, v0
	v_mov_b32_e32 v21, v0
	v_mov_b32_e32 v22, v0
	v_mov_b32_e32 v23, v0
	v_mov_b32_e32 v32, v0
	v_mov_b32_e32 v33, v0
	v_mov_b32_e32 v34, v0
	v_mov_b32_e32 v35, v0
	v_mov_b32_e32 v36, v0
	v_mov_b32_e32 v37, v0
	v_mov_b32_e32 v38, v0
	v_mov_b32_e32 v39, v0
	v_mov_b32_e32 v48, v0
	v_mov_b32_e32 v49, v0
	v_mov_b32_e32 v50, v0
	v_mov_b32_e32 v51, v0
	v_mov_b32_e32 v52, v0
	v_mov_b32_e32 v53, v0
	v_mov_b32_e32 v54, v0
	v_mov_b32_e32 v55, v0
	v_mov_b32_e32 v8, v0
	v_mov_b32_e32 v9, v0
	v_mov_b32_e32 v10, v0
	v_mov_b32_e32 v11, v0
	v_mov_b32_e32 v12, v0
	v_mov_b32_e32 v13, v0
	v_mov_b32_e32 v14, v0
	v_mov_b32_e32 v15, v0
	v_mov_b32_e32 v24, v0
	v_mov_b32_e32 v25, v0
	v_mov_b32_e32 v26, v0
	v_mov_b32_e32 v27, v0
	v_mov_b32_e32 v28, v0
	v_mov_b32_e32 v29, v0
	v_mov_b32_e32 v30, v0
	v_mov_b32_e32 v31, v0
	v_mov_b32_e32 v40, v0
	v_mov_b32_e32 v41, v0
	v_mov_b32_e32 v42, v0
	v_mov_b32_e32 v43, v0
	v_mov_b32_e32 v44, v0
	v_mov_b32_e32 v45, v0
	v_mov_b32_e32 v46, v0
	v_mov_b32_e32 v47, v0
	v_mov_b32_e32 v56, v0
	v_mov_b32_e32 v57, v0
	v_mov_b32_e32 v58, v0
	v_mov_b32_e32 v59, v0
	v_mov_b32_e32 v60, v0
	v_mov_b32_e32 v61, v0
	v_mov_b32_e32 v62, v0
	v_mov_b32_e32 v63, v0
	v_mov_b32_e32 v64, v0
	v_mov_b32_e32 v65, v0
	v_mov_b32_e32 v66, v0
	v_mov_b32_e32 v67, v0
	v_mov_b32_e32 v68, v0
	v_mov_b32_e32 v69, v0
	v_mov_b32_e32 v70, v0
	v_mov_b32_e32 v71, v0
	v_mov_b32_e32 v80, v0
	v_mov_b32_e32 v81, v0
	v_mov_b32_e32 v82, v0
	v_mov_b32_e32 v83, v0
	v_mov_b32_e32 v84, v0
	v_mov_b32_e32 v85, v0
	v_mov_b32_e32 v86, v0
	v_mov_b32_e32 v87, v0
	v_mov_b32_e32 v96, v0
	v_mov_b32_e32 v97, v0
	v_mov_b32_e32 v98, v0
	v_mov_b32_e32 v99, v0
	v_mov_b32_e32 v100, v0
	v_mov_b32_e32 v101, v0
	v_mov_b32_e32 v102, v0
	v_mov_b32_e32 v103, v0
	v_mov_b32_e32 v112, v0
	v_mov_b32_e32 v113, v0
	v_mov_b32_e32 v114, v0
	v_mov_b32_e32 v115, v0
	v_mov_b32_e32 v116, v0
	v_mov_b32_e32 v117, v0
	v_mov_b32_e32 v118, v0
	v_mov_b32_e32 v119, v0
	v_mov_b32_e32 v72, v0
	v_mov_b32_e32 v73, v0
	v_mov_b32_e32 v74, v0
	v_mov_b32_e32 v75, v0
	v_mov_b32_e32 v76, v0
	v_mov_b32_e32 v77, v0
	v_mov_b32_e32 v78, v0
	v_mov_b32_e32 v79, v0
	v_mov_b32_e32 v88, v0
	v_mov_b32_e32 v89, v0
	v_mov_b32_e32 v90, v0
	v_mov_b32_e32 v91, v0
	v_mov_b32_e32 v92, v0
	v_mov_b32_e32 v93, v0
	v_mov_b32_e32 v94, v0
	v_mov_b32_e32 v95, v0
	v_mov_b32_e32 v104, v0
	v_mov_b32_e32 v105, v0
	v_mov_b32_e32 v106, v0
	v_mov_b32_e32 v107, v0
	v_mov_b32_e32 v108, v0
	v_mov_b32_e32 v109, v0
	v_mov_b32_e32 v110, v0
	v_mov_b32_e32 v111, v0
	v_mov_b32_e32 v120, v0
	v_mov_b32_e32 v121, v0
	v_mov_b32_e32 v122, v0
	v_mov_b32_e32 v123, v0
	v_mov_b32_e32 v124, v0
	v_mov_b32_e32 v125, v0
	v_mov_b32_e32 v126, v0
	v_mov_b32_e32 v127, v0
	.p2alignl 6, 3212836864
	s_nop 0
	s_nop 0
	s_nop 0
	s_nop 0
	s_nop 0
	s_nop 0
	s_nop 0
	s_nop 0
	s_nop 0
	s_nop 0
	s_nop 0
.LBB0_100:
	ds_read_b128 v[128:131], v160
	ds_read_b128 v[170:173], v160 offset:1024
	ds_read_b128 v[174:177], v160 offset:2048
	ds_read_b128 v[178:181], v160 offset:3072
	ds_read_b128 v[182:185], v161
	ds_read_b128 v[186:189], v161 offset:1024
	ds_read_b128 v[190:193], v161 offset:2048
	ds_read_b128 v[194:197], v161 offset:3072
	s_add_u32 s18, s16, 0xfff7c080
	s_addc_u32 s19, s17, -1
	s_cmp_eq_u32 s53, 28
	s_cselect_b32 s21, s3, s19
	s_cselect_b32 s20, s2, s18
	s_cselect_b32 s19, s15, s52
	s_cselect_b32 s18, s14, s51
	v_lshl_add_u64 v[158:159], s[16:17], 0, v[150:151]
	s_add_i32 m0, s35, 0xc000
	ds_read_b128 v[198:201], v162
	ds_read_b128 v[202:205], v162 offset:1024
	ds_read_b128 v[206:209], v162 offset:2048
	ds_read_b128 v[210:213], v162 offset:3072
	ds_read_b128 v[214:217], v162 offset:4096
	ds_read_b128 v[218:221], v162 offset:5120
	ds_read_b128 v[222:225], v162 offset:6144
	ds_read_b128 v[226:229], v162 offset:7168
	global_load_lds_dwordx4 v[158:159], off
	v_lshl_add_u64 v[158:159], s[16:17], 0, v[152:153]
	s_add_i32 m0, s35, 0xe000
	s_nop 0
	global_load_lds_dwordx4 v[158:159], off
	s_waitcnt vmcnt(8)
	s_waitcnt lgkmcnt(0)
	s_barrier
	s_setprio 1
	s_waitcnt lgkmcnt(0)
	v_mfma_f32_16x16x32_bf16 v[124:127], v[128:131], v[198:201], v[124:127]
	v_mfma_f32_16x16x32_bf16 v[120:123], v[174:177], v[198:201], v[120:123]
	v_mfma_f32_16x16x32_bf16 v[108:111], v[128:131], v[206:209], v[108:111]
	v_mfma_f32_16x16x32_bf16 v[104:107], v[174:177], v[206:209], v[104:107]
	v_mfma_f32_16x16x32_bf16 v[92:95], v[128:131], v[214:217], v[92:95]
	v_mfma_f32_16x16x32_bf16 v[88:91], v[174:177], v[214:217], v[88:91]
	v_mfma_f32_16x16x32_bf16 v[76:79], v[128:131], v[222:225], v[76:79]
	v_mfma_f32_16x16x32_bf16 v[72:75], v[174:177], v[222:225], v[72:75]
	v_mfma_f32_16x16x32_bf16 v[124:127], v[170:173], v[202:205], v[124:127]
	v_mfma_f32_16x16x32_bf16 v[120:123], v[178:181], v[202:205], v[120:123]
	v_mfma_f32_16x16x32_bf16 v[108:111], v[170:173], v[210:213], v[108:111]
	v_mfma_f32_16x16x32_bf16 v[104:107], v[178:181], v[210:213], v[104:107]
	v_mfma_f32_16x16x32_bf16 v[92:95], v[170:173], v[218:221], v[92:95]
	v_mfma_f32_16x16x32_bf16 v[88:91], v[178:181], v[218:221], v[88:91]
	v_mfma_f32_16x16x32_bf16 v[76:79], v[170:173], v[226:229], v[76:79]
	v_mfma_f32_16x16x32_bf16 v[72:75], v[178:181], v[226:229], v[72:75]
	s_setprio 0
	s_setprio 1
	v_mfma_f32_16x16x32_bf16 v[116:119], v[182:185], v[198:201], v[116:119]
	v_mfma_f32_16x16x32_bf16 v[112:115], v[190:193], v[198:201], v[112:115]
	v_mfma_f32_16x16x32_bf16 v[100:103], v[182:185], v[206:209], v[100:103]
	v_mfma_f32_16x16x32_bf16 v[96:99], v[190:193], v[206:209], v[96:99]
	v_mfma_f32_16x16x32_bf16 v[84:87], v[182:185], v[214:217], v[84:87]
	v_mfma_f32_16x16x32_bf16 v[80:83], v[190:193], v[214:217], v[80:83]
	v_mfma_f32_16x16x32_bf16 v[68:71], v[182:185], v[222:225], v[68:71]
	v_mfma_f32_16x16x32_bf16 v[64:67], v[190:193], v[222:225], v[64:67]
	v_mfma_f32_16x16x32_bf16 v[116:119], v[186:189], v[202:205], v[116:119]
	v_mfma_f32_16x16x32_bf16 v[112:115], v[194:197], v[202:205], v[112:115]
	v_mfma_f32_16x16x32_bf16 v[100:103], v[186:189], v[210:213], v[100:103]
	v_mfma_f32_16x16x32_bf16 v[96:99], v[194:197], v[210:213], v[96:99]
	v_mfma_f32_16x16x32_bf16 v[84:87], v[186:189], v[218:221], v[84:87]
	v_mfma_f32_16x16x32_bf16 v[80:83], v[194:197], v[218:221], v[80:83]
	v_mfma_f32_16x16x32_bf16 v[68:71], v[186:189], v[226:229], v[68:71]
	v_mfma_f32_16x16x32_bf16 v[64:67], v[194:197], v[226:229], v[64:67]
	s_setprio 0
	s_barrier
; #define PG8_STAGE(bufoff, gbase, voff) do { _Pragma("unroll") for (int _i = 0; _i < 2; ++_i) \
;         __builtin_amdgcn_global_load_lds((const unsigned*)((const char*)(gbase) + (voff)[_i]), (LAS unsigned*)(lds + (bufoff) + ldsw + _i * 8192), 16, 0, 0); } while (0)
; #define PG8_LDA(dst, b, h) do { _Pragma("unroll") for (int m = 0; m < 4; ++m) _Pragma("unroll") for (int k = 0; k < 2; ++k) dst[m][k] = *(const LAS bf16x8*)(lds + PG8_SA(b, h) + aoff + m * 2048 + k * 1024); } while (0)
; #define PG8_LDB(dst, b, h) do { _Pragma("unroll") for (int n = 0; n < 2; ++n) _Pragma("unroll") for (int k = 0; k < 2; ++k) dst[n][k] = *(const LAS bf16x8*)(lds + PG8_SB(b, h) + boff + n * 2048 + k * 1024); } while (0)
; #define PG8_MMA(ai, bj, At, Bt) do { __builtin_amdgcn_s_setprio(1); _Pragma("unroll") for (int m = 0; m < 4; ++m) _Pragma("unroll") for (int n = 0; n < 2; ++n) _Pragma("unroll") for (int k = 0; k < 2; ++k) \
;         acc[ai][bj][m][n] = __builtin_amdgcn_mfma_f32_16x16x32_bf16(Bt[n][k], At[m][k], acc[ai][bj][m][n], 0, 0, 0); __builtin_amdgcn_s_setprio(0); } while (0)
; #define PG8_WAIT_V(n) asm volatile("s_waitcnt vmcnt(" #n ")" ::: "memory")
; #define PG8_WAIT_L(n) asm volatile("s_waitcnt lgkmcnt(" #n ")" ::: "memory")
; #define PG8_BAR __builtin_amdgcn_s_barrier()
; #define PG8_SCHED __builtin_amdgcn_sched_barrier(0)
; template <class EpiT>
; __device__ __forceinline__ void gemm_phase(LAS unsigned char* lds, const Gemm g, const StaticOrder& S, const EpiT& E) {
;     ...
;             PG8_LDA(At, 0, 1); PG8_STAGE(PG8_SB(0, 0), b2, voffB); PG8_STAGE(PG8_SB(0, 1), b2 + hstepB, voffB); PG8_STAGE(PG8_SA(0, 0), a2, voffA);
;             PG8_WAIT_V(8); PG8_WAIT_L(0); PG8_BAR; PG8_MMA(1, 0, At, B0); PG8_MMA(1, 1, At, B1); PG8_BAR; PG8_SCHED;
;             PG8_LDB(B0, 1, 0); PG8_LDB(B1, 1, 1); PG8_SCHED; PG8_LDA(At, 1, 0); PG8_STAGE(PG8_SA(0, 1), a2 + hstepA, voffA);
;             PG8_WAIT_V(8); PG8_WAIT_L(0); PG8_BAR; PG8_MMA(0, 0, At, B0); PG8_MMA(0, 1, At, B1); PG8_BAR; PG8_SCHED;
	s_add_i32 s54, s43, s25
	v_lshl_add_u64 v[158:159], s[18:19], 0, v[136:137]
	s_mov_b32 m0, s54
	ds_read_b128 v[198:201], v162 offset:16384
	ds_read_b128 v[202:205], v162 offset:17408
	ds_read_b128 v[206:209], v162 offset:18432
	ds_read_b128 v[210:213], v162 offset:19456
	ds_read_b128 v[214:217], v162 offset:20480
	ds_read_b128 v[218:221], v162 offset:21504
	ds_read_b128 v[222:225], v162 offset:22528
	ds_read_b128 v[226:229], v162 offset:23552
	global_load_lds_dwordx4 v[158:159], off
	s_add_i32 m0, s54, 0x2000
	s_add_u32 s54, s18, 0x84000
	v_lshl_add_u64 v[166:167], s[18:19], 0, v[132:133]
	s_addc_u32 s55, s19, 0
	s_add_i32 s56, s44, s25
	global_load_lds_dwordx4 v[166:167], off
	v_lshl_add_u64 v[230:231], s[54:55], 0, v[136:137]
	s_mov_b32 m0, s56
	v_lshl_add_u64 v[232:233], s[20:21], 0, v[134:135]
	global_load_lds_dwordx4 v[230:231], off
	v_lshl_add_u64 v[230:231], s[54:55], 0, v[132:133]
	s_add_i32 m0, s56, 0x2000
	s_nop 0
	global_load_lds_dwordx4 v[230:231], off
	v_lshl_add_u64 v[230:231], s[20:21], 0, v[138:139]
	s_mov_b32 m0, s35
	s_nop 0
	global_load_lds_dwordx4 v[230:231], off
	s_mov_b32 m0, s36
	s_nop 0
	global_load_lds_dwordx4 v[232:233], off
	s_waitcnt vmcnt(8)
	s_waitcnt lgkmcnt(0)
	s_barrier
	s_setprio 1
	s_waitcnt lgkmcnt(0)
	v_mfma_f32_16x16x32_bf16 v[60:63], v[128:131], v[198:201], v[60:63]
	v_mfma_f32_16x16x32_bf16 v[56:59], v[174:177], v[198:201], v[56:59]
	v_mfma_f32_16x16x32_bf16 v[44:47], v[128:131], v[206:209], v[44:47]
	v_mfma_f32_16x16x32_bf16 v[40:43], v[174:177], v[206:209], v[40:43]
	v_mfma_f32_16x16x32_bf16 v[28:31], v[128:131], v[214:217], v[28:31]
	v_mfma_f32_16x16x32_bf16 v[24:27], v[174:177], v[214:217], v[24:27]
	v_mfma_f32_16x16x32_bf16 v[12:15], v[128:131], v[222:225], v[12:15]
	v_mfma_f32_16x16x32_bf16 v[8:11], v[174:177], v[222:225], v[8:11]
	v_mfma_f32_16x16x32_bf16 v[60:63], v[170:173], v[202:205], v[60:63]
	v_mfma_f32_16x16x32_bf16 v[56:59], v[178:181], v[202:205], v[56:59]
	v_mfma_f32_16x16x32_bf16 v[44:47], v[170:173], v[210:213], v[44:47]
	v_mfma_f32_16x16x32_bf16 v[40:43], v[178:181], v[210:213], v[40:43]
	v_mfma_f32_16x16x32_bf16 v[28:31], v[170:173], v[218:221], v[28:31]
	v_mfma_f32_16x16x32_bf16 v[24:27], v[178:181], v[218:221], v[24:27]
	v_mfma_f32_16x16x32_bf16 v[12:15], v[170:173], v[226:229], v[12:15]
	v_mfma_f32_16x16x32_bf16 v[8:11], v[178:181], v[226:229], v[8:11]
	s_setprio 0
	s_setprio 1
	v_mfma_f32_16x16x32_bf16 v[52:55], v[182:185], v[198:201], v[52:55]
	v_mfma_f32_16x16x32_bf16 v[48:51], v[190:193], v[198:201], v[48:51]
	v_mfma_f32_16x16x32_bf16 v[36:39], v[182:185], v[206:209], v[36:39]
	v_mfma_f32_16x16x32_bf16 v[32:35], v[190:193], v[206:209], v[32:35]
	v_mfma_f32_16x16x32_bf16 v[20:23], v[182:185], v[214:217], v[20:23]
	v_mfma_f32_16x16x32_bf16 v[16:19], v[190:193], v[214:217], v[16:19]
	v_mfma_f32_16x16x32_bf16 v[4:7], v[182:185], v[222:225], v[4:7]
	v_mfma_f32_16x16x32_bf16 v[0:3], v[190:193], v[222:225], v[0:3]
	v_mfma_f32_16x16x32_bf16 v[52:55], v[186:189], v[202:205], v[52:55]
	v_mfma_f32_16x16x32_bf16 v[48:51], v[194:197], v[202:205], v[48:51]
	v_mfma_f32_16x16x32_bf16 v[36:39], v[186:189], v[210:213], v[36:39]
	v_mfma_f32_16x16x32_bf16 v[32:35], v[194:197], v[210:213], v[32:35]
	v_mfma_f32_16x16x32_bf16 v[20:23], v[186:189], v[218:221], v[20:23]
	v_mfma_f32_16x16x32_bf16 v[16:19], v[194:197], v[218:221], v[16:19]
	v_mfma_f32_16x16x32_bf16 v[4:7], v[186:189], v[226:229], v[4:7]
	v_mfma_f32_16x16x32_bf16 v[0:3], v[194:197], v[226:229], v[0:3]
	s_setprio 0
	s_barrier
	s_add_i32 s54, 0, 0x18000
	v_add_u32_e32 v140, s54, v145
	s_add_i32 s55, 0, 0x1c000
	ds_read_b128 v[128:131], v140
	ds_read_b128 v[170:173], v140 offset:1024
	ds_read_b128 v[174:177], v140 offset:2048
	ds_read_b128 v[178:181], v140 offset:3072
	v_add_u32_e32 v140, s55, v145
	ds_read_b128 v[182:185], v140
	ds_read_b128 v[186:189], v140 offset:1024
	ds_read_b128 v[190:193], v140 offset:2048
	ds_read_b128 v[194:197], v140 offset:3072
	s_add_u32 s20, s20, 0x84000
	s_addc_u32 s21, s21, 0
	s_mov_b32 m0, s37
	v_lshl_add_u64 v[234:235], s[20:21], 0, v[138:139]
	ds_read_b128 v[198:201], v162 offset:32768
	ds_read_b128 v[202:205], v162 offset:33792
	ds_read_b128 v[206:209], v162 offset:34816
	ds_read_b128 v[210:213], v162 offset:35840
	ds_read_b128 v[214:217], v162 offset:36864
	ds_read_b128 v[218:221], v162 offset:37888
	ds_read_b128 v[222:225], v162 offset:38912
	ds_read_b128 v[226:229], v162 offset:39936
	global_load_lds_dwordx4 v[234:235], off
	v_lshl_add_u64 v[234:235], s[20:21], 0, v[134:135]
	s_mov_b32 m0, s38
	s_nop 0
	global_load_lds_dwordx4 v[234:235], off
	s_waitcnt vmcnt(8)
	s_waitcnt lgkmcnt(0)
	s_barrier
; #define PG8_STAGE(bufoff, gbase, voff) do { _Pragma("unroll") for (int _i = 0; _i < 2; ++_i) \
;         __builtin_amdgcn_global_load_lds((const unsigned*)((const char*)(gbase) + (voff)[_i]), (LAS unsigned*)(lds + (bufoff) + ldsw + _i * 8192), 16, 0, 0); } while (0)
; #define PG8_LDA(dst, b, h) do { _Pragma("unroll") for (int m = 0; m < 4; ++m) _Pragma("unroll") for (int k = 0; k < 2; ++k) dst[m][k] = *(const LAS bf16x8*)(lds + PG8_SA(b, h) + aoff + m * 2048 + k * 1024); } while (0)
; #define PG8_MMA(ai, bj, At, Bt) do { __builtin_amdgcn_s_setprio(1); _Pragma("unroll") for (int m = 0; m < 4; ++m) _Pragma("unroll") for (int n = 0; n < 2; ++n) _Pragma("unroll") for (int k = 0; k < 2; ++k) \
;         acc[ai][bj][m][n] = __builtin_amdgcn_mfma_f32_16x16x32_bf16(Bt[n][k], At[m][k], acc[ai][bj][m][n], 0, 0, 0); __builtin_amdgcn_s_setprio(0); } while (0)
; #define PG8_WAIT_V(n) asm volatile("s_waitcnt vmcnt(" #n ")" ::: "memory")
; #define PG8_WAIT_L(n) asm volatile("s_waitcnt lgkmcnt(" #n ")" ::: "memory")
; #define PG8_BAR __builtin_amdgcn_s_barrier()
; #define PG8_SCHED __builtin_amdgcn_sched_barrier(0)
; template <class EpiT>
; __device__ __forceinline__ void gemm_phase(LAS unsigned char* lds, const Gemm g, const StaticOrder& S, const EpiT& E) {
;     ...
;             PG8_WAIT_V(8); PG8_WAIT_L(0); PG8_BAR; PG8_MMA(0, 0, At, B0); PG8_MMA(0, 1, At, B1); PG8_BAR; PG8_SCHED;
;             PG8_LDA(At, 1, 1); PG8_STAGE(PG8_SB(1, 0), b3, voffB); PG8_STAGE(PG8_SB(1, 1), b3 + hstepB, voffB); PG8_STAGE(PG8_SA(1, 0), a3, voffA);
;             PG8_WAIT_V(8); PG8_WAIT_L(0); PG8_BAR; PG8_MMA(1, 0, At, B0); PG8_MMA(1, 1, At, B1); PG8_BAR; PG8_SCHED;
;         }
;         if (wr == 0) PG8_BAR;
	s_setprio 1
	s_waitcnt lgkmcnt(0)
	v_mfma_f32_16x16x32_bf16 v[124:127], v[128:131], v[198:201], v[124:127]
	v_mfma_f32_16x16x32_bf16 v[120:123], v[174:177], v[198:201], v[120:123]
	v_mfma_f32_16x16x32_bf16 v[108:111], v[128:131], v[206:209], v[108:111]
	v_mfma_f32_16x16x32_bf16 v[104:107], v[174:177], v[206:209], v[104:107]
	v_mfma_f32_16x16x32_bf16 v[92:95], v[128:131], v[214:217], v[92:95]
	v_mfma_f32_16x16x32_bf16 v[88:91], v[174:177], v[214:217], v[88:91]
	v_mfma_f32_16x16x32_bf16 v[76:79], v[128:131], v[222:225], v[76:79]
	v_mfma_f32_16x16x32_bf16 v[72:75], v[174:177], v[222:225], v[72:75]
	v_mfma_f32_16x16x32_bf16 v[124:127], v[170:173], v[202:205], v[124:127]
	v_mfma_f32_16x16x32_bf16 v[120:123], v[178:181], v[202:205], v[120:123]
	v_mfma_f32_16x16x32_bf16 v[108:111], v[170:173], v[210:213], v[108:111]
	v_mfma_f32_16x16x32_bf16 v[104:107], v[178:181], v[210:213], v[104:107]
	v_mfma_f32_16x16x32_bf16 v[92:95], v[170:173], v[218:221], v[92:95]
	v_mfma_f32_16x16x32_bf16 v[88:91], v[178:181], v[218:221], v[88:91]
	v_mfma_f32_16x16x32_bf16 v[76:79], v[170:173], v[226:229], v[76:79]
	v_mfma_f32_16x16x32_bf16 v[72:75], v[178:181], v[226:229], v[72:75]
	s_setprio 0
	s_setprio 1
	v_mfma_f32_16x16x32_bf16 v[116:119], v[182:185], v[198:201], v[116:119]
	v_mfma_f32_16x16x32_bf16 v[112:115], v[190:193], v[198:201], v[112:115]
	v_mfma_f32_16x16x32_bf16 v[100:103], v[182:185], v[206:209], v[100:103]
	v_mfma_f32_16x16x32_bf16 v[96:99], v[190:193], v[206:209], v[96:99]
	v_mfma_f32_16x16x32_bf16 v[84:87], v[182:185], v[214:217], v[84:87]
	v_mfma_f32_16x16x32_bf16 v[80:83], v[190:193], v[214:217], v[80:83]
	v_mfma_f32_16x16x32_bf16 v[68:71], v[182:185], v[222:225], v[68:71]
	v_mfma_f32_16x16x32_bf16 v[64:67], v[190:193], v[222:225], v[64:67]
	v_mfma_f32_16x16x32_bf16 v[116:119], v[186:189], v[202:205], v[116:119]
	v_mfma_f32_16x16x32_bf16 v[112:115], v[194:197], v[202:205], v[112:115]
	v_mfma_f32_16x16x32_bf16 v[100:103], v[186:189], v[210:213], v[100:103]
	v_mfma_f32_16x16x32_bf16 v[96:99], v[194:197], v[210:213], v[96:99]
	v_mfma_f32_16x16x32_bf16 v[84:87], v[186:189], v[218:221], v[84:87]
	v_mfma_f32_16x16x32_bf16 v[80:83], v[194:197], v[218:221], v[80:83]
	v_mfma_f32_16x16x32_bf16 v[68:71], v[186:189], v[226:229], v[68:71]
	v_mfma_f32_16x16x32_bf16 v[64:67], v[194:197], v[226:229], v[64:67]
	s_setprio 0
	s_barrier
	s_add_i32 s20, s54, s25
	v_lshl_add_u64 v[158:159], v[158:159], 0, s[10:11]
	s_mov_b32 m0, s20
	ds_read_b128 v[198:201], v162 offset:49152
	ds_read_b128 v[202:205], v162 offset:50176
	ds_read_b128 v[206:209], v162 offset:51200
	ds_read_b128 v[210:213], v162 offset:52224
	ds_read_b128 v[214:217], v162 offset:53248
	ds_read_b128 v[218:221], v162 offset:54272
	ds_read_b128 v[222:225], v162 offset:55296
	ds_read_b128 v[226:229], v162 offset:56320
	global_load_lds_dwordx4 v[158:159], off
	s_add_i32 m0, s20, 0x2000
	s_add_u32 s18, s18, 0x84080
	v_lshl_add_u64 v[158:159], v[166:167], 0, s[10:11]
	s_addc_u32 s19, s19, 0
	s_add_i32 s20, s55, s25
	global_load_lds_dwordx4 v[158:159], off
	v_lshl_add_u64 v[158:159], s[18:19], 0, v[136:137]
	s_mov_b32 m0, s20
	s_nop 0
	global_load_lds_dwordx4 v[158:159], off
	v_lshl_add_u64 v[158:159], s[18:19], 0, v[132:133]
	s_add_i32 m0, s20, 0x2000
	s_nop 0
	global_load_lds_dwordx4 v[158:159], off
	v_lshl_add_u64 v[158:159], v[230:231], 0, s[10:11]
	s_mov_b32 m0, s40
	s_nop 0
	global_load_lds_dwordx4 v[158:159], off
	v_lshl_add_u64 v[158:159], v[232:233], 0, s[10:11]
	s_mov_b32 m0, s41
	s_nop 0
	global_load_lds_dwordx4 v[158:159], off
	s_waitcnt vmcnt(8)
	s_waitcnt lgkmcnt(0)
	s_barrier
	s_setprio 1
	s_waitcnt lgkmcnt(0)
	v_mfma_f32_16x16x32_bf16 v[60:63], v[128:131], v[198:201], v[60:63]
	v_mfma_f32_16x16x32_bf16 v[56:59], v[174:177], v[198:201], v[56:59]
	v_mfma_f32_16x16x32_bf16 v[44:47], v[128:131], v[206:209], v[44:47]
	v_mfma_f32_16x16x32_bf16 v[40:43], v[174:177], v[206:209], v[40:43]
	v_mfma_f32_16x16x32_bf16 v[28:31], v[128:131], v[214:217], v[28:31]
	v_mfma_f32_16x16x32_bf16 v[24:27], v[174:177], v[214:217], v[24:27]
	v_mfma_f32_16x16x32_bf16 v[12:15], v[128:131], v[222:225], v[12:15]
	v_mfma_f32_16x16x32_bf16 v[8:11], v[174:177], v[222:225], v[8:11]
	v_mfma_f32_16x16x32_bf16 v[60:63], v[170:173], v[202:205], v[60:63]
	v_mfma_f32_16x16x32_bf16 v[56:59], v[178:181], v[202:205], v[56:59]
	v_mfma_f32_16x16x32_bf16 v[44:47], v[170:173], v[210:213], v[44:47]
	v_mfma_f32_16x16x32_bf16 v[40:43], v[178:181], v[210:213], v[40:43]
	v_mfma_f32_16x16x32_bf16 v[28:31], v[170:173], v[218:221], v[28:31]
	v_mfma_f32_16x16x32_bf16 v[24:27], v[178:181], v[218:221], v[24:27]
	v_mfma_f32_16x16x32_bf16 v[12:15], v[170:173], v[226:229], v[12:15]
	v_mfma_f32_16x16x32_bf16 v[8:11], v[178:181], v[226:229], v[8:11]
	s_setprio 0
	s_setprio 1
	v_mfma_f32_16x16x32_bf16 v[52:55], v[182:185], v[198:201], v[52:55]
	v_mfma_f32_16x16x32_bf16 v[48:51], v[190:193], v[198:201], v[48:51]
	v_mfma_f32_16x16x32_bf16 v[36:39], v[182:185], v[206:209], v[36:39]
	v_mfma_f32_16x16x32_bf16 v[32:35], v[190:193], v[206:209], v[32:35]
	v_mfma_f32_16x16x32_bf16 v[20:23], v[182:185], v[214:217], v[20:23]
	v_mfma_f32_16x16x32_bf16 v[16:19], v[190:193], v[214:217], v[16:19]
	v_mfma_f32_16x16x32_bf16 v[4:7], v[182:185], v[222:225], v[4:7]
	v_mfma_f32_16x16x32_bf16 v[0:3], v[190:193], v[222:225], v[0:3]
	v_mfma_f32_16x16x32_bf16 v[52:55], v[186:189], v[202:205], v[52:55]
	v_mfma_f32_16x16x32_bf16 v[48:51], v[194:197], v[202:205], v[48:51]
	v_mfma_f32_16x16x32_bf16 v[36:39], v[186:189], v[210:213], v[36:39]
	v_mfma_f32_16x16x32_bf16 v[32:35], v[194:197], v[210:213], v[32:35]
	v_mfma_f32_16x16x32_bf16 v[20:23], v[186:189], v[218:221], v[20:23]
	v_mfma_f32_16x16x32_bf16 v[16:19], v[194:197], v[218:221], v[16:19]
	v_mfma_f32_16x16x32_bf16 v[4:7], v[186:189], v[226:229], v[4:7]
	v_mfma_f32_16x16x32_bf16 v[0:3], v[194:197], v[226:229], v[0:3]
	s_setprio 0
	s_barrier
	s_add_i32 s53, s53, 2
	s_add_u32 s16, s16, 0x100
	s_addc_u32 s17, s17, 0
	s_add_u32 s51, s51, 0x100
	s_addc_u32 s52, s52, 0
	s_cmp_gt_u32 s53, 29
	s_cbranch_scc0 .LBB0_100
	s_and_b64 vcc, exec, s[12:13]
	s_cbranch_vccz .LBB0_103
	s_barrier

; __device__ __forceinline__ unsigned xb_ld(unsigned* p)              { return __hip_atomic_load(p, __ATOMIC_RELAXED, __HIP_MEMORY_SCOPE_AGENT); }
; __device__ __forceinline__ unsigned xb_add(unsigned* p, unsigned v) { return __hip_atomic_fetch_add(p, v, __ATOMIC_RELAXED, __HIP_MEMORY_SCOPE_AGENT); }
; #define XB_SPIN(cond, bar) do { unsigned _sp = 0; while (cond) { __builtin_amdgcn_s_sleep(1); \
;     if ((++_sp & 255u) == 0u) { if (xb_ld(&(bar)[XB_TMO])) break; if (_sp > XB_SPIN_CAP) { atomicAdd(&(bar)[XB_TMO], 1u); break; } } } } while (0)
; __device__ __forceinline__ void xcd_barrier(const XcdBarrier& b) {
;     ...
;         const unsigned old = xb_add(&bar[XB_XSUB(b.x)], 1u);
;         const unsigned gen = old / nloc;
;         if (old + 1u == (gen + 1u) * nloc) {
;             __builtin_amdgcn_fence(__ATOMIC_RELEASE, "agent");
;             asm volatile("s_waitcnt vmcnt(0)" ::: "memory");
;             const unsigned og = xb_add(&bar[XB_TOP], 1u);
;             const unsigned tg = og / nx;
;             if (og + 1u == (tg + 1u) * nx) xb_add(&bar[XB_TOPGEN], 1u);
;             else XB_SPIN(xb_ld(&bar[XB_TOPGEN]) == tg, bar);
;             __builtin_amdgcn_fence(__ATOMIC_ACQUIRE, "agent");
;             xb_add(&bar[XB_XGEN(b.x)], 1u);
;             asm volatile("s_waitcnt vmcnt(0)" ::: "memory");
;         } else {
;             XB_SPIN(xb_ld(&bar[XB_XGEN(b.x)]) == gen, bar);
.LBB0_129:
	v_readlane_b32 s4, v236, 18
	s_lshl_b32 s4, s4, 8
	s_add_u32 s4, s28, s4
	s_addc_u32 s5, s29, 0
	v_mov_b32_e32 v1, 0x1000
	v_mov_b32_e32 v3, 1
	global_atomic_add v3, v1, v3, s[4:5] offset:1024 sc0
	v_cvt_f32_u32_e32 v1, v2
	v_sub_u32_e32 v4, 0, v2
	v_rcp_iflag_f32_e32 v1, v1
	s_nop 0
	v_mul_f32_e32 v1, 0x4f7ffffe, v1
	v_cvt_u32_f32_e32 v1, v1
	v_mul_lo_u32 v4, v4, v1
	v_mul_hi_u32 v4, v1, v4
	v_add_u32_e32 v1, v1, v4
	s_waitcnt vmcnt(0)
	v_mul_hi_u32 v1, v3, v1
	v_mul_lo_u32 v4, v1, v2
	v_sub_u32_e32 v4, v3, v4
	v_add_u32_e32 v5, 1, v1
	v_cmp_ge_u32_e32 vcc, v4, v2
	v_add_u32_e32 v3, 1, v3
	s_nop 0
	v_cndmask_b32_e32 v1, v1, v5, vcc
	v_sub_u32_e32 v5, v4, v2
	v_cndmask_b32_e32 v4, v4, v5, vcc
	v_add_u32_e32 v5, 1, v1
	v_cmp_ge_u32_e32 vcc, v4, v2
	s_nop 1
	v_cndmask_b32_e32 v1, v1, v5, vcc
	v_mul_lo_u32 v4, v2, v1
	v_add_u32_e32 v2, v4, v2
	v_cmp_ne_u32_e32 vcc, v3, v2
	s_and_saveexec_b64 s[6:7], vcc
	s_xor_b64 s[6:7], exec, s[6:7]
	s_cbranch_execz .LBB0_143
	s_waitcnt lgkmcnt(0)
	v_mov_b32_e32 v0, 0x3000
	global_load_dword v0, v0, s[28:29] offset:1280 sc1
	s_add_u32 s10, s28, 0x3500
	s_addc_u32 s11, s29, 0
	s_waitcnt vmcnt(0)
	v_cmp_eq_u32_e32 vcc, v0, v1
	s_and_saveexec_b64 s[8:9], vcc
	s_cbranch_execz .LBB0_142
	s_mov_b32 s22, 1
	s_mov_b64 s[12:13], 0
	v_mov_b32_e32 v0, 0
	s_branch .LBB0_133

; __device__ __forceinline__ unsigned xb_add(unsigned* p, unsigned v) { return __hip_atomic_fetch_add(p, v, __ATOMIC_RELAXED, __HIP_MEMORY_SCOPE_AGENT); }
; __device__ __forceinline__ void xcd_barrier(const XcdBarrier& b) {
;     ...
;             __builtin_amdgcn_fence(__ATOMIC_ACQUIRE, "agent");
;             xb_add(&bar[XB_XGEN(b.x)], 1u);
;             asm volatile("s_waitcnt vmcnt(0)" ::: "memory");
.LBB0_160:
	s_or_b64 exec, exec, s[6:7]
	v_mov_b32_e32 v0, 0x2000
	v_mov_b32_e32 v1, 1
	s_waitcnt vmcnt(0)
	buffer_inv sc1
	s_waitcnt vmcnt(0)

; #define PG8_STAGE(bufoff, gbase, voff) do { _Pragma("unroll") for (int _i = 0; _i < 2; ++_i) \
;         __builtin_amdgcn_global_load_lds((const unsigned*)((const char*)(gbase) + (voff)[_i]), (LAS unsigned*)(lds + (bufoff) + ldsw + _i * 8192), 16, 0, 0); } while (0)
; #define PG8_LDA(dst, b, h) do { _Pragma("unroll") for (int m = 0; m < 4; ++m) _Pragma("unroll") for (int k = 0; k < 2; ++k) dst[m][k] = *(const LAS bf16x8*)(lds + PG8_SA(b, h) + aoff + m * 2048 + k * 1024); } while (0)
; #define PG8_LDB(dst, b, h) do { _Pragma("unroll") for (int n = 0; n < 2; ++n) _Pragma("unroll") for (int k = 0; k < 2; ++k) dst[n][k] = *(const LAS bf16x8*)(lds + PG8_SB(b, h) + boff + n * 2048 + k * 1024); } while (0)
; #define PG8_WAIT_V(n) asm volatile("s_waitcnt vmcnt(" #n ")" ::: "memory")
; #define PG8_WAIT_L(n) asm volatile("s_waitcnt lgkmcnt(" #n ")" ::: "memory")
; #define PG8_BAR __builtin_amdgcn_s_barrier()
; #define PG8_SCHED __builtin_amdgcn_sched_barrier(0)
; template <class EpiT>
; __device__ __forceinline__ void gemm_phase(LAS unsigned char* lds, const Gemm g, const StaticOrder& S, const EpiT& E) {
;     ...
;         const bool has_next = S.next(ui + 1, nxt);
;         const char* nA = has_next ? (const char*)g.A + (size_t)nxt.pm * tstepA + (size_t)nxt.pn * g.a_koff * 2 : cA; const char* nB = has_next ? (const char*)g.Bt + (size_t)nxt.pn * tstepB : cB;
;         for (int t = 0; t < nt; t += 2) {
;             const bool last = (t == nt - 2);
;             const char* a1 = cA + (size_t)(t + 1) * kstep;
;             const char* a2 = last ? nA : cA + (size_t)(t + 2) * kstep; const char* b2 = last ? nB : cB + (size_t)(t + 2) * kstep;
;             const char* a3 = a2 + kstep; const char* b3 = b2 + kstep;
;             PG8_LDB(B0, 0, 0); PG8_LDB(B1, 0, 1); PG8_SCHED; PG8_LDA(At, 0, 0); PG8_STAGE(PG8_SA(1, 1), a1 + hstepA, voffA);
;             PG8_WAIT_V(8); PG8_WAIT_L(0); PG8_BAR; PG8_MMA(0, 0, At, B0); PG8_MMA(0, 1, At, B1); PG8_BAR; PG8_SCHED;
;     ...
; #pragma unroll
;         for (int a = 0; a < 2; ++a)
; #pragma unroll
;             for (int b = 0; b < 2; ++b)
; #pragma unroll
;                 for (int m = 0; m < 4; ++m)
; #pragma unroll
;                     for (int n = 0; n < 2; ++n) acc[a][b][m][n] = (f32x4){0.f, 0.f, 0.f, 0.f};
;         cur = nxt; cA = nA; cB = nB; ++ui;
.LBB0_295:
	s_lshl_b64 s[4:5], s[16:17], 17
	s_add_u32 s22, s33, s4
	s_addc_u32 s23, s35, s5
	s_and_b64 s[4:5], s[2:3], exec
	v_mov_b32_e32 v0, 0
	s_cselect_b32 s17, s23, s47
	s_cselect_b32 s19, s22, s46
	s_mov_b32 s54, 0
	s_mov_b64 s[4:5], -1
	s_mov_b64 s[68:69], 0
	v_mov_b32_e32 v1, v0
	v_mov_b32_e32 v2, v0
	v_mov_b32_e32 v3, v0
	v_mov_b32_e32 v4, v0
	v_mov_b32_e32 v5, v0
	v_mov_b32_e32 v6, v0
	v_mov_b32_e32 v7, v0
	v_mov_b32_e32 v16, v0
	v_mov_b32_e32 v17, v0
	v_mov_b32_e32 v18, v0
	v_mov_b32_e32 v19, v0
	v_mov_b32_e32 v20, v0
	v_mov_b32_e32 v21, v0
	v_mov_b32_e32 v22, v0
	v_mov_b32_e32 v23, v0
	v_mov_b32_e32 v32, v0
	v_mov_b32_e32 v33, v0
	v_mov_b32_e32 v34, v0
	v_mov_b32_e32 v35, v0
	v_mov_b32_e32 v36, v0
	v_mov_b32_e32 v37, v0
	v_mov_b32_e32 v38, v0
	v_mov_b32_e32 v39, v0
	v_mov_b32_e32 v48, v0
	v_mov_b32_e32 v49, v0
	v_mov_b32_e32 v50, v0
	v_mov_b32_e32 v51, v0
	v_mov_b32_e32 v52, v0
	v_mov_b32_e32 v53, v0
	v_mov_b32_e32 v54, v0
	v_mov_b32_e32 v55, v0
	v_mov_b32_e32 v8, v0
	v_mov_b32_e32 v9, v0
	v_mov_b32_e32 v10, v0
	v_mov_b32_e32 v11, v0
	v_mov_b32_e32 v12, v0
	v_mov_b32_e32 v13, v0
	v_mov_b32_e32 v14, v0
	v_mov_b32_e32 v15, v0
	v_mov_b32_e32 v24, v0
	v_mov_b32_e32 v25, v0
	v_mov_b32_e32 v26, v0
	v_mov_b32_e32 v27, v0
	v_mov_b32_e32 v28, v0
	v_mov_b32_e32 v29, v0
	v_mov_b32_e32 v30, v0
	v_mov_b32_e32 v31, v0
	v_mov_b32_e32 v40, v0
	v_mov_b32_e32 v41, v0
	v_mov_b32_e32 v42, v0
	v_mov_b32_e32 v43, v0
	v_mov_b32_e32 v44, v0
	v_mov_b32_e32 v45, v0
	v_mov_b32_e32 v46, v0
	v_mov_b32_e32 v47, v0
	v_mov_b32_e32 v56, v0
	v_mov_b32_e32 v57, v0
	v_mov_b32_e32 v58, v0
	v_mov_b32_e32 v59, v0
	v_mov_b32_e32 v60, v0
	v_mov_b32_e32 v61, v0
	v_mov_b32_e32 v62, v0
	v_mov_b32_e32 v63, v0
	v_mov_b32_e32 v64, v0
	v_mov_b32_e32 v65, v0
	v_mov_b32_e32 v66, v0
	v_mov_b32_e32 v67, v0
	v_mov_b32_e32 v68, v0
	v_mov_b32_e32 v69, v0
	v_mov_b32_e32 v70, v0
	v_mov_b32_e32 v71, v0
	v_mov_b32_e32 v80, v0
	v_mov_b32_e32 v81, v0
	v_mov_b32_e32 v82, v0
	v_mov_b32_e32 v83, v0
	v_mov_b32_e32 v84, v0
	v_mov_b32_e32 v85, v0
	v_mov_b32_e32 v86, v0
	v_mov_b32_e32 v87, v0
	v_mov_b32_e32 v96, v0
	v_mov_b32_e32 v97, v0
	v_mov_b32_e32 v98, v0
	v_mov_b32_e32 v99, v0
	v_mov_b32_e32 v100, v0
	v_mov_b32_e32 v101, v0
	v_mov_b32_e32 v102, v0
	v_mov_b32_e32 v103, v0
	v_mov_b32_e32 v112, v0
	v_mov_b32_e32 v113, v0
	v_mov_b32_e32 v114, v0
	v_mov_b32_e32 v115, v0
	v_mov_b32_e32 v116, v0
	v_mov_b32_e32 v117, v0
	v_mov_b32_e32 v118, v0
	v_mov_b32_e32 v119, v0
	v_mov_b32_e32 v72, v0
	v_mov_b32_e32 v73, v0
	v_mov_b32_e32 v74, v0
	v_mov_b32_e32 v75, v0
	v_mov_b32_e32 v76, v0
	v_mov_b32_e32 v77, v0
	v_mov_b32_e32 v78, v0
	v_mov_b32_e32 v79, v0
	v_mov_b32_e32 v88, v0
	v_mov_b32_e32 v89, v0
	v_mov_b32_e32 v90, v0
	v_mov_b32_e32 v91, v0
	v_mov_b32_e32 v92, v0
	v_mov_b32_e32 v93, v0
	v_mov_b32_e32 v94, v0
	v_mov_b32_e32 v95, v0
	v_mov_b32_e32 v104, v0
	v_mov_b32_e32 v105, v0
	v_mov_b32_e32 v106, v0
	v_mov_b32_e32 v107, v0
	v_mov_b32_e32 v108, v0
	v_mov_b32_e32 v109, v0
	v_mov_b32_e32 v110, v0
	v_mov_b32_e32 v111, v0
	v_mov_b32_e32 v120, v0
	v_mov_b32_e32 v121, v0
	v_mov_b32_e32 v122, v0
	v_mov_b32_e32 v123, v0
	v_mov_b32_e32 v124, v0
	v_mov_b32_e32 v125, v0
	v_mov_b32_e32 v126, v0
	v_mov_b32_e32 v127, v0
	.p2alignl 6, 3212836864
	s_nop 0
	s_nop 0
	s_nop 0
	s_nop 0
	s_nop 0
	s_nop 0
	s_nop 0
	s_nop 0
.LBB0_296:
	s_add_u32 s58, s66, s54
	s_addc_u32 s59, s67, 0
	s_add_u32 s55, s58, 0x100
	s_addc_u32 s61, s59, 0
	s_and_b64 s[56:57], s[68:69], exec
	s_cselect_b32 s73, s21, s61
	s_cselect_b32 s72, s20, s55
	s_add_u32 s54, s46, s54
	s_addc_u32 s55, s47, 0
	s_add_u32 s56, s54, 0x100
	s_addc_u32 s57, s55, 0
	s_and_b64 s[54:55], s[68:69], exec
	s_cselect_b32 s75, s17, s57
	s_cselect_b32 s74, s19, s56
	s_add_u32 s78, s58, 0x40080
	s_addc_u32 s79, s59, 0
	s_add_i32 s80, s51, s36
	ds_read_b128 v[128:131], v167
	ds_read_b128 v[132:135], v167 offset:1024
	ds_read_b128 v[136:139], v167 offset:2048
	ds_read_b128 v[140:143], v167 offset:3072
	ds_read_b128 v[160:163], v169
	ds_read_b128 v[172:175], v169 offset:1024
	ds_read_b128 v[176:179], v169 offset:2048
	ds_read_b128 v[180:183], v169 offset:3072
	s_add_i32 m0, s37, 0xc000
	s_add_i32 s84, s37, 0xe000
	s_add_i32 s61, s80, 0x2000
	s_add_u32 s76, s74, 0x10000
	s_addc_u32 s77, s75, 0
	s_add_i32 s65, s52, s36
	s_add_i32 s64, s65, 0x2000
	s_add_i32 s59, 0, 0x18000
	s_add_i32 s58, 0, 0x1c000
	s_add_u32 s70, s72, 0x40000
	s_addc_u32 s71, s73, 0
	s_add_i32 s57, s59, s36
	s_add_i32 s55, s57, 0x2000
	s_add_u32 s68, s74, 0x10080
	s_addc_u32 s69, s75, 0
	s_add_i32 s56, s58, s36
	s_add_i32 s54, s56, 0x2000
	v_lshl_add_u64 v[216:217], s[78:79], 0, v[146:147]
	ds_read_b128 v[184:187], v170
	ds_read_b128 v[188:191], v170 offset:1024
	ds_read_b128 v[192:195], v170 offset:2048
	ds_read_b128 v[196:199], v170 offset:3072
	ds_read_b128 v[200:203], v170 offset:4096
	ds_read_b128 v[204:207], v170 offset:5120
	ds_read_b128 v[208:211], v170 offset:6144
	ds_read_b128 v[212:215], v170 offset:7168
	global_load_lds_dwordx4 v[216:217], off
	v_lshl_add_u64 v[216:217], s[78:79], 0, v[150:151]
	s_mov_b32 m0, s84
	s_nop 0
	global_load_lds_dwordx4 v[216:217], off
	s_waitcnt vmcnt(8)
	s_waitcnt lgkmcnt(0)
	s_barrier
; #define PG8_STAGE(bufoff, gbase, voff) do { _Pragma("unroll") for (int _i = 0; _i < 2; ++_i) \
;         __builtin_amdgcn_global_load_lds((const unsigned*)((const char*)(gbase) + (voff)[_i]), (LAS unsigned*)(lds + (bufoff) + ldsw + _i * 8192), 16, 0, 0); } while (0)
; #define PG8_LDA(dst, b, h) do { _Pragma("unroll") for (int m = 0; m < 4; ++m) _Pragma("unroll") for (int k = 0; k < 2; ++k) dst[m][k] = *(const LAS bf16x8*)(lds + PG8_SA(b, h) + aoff + m * 2048 + k * 1024); } while (0)
; #define PG8_MMA(ai, bj, At, Bt) do { __builtin_amdgcn_s_setprio(1); _Pragma("unroll") for (int m = 0; m < 4; ++m) _Pragma("unroll") for (int n = 0; n < 2; ++n) _Pragma("unroll") for (int k = 0; k < 2; ++k) \
;         acc[ai][bj][m][n] = __builtin_amdgcn_mfma_f32_16x16x32_bf16(Bt[n][k], At[m][k], acc[ai][bj][m][n], 0, 0, 0); __builtin_amdgcn_s_setprio(0); } while (0)
; #define PG8_WAIT_V(n) asm volatile("s_waitcnt vmcnt(" #n ")" ::: "memory")
; #define PG8_WAIT_L(n) asm volatile("s_waitcnt lgkmcnt(" #n ")" ::: "memory")
; #define PG8_BAR __builtin_amdgcn_s_barrier()
; #define PG8_SCHED __builtin_amdgcn_sched_barrier(0)
; template <class EpiT>
; __device__ __forceinline__ void gemm_phase(LAS unsigned char* lds, const Gemm g, const StaticOrder& S, const EpiT& E) {
;     ...
;             PG8_WAIT_V(8); PG8_WAIT_L(0); PG8_BAR; PG8_MMA(0, 0, At, B0); PG8_MMA(0, 1, At, B1); PG8_BAR; PG8_SCHED;
;             PG8_LDA(At, 0, 1); PG8_STAGE(PG8_SB(0, 0), b2, voffB); PG8_STAGE(PG8_SB(0, 1), b2 + hstepB, voffB); PG8_STAGE(PG8_SA(0, 0), a2, voffA);
;             PG8_WAIT_V(8); PG8_WAIT_L(0); PG8_BAR; PG8_MMA(1, 0, At, B0); PG8_MMA(1, 1, At, B1); PG8_BAR; PG8_SCHED;
	s_setprio 1
	s_waitcnt lgkmcnt(0)
	v_mfma_f32_16x16x32_bf16 v[124:127], v[128:131], v[184:187], v[124:127]
	v_mfma_f32_16x16x32_bf16 v[120:123], v[136:139], v[184:187], v[120:123]
	v_mfma_f32_16x16x32_bf16 v[108:111], v[128:131], v[192:195], v[108:111]
	v_mfma_f32_16x16x32_bf16 v[104:107], v[136:139], v[192:195], v[104:107]
	v_mfma_f32_16x16x32_bf16 v[92:95], v[128:131], v[200:203], v[92:95]
	v_mfma_f32_16x16x32_bf16 v[88:91], v[136:139], v[200:203], v[88:91]
	v_mfma_f32_16x16x32_bf16 v[76:79], v[128:131], v[208:211], v[76:79]
	v_mfma_f32_16x16x32_bf16 v[72:75], v[136:139], v[208:211], v[72:75]
	v_mfma_f32_16x16x32_bf16 v[124:127], v[132:135], v[188:191], v[124:127]
	v_mfma_f32_16x16x32_bf16 v[120:123], v[140:143], v[188:191], v[120:123]
	v_mfma_f32_16x16x32_bf16 v[108:111], v[132:135], v[196:199], v[108:111]
	v_mfma_f32_16x16x32_bf16 v[104:107], v[140:143], v[196:199], v[104:107]
	v_mfma_f32_16x16x32_bf16 v[92:95], v[132:135], v[204:207], v[92:95]
	v_mfma_f32_16x16x32_bf16 v[88:91], v[140:143], v[204:207], v[88:91]
	v_mfma_f32_16x16x32_bf16 v[76:79], v[132:135], v[212:215], v[76:79]
	v_mfma_f32_16x16x32_bf16 v[72:75], v[140:143], v[212:215], v[72:75]
	s_setprio 0
	s_setprio 1
	v_mfma_f32_16x16x32_bf16 v[116:119], v[160:163], v[184:187], v[116:119]
	v_mfma_f32_16x16x32_bf16 v[112:115], v[176:179], v[184:187], v[112:115]
	v_mfma_f32_16x16x32_bf16 v[100:103], v[160:163], v[192:195], v[100:103]
	v_mfma_f32_16x16x32_bf16 v[96:99], v[176:179], v[192:195], v[96:99]
	v_mfma_f32_16x16x32_bf16 v[84:87], v[160:163], v[200:203], v[84:87]
	v_mfma_f32_16x16x32_bf16 v[80:83], v[176:179], v[200:203], v[80:83]
	v_mfma_f32_16x16x32_bf16 v[68:71], v[160:163], v[208:211], v[68:71]
	v_mfma_f32_16x16x32_bf16 v[64:67], v[176:179], v[208:211], v[64:67]
	v_mfma_f32_16x16x32_bf16 v[116:119], v[172:175], v[188:191], v[116:119]
	v_mfma_f32_16x16x32_bf16 v[112:115], v[180:183], v[188:191], v[112:115]
	v_mfma_f32_16x16x32_bf16 v[100:103], v[172:175], v[196:199], v[100:103]
	v_mfma_f32_16x16x32_bf16 v[96:99], v[180:183], v[196:199], v[96:99]
	v_mfma_f32_16x16x32_bf16 v[84:87], v[172:175], v[204:207], v[84:87]
	v_mfma_f32_16x16x32_bf16 v[80:83], v[180:183], v[204:207], v[80:83]
	v_mfma_f32_16x16x32_bf16 v[68:71], v[172:175], v[212:215], v[68:71]
	v_mfma_f32_16x16x32_bf16 v[64:67], v[180:183], v[212:215], v[64:67]
	s_setprio 0
	s_barrier
	s_mov_b32 m0, s80
	v_lshl_add_u64 v[216:217], s[74:75], 0, v[148:149]
	ds_read_b128 v[184:187], v170 offset:16384
	ds_read_b128 v[188:191], v170 offset:17408
	ds_read_b128 v[192:195], v170 offset:18432
	ds_read_b128 v[196:199], v170 offset:19456
	ds_read_b128 v[200:203], v170 offset:20480
	ds_read_b128 v[204:207], v170 offset:21504
	ds_read_b128 v[208:211], v170 offset:22528
	ds_read_b128 v[212:215], v170 offset:23552
	global_load_lds_dwordx4 v[216:217], off
	v_lshl_add_u64 v[218:219], s[74:75], 0, v[152:153]
	s_mov_b32 m0, s61
	v_lshl_add_u64 v[220:221], s[76:77], 0, v[148:149]
	global_load_lds_dwordx4 v[218:219], off
	s_mov_b32 m0, s65
	v_lshl_add_u64 v[222:223], s[72:73], 0, v[150:151]
	global_load_lds_dwordx4 v[220:221], off
	v_lshl_add_u64 v[220:221], s[76:77], 0, v[152:153]
	s_mov_b32 m0, s64
	s_nop 0
	global_load_lds_dwordx4 v[220:221], off
	v_lshl_add_u64 v[220:221], s[72:73], 0, v[146:147]
	s_mov_b32 m0, s37
	s_nop 0
	global_load_lds_dwordx4 v[220:221], off
	s_mov_b32 m0, s38
	s_nop 0
	global_load_lds_dwordx4 v[222:223], off
	s_waitcnt vmcnt(8)
	s_waitcnt lgkmcnt(0)
	s_barrier
	s_setprio 1
	s_waitcnt lgkmcnt(0)
	v_mfma_f32_16x16x32_bf16 v[60:63], v[128:131], v[184:187], v[60:63]
	v_mfma_f32_16x16x32_bf16 v[56:59], v[136:139], v[184:187], v[56:59]
	v_mfma_f32_16x16x32_bf16 v[44:47], v[128:131], v[192:195], v[44:47]
	v_mfma_f32_16x16x32_bf16 v[40:43], v[136:139], v[192:195], v[40:43]
	v_mfma_f32_16x16x32_bf16 v[28:31], v[128:131], v[200:203], v[28:31]
	v_mfma_f32_16x16x32_bf16 v[24:27], v[136:139], v[200:203], v[24:27]
	v_mfma_f32_16x16x32_bf16 v[12:15], v[128:131], v[208:211], v[12:15]
	v_mfma_f32_16x16x32_bf16 v[8:11], v[136:139], v[208:211], v[8:11]
	v_mfma_f32_16x16x32_bf16 v[60:63], v[132:135], v[188:191], v[60:63]
	v_mfma_f32_16x16x32_bf16 v[56:59], v[140:143], v[188:191], v[56:59]
	v_mfma_f32_16x16x32_bf16 v[44:47], v[132:135], v[196:199], v[44:47]
	v_mfma_f32_16x16x32_bf16 v[40:43], v[140:143], v[196:199], v[40:43]
	v_mfma_f32_16x16x32_bf16 v[28:31], v[132:135], v[204:207], v[28:31]
	v_mfma_f32_16x16x32_bf16 v[24:27], v[140:143], v[204:207], v[24:27]
	v_mfma_f32_16x16x32_bf16 v[12:15], v[132:135], v[212:215], v[12:15]
	v_mfma_f32_16x16x32_bf16 v[8:11], v[140:143], v[212:215], v[8:11]
	s_setprio 0
	s_setprio 1
	v_mfma_f32_16x16x32_bf16 v[52:55], v[160:163], v[184:187], v[52:55]
	v_mfma_f32_16x16x32_bf16 v[48:51], v[176:179], v[184:187], v[48:51]
	v_mfma_f32_16x16x32_bf16 v[36:39], v[160:163], v[192:195], v[36:39]
	v_mfma_f32_16x16x32_bf16 v[32:35], v[176:179], v[192:195], v[32:35]
	v_mfma_f32_16x16x32_bf16 v[20:23], v[160:163], v[200:203], v[20:23]
	v_mfma_f32_16x16x32_bf16 v[16:19], v[176:179], v[200:203], v[16:19]
	v_mfma_f32_16x16x32_bf16 v[4:7], v[160:163], v[208:211], v[4:7]
	v_mfma_f32_16x16x32_bf16 v[0:3], v[176:179], v[208:211], v[0:3]
	v_mfma_f32_16x16x32_bf16 v[52:55], v[172:175], v[188:191], v[52:55]
	v_mfma_f32_16x16x32_bf16 v[48:51], v[180:183], v[188:191], v[48:51]
	v_mfma_f32_16x16x32_bf16 v[36:39], v[172:175], v[196:199], v[36:39]
	v_mfma_f32_16x16x32_bf16 v[32:35], v[180:183], v[196:199], v[32:35]
	v_mfma_f32_16x16x32_bf16 v[20:23], v[172:175], v[204:207], v[20:23]
	v_mfma_f32_16x16x32_bf16 v[16:19], v[180:183], v[204:207], v[16:19]
	v_mfma_f32_16x16x32_bf16 v[4:7], v[172:175], v[212:215], v[4:7]
	v_mfma_f32_16x16x32_bf16 v[0:3], v[180:183], v[212:215], v[0:3]
	s_setprio 0
	s_barrier
; #define PG8_STAGE(bufoff, gbase, voff) do { _Pragma("unroll") for (int _i = 0; _i < 2; ++_i) \
;         __builtin_amdgcn_global_load_lds((const unsigned*)((const char*)(gbase) + (voff)[_i]), (LAS unsigned*)(lds + (bufoff) + ldsw + _i * 8192), 16, 0, 0); } while (0)
; #define PG8_LDA(dst, b, h) do { _Pragma("unroll") for (int m = 0; m < 4; ++m) _Pragma("unroll") for (int k = 0; k < 2; ++k) dst[m][k] = *(const LAS bf16x8*)(lds + PG8_SA(b, h) + aoff + m * 2048 + k * 1024); } while (0)
; #define PG8_LDB(dst, b, h) do { _Pragma("unroll") for (int n = 0; n < 2; ++n) _Pragma("unroll") for (int k = 0; k < 2; ++k) dst[n][k] = *(const LAS bf16x8*)(lds + PG8_SB(b, h) + boff + n * 2048 + k * 1024); } while (0)
; #define PG8_MMA(ai, bj, At, Bt) do { __builtin_amdgcn_s_setprio(1); _Pragma("unroll") for (int m = 0; m < 4; ++m) _Pragma("unroll") for (int n = 0; n < 2; ++n) _Pragma("unroll") for (int k = 0; k < 2; ++k) \
;         acc[ai][bj][m][n] = __builtin_amdgcn_mfma_f32_16x16x32_bf16(Bt[n][k], At[m][k], acc[ai][bj][m][n], 0, 0, 0); __builtin_amdgcn_s_setprio(0); } while (0)
; #define PG8_WAIT_V(n) asm volatile("s_waitcnt vmcnt(" #n ")" ::: "memory")
; #define PG8_WAIT_L(n) asm volatile("s_waitcnt lgkmcnt(" #n ")" ::: "memory")
; #define PG8_BAR __builtin_amdgcn_s_barrier()
; #define PG8_SCHED __builtin_amdgcn_sched_barrier(0)
; template <class EpiT>
; __device__ __forceinline__ void gemm_phase(LAS unsigned char* lds, const Gemm g, const StaticOrder& S, const EpiT& E) {
;     ...
;             PG8_LDB(B0, 1, 0); PG8_LDB(B1, 1, 1); PG8_SCHED; PG8_LDA(At, 1, 0); PG8_STAGE(PG8_SA(0, 1), a2 + hstepA, voffA);
;             PG8_WAIT_V(8); PG8_WAIT_L(0); PG8_BAR; PG8_MMA(0, 0, At, B0); PG8_MMA(0, 1, At, B1); PG8_BAR; PG8_SCHED;
;             PG8_LDA(At, 1, 1); PG8_STAGE(PG8_SB(1, 0), b3, voffB); PG8_STAGE(PG8_SB(1, 1), b3 + hstepB, voffB); PG8_STAGE(PG8_SA(1, 0), a3, voffA);
;             PG8_WAIT_V(8); PG8_WAIT_L(0); PG8_BAR; PG8_MMA(1, 0, At, B0); PG8_MMA(1, 1, At, B1); PG8_BAR; PG8_SCHED;
;         }
;         if (wr == 0) PG8_BAR;
	v_add_u32_e32 v140, s59, v145
	v_add_u32_e32 v180, s58, v145
	ds_read_b128 v[128:131], v140
	ds_read_b128 v[132:135], v140 offset:1024
	ds_read_b128 v[136:139], v140 offset:2048
	ds_read_b128 v[140:143], v140 offset:3072
	ds_read_b128 v[160:163], v180
	ds_read_b128 v[172:175], v180 offset:1024
	ds_read_b128 v[176:179], v180 offset:2048
	ds_read_b128 v[180:183], v180 offset:3072
	s_mov_b32 m0, s39
	v_lshl_add_u64 v[224:225], s[70:71], 0, v[146:147]
	ds_read_b128 v[184:187], v170 offset:32768
	ds_read_b128 v[188:191], v170 offset:33792
	ds_read_b128 v[192:195], v170 offset:34816
	ds_read_b128 v[196:199], v170 offset:35840
	ds_read_b128 v[200:203], v170 offset:36864
	ds_read_b128 v[204:207], v170 offset:37888
	ds_read_b128 v[208:211], v170 offset:38912
	ds_read_b128 v[212:215], v170 offset:39936
	global_load_lds_dwordx4 v[224:225], off
	v_lshl_add_u64 v[224:225], s[70:71], 0, v[150:151]
	s_mov_b32 m0, s41
	s_nop 0
	global_load_lds_dwordx4 v[224:225], off
	s_waitcnt vmcnt(8)
	s_waitcnt lgkmcnt(0)
	s_barrier
	s_setprio 1
	s_waitcnt lgkmcnt(0)
	v_mfma_f32_16x16x32_bf16 v[124:127], v[128:131], v[184:187], v[124:127]
	v_mfma_f32_16x16x32_bf16 v[120:123], v[136:139], v[184:187], v[120:123]
	v_mfma_f32_16x16x32_bf16 v[108:111], v[128:131], v[192:195], v[108:111]
	v_mfma_f32_16x16x32_bf16 v[104:107], v[136:139], v[192:195], v[104:107]
	v_mfma_f32_16x16x32_bf16 v[92:95], v[128:131], v[200:203], v[92:95]
	v_mfma_f32_16x16x32_bf16 v[88:91], v[136:139], v[200:203], v[88:91]
	v_mfma_f32_16x16x32_bf16 v[76:79], v[128:131], v[208:211], v[76:79]
	v_mfma_f32_16x16x32_bf16 v[72:75], v[136:139], v[208:211], v[72:75]
	v_mfma_f32_16x16x32_bf16 v[124:127], v[132:135], v[188:191], v[124:127]
	v_mfma_f32_16x16x32_bf16 v[120:123], v[140:143], v[188:191], v[120:123]
	v_mfma_f32_16x16x32_bf16 v[108:111], v[132:135], v[196:199], v[108:111]
	v_mfma_f32_16x16x32_bf16 v[104:107], v[140:143], v[196:199], v[104:107]
	v_mfma_f32_16x16x32_bf16 v[92:95], v[132:135], v[204:207], v[92:95]
	v_mfma_f32_16x16x32_bf16 v[88:91], v[140:143], v[204:207], v[88:91]
	v_mfma_f32_16x16x32_bf16 v[76:79], v[132:135], v[212:215], v[76:79]
	v_mfma_f32_16x16x32_bf16 v[72:75], v[140:143], v[212:215], v[72:75]
	s_setprio 0
	s_setprio 1
	v_mfma_f32_16x16x32_bf16 v[116:119], v[160:163], v[184:187], v[116:119]
	v_mfma_f32_16x16x32_bf16 v[112:115], v[176:179], v[184:187], v[112:115]
	v_mfma_f32_16x16x32_bf16 v[100:103], v[160:163], v[192:195], v[100:103]
	v_mfma_f32_16x16x32_bf16 v[96:99], v[176:179], v[192:195], v[96:99]
	v_mfma_f32_16x16x32_bf16 v[84:87], v[160:163], v[200:203], v[84:87]
	v_mfma_f32_16x16x32_bf16 v[80:83], v[176:179], v[200:203], v[80:83]
	v_mfma_f32_16x16x32_bf16 v[68:71], v[160:163], v[208:211], v[68:71]
	v_mfma_f32_16x16x32_bf16 v[64:67], v[176:179], v[208:211], v[64:67]
	v_mfma_f32_16x16x32_bf16 v[116:119], v[172:175], v[188:191], v[116:119]
	v_mfma_f32_16x16x32_bf16 v[112:115], v[180:183], v[188:191], v[112:115]
	v_mfma_f32_16x16x32_bf16 v[100:103], v[172:175], v[196:199], v[100:103]
	v_mfma_f32_16x16x32_bf16 v[96:99], v[180:183], v[196:199], v[96:99]
	v_mfma_f32_16x16x32_bf16 v[84:87], v[172:175], v[204:207], v[84:87]
	v_mfma_f32_16x16x32_bf16 v[80:83], v[180:183], v[204:207], v[80:83]
	v_mfma_f32_16x16x32_bf16 v[68:71], v[172:175], v[212:215], v[68:71]
	v_mfma_f32_16x16x32_bf16 v[64:67], v[180:183], v[212:215], v[64:67]
	s_setprio 0
	s_barrier
	s_mov_b32 m0, s57
	v_lshl_add_u64 v[216:217], v[216:217], 0, s[10:11]
	ds_read_b128 v[184:187], v170 offset:49152
	ds_read_b128 v[188:191], v170 offset:50176
	ds_read_b128 v[192:195], v170 offset:51200
	ds_read_b128 v[196:199], v170 offset:52224
	ds_read_b128 v[200:203], v170 offset:53248
	ds_read_b128 v[204:207], v170 offset:54272
	ds_read_b128 v[208:211], v170 offset:55296
	ds_read_b128 v[212:215], v170 offset:56320
	global_load_lds_dwordx4 v[216:217], off
	v_lshl_add_u64 v[216:217], v[218:219], 0, s[10:11]
	s_mov_b32 m0, s55
	s_nop 0
	global_load_lds_dwordx4 v[216:217], off
	v_lshl_add_u64 v[216:217], s[68:69], 0, v[148:149]
	s_mov_b32 m0, s56
	s_nop 0
	global_load_lds_dwordx4 v[216:217], off
	v_lshl_add_u64 v[216:217], s[68:69], 0, v[152:153]
	s_mov_b32 m0, s54
	s_nop 0
	global_load_lds_dwordx4 v[216:217], off
	v_lshl_add_u64 v[216:217], v[220:221], 0, s[10:11]
	s_mov_b32 m0, s44
	s_nop 0
	global_load_lds_dwordx4 v[216:217], off
	v_lshl_add_u64 v[216:217], v[222:223], 0, s[10:11]
	s_mov_b32 m0, s45
	s_nop 0
	global_load_lds_dwordx4 v[216:217], off
	s_waitcnt vmcnt(8)
	s_waitcnt lgkmcnt(0)
	s_barrier
	s_setprio 1
	s_waitcnt lgkmcnt(0)
	v_mfma_f32_16x16x32_bf16 v[60:63], v[128:131], v[184:187], v[60:63]
	v_mfma_f32_16x16x32_bf16 v[56:59], v[136:139], v[184:187], v[56:59]
	v_mfma_f32_16x16x32_bf16 v[44:47], v[128:131], v[192:195], v[44:47]
	v_mfma_f32_16x16x32_bf16 v[40:43], v[136:139], v[192:195], v[40:43]
	v_mfma_f32_16x16x32_bf16 v[28:31], v[128:131], v[200:203], v[28:31]
	v_mfma_f32_16x16x32_bf16 v[24:27], v[136:139], v[200:203], v[24:27]
	v_mfma_f32_16x16x32_bf16 v[12:15], v[128:131], v[208:211], v[12:15]
	v_mfma_f32_16x16x32_bf16 v[8:11], v[136:139], v[208:211], v[8:11]
	v_mfma_f32_16x16x32_bf16 v[60:63], v[132:135], v[188:191], v[60:63]
	v_mfma_f32_16x16x32_bf16 v[56:59], v[140:143], v[188:191], v[56:59]
	v_mfma_f32_16x16x32_bf16 v[44:47], v[132:135], v[196:199], v[44:47]
	v_mfma_f32_16x16x32_bf16 v[40:43], v[140:143], v[196:199], v[40:43]
	v_mfma_f32_16x16x32_bf16 v[28:31], v[132:135], v[204:207], v[28:31]
	v_mfma_f32_16x16x32_bf16 v[24:27], v[140:143], v[204:207], v[24:27]
	v_mfma_f32_16x16x32_bf16 v[12:15], v[132:135], v[212:215], v[12:15]
	v_mfma_f32_16x16x32_bf16 v[8:11], v[140:143], v[212:215], v[8:11]
	s_setprio 0
	s_setprio 1
	v_mfma_f32_16x16x32_bf16 v[52:55], v[160:163], v[184:187], v[52:55]
	v_mfma_f32_16x16x32_bf16 v[48:51], v[176:179], v[184:187], v[48:51]
	v_mfma_f32_16x16x32_bf16 v[36:39], v[160:163], v[192:195], v[36:39]
	v_mfma_f32_16x16x32_bf16 v[32:35], v[176:179], v[192:195], v[32:35]
	v_mfma_f32_16x16x32_bf16 v[20:23], v[160:163], v[200:203], v[20:23]
	v_mfma_f32_16x16x32_bf16 v[16:19], v[176:179], v[200:203], v[16:19]
	v_mfma_f32_16x16x32_bf16 v[4:7], v[160:163], v[208:211], v[4:7]
	v_mfma_f32_16x16x32_bf16 v[0:3], v[176:179], v[208:211], v[0:3]
	v_mfma_f32_16x16x32_bf16 v[52:55], v[172:175], v[188:191], v[52:55]
	v_mfma_f32_16x16x32_bf16 v[48:51], v[180:183], v[188:191], v[48:51]
	v_mfma_f32_16x16x32_bf16 v[36:39], v[172:175], v[196:199], v[36:39]
	v_mfma_f32_16x16x32_bf16 v[32:35], v[180:183], v[196:199], v[32:35]
	v_mfma_f32_16x16x32_bf16 v[20:23], v[172:175], v[204:207], v[20:23]
	v_mfma_f32_16x16x32_bf16 v[16:19], v[180:183], v[204:207], v[16:19]
	v_mfma_f32_16x16x32_bf16 v[4:7], v[172:175], v[212:215], v[4:7]
	v_mfma_f32_16x16x32_bf16 v[0:3], v[180:183], v[212:215], v[0:3]
	s_setprio 0
	s_barrier
	s_movk_i32 s54, 0x100
	s_andn2_b64 vcc, exec, s[4:5]
	s_mov_b64 s[68:69], -1
	s_mov_b64 s[4:5], 0
	s_cbranch_vccz .LBB0_296
	s_and_b64 vcc, exec, s[12:13]
	s_cbranch_vccz .LBB0_299
	s_barrier

; #define PG8_BAR __builtin_amdgcn_s_barrier()
; template <class EpiT>
; __device__ __forceinline__ void gemm_phase(LAS unsigned char* lds, const Gemm g, const StaticOrder& S, const EpiT& E) {
;     ...
; #pragma unroll
;         for (int a = 0; a < 2; ++a)
; #pragma unroll
;             for (int b = 0; b < 2; ++b)
; #pragma unroll
;                 for (int m = 0; m < 4; ++m)
; #pragma unroll
;                     for (int n = 0; n < 2; ++n) acc[a][b][m][n] = (f32x4){0.f, 0.f, 0.f, 0.f};
;         cur = nxt; cA = nA; cB = nB; ++ui;
;         if (wr == 1) PG8_BAR;
.LBB0_391:
	s_add_u32 s18, s18, 0x84080
	s_addc_u32 s19, s19, 0
	s_add_u32 s51, s20, 0x100
	v_mov_b32_e32 v0, 0
	s_addc_u32 s52, s21, 0
	s_mov_b32 s53, -2
	v_mov_b32_e32 v1, v0
	v_mov_b32_e32 v2, v0
	v_mov_b32_e32 v3, v0
	v_mov_b32_e32 v4, v0
	v_mov_b32_e32 v5, v0
	v_mov_b32_e32 v6, v0
	v_mov_b32_e32 v7, v0
	v_mov_b32_e32 v16, v0
	v_mov_b32_e32 v17, v0
	v_mov_b32_e32 v18, v0
	v_mov_b32_e32 v19, v0
	v_mov_b32_e32 v20, v0
	v_mov_b32_e32 v21, v0
	v_mov_b32_e32 v22, v0
	v_mov_b32_e32 v23, v0
	v_mov_b32_e32 v32, v0
	v_mov_b32_e32 v33, v0
	v_mov_b32_e32 v34, v0
	v_mov_b32_e32 v35, v0
	v_mov_b32_e32 v36, v0
	v_mov_b32_e32 v37, v0
	v_mov_b32_e32 v38, v0
	v_mov_b32_e32 v39, v0
	v_mov_b32_e32 v48, v0
	v_mov_b32_e32 v49, v0
	v_mov_b32_e32 v50, v0
	v_mov_b32_e32 v51, v0
	v_mov_b32_e32 v52, v0
	v_mov_b32_e32 v53, v0
	v_mov_b32_e32 v54, v0
	v_mov_b32_e32 v55, v0
	v_mov_b32_e32 v8, v0
	v_mov_b32_e32 v9, v0
	v_mov_b32_e32 v10, v0
	v_mov_b32_e32 v11, v0
	v_mov_b32_e32 v12, v0
	v_mov_b32_e32 v13, v0
	v_mov_b32_e32 v14, v0
	v_mov_b32_e32 v15, v0
	v_mov_b32_e32 v24, v0
	v_mov_b32_e32 v25, v0
	v_mov_b32_e32 v26, v0
	v_mov_b32_e32 v27, v0
	v_mov_b32_e32 v28, v0
	v_mov_b32_e32 v29, v0
	v_mov_b32_e32 v30, v0
	v_mov_b32_e32 v31, v0
	v_mov_b32_e32 v40, v0
	v_mov_b32_e32 v41, v0
	v_mov_b32_e32 v42, v0
	v_mov_b32_e32 v43, v0
	v_mov_b32_e32 v44, v0
	v_mov_b32_e32 v45, v0
	v_mov_b32_e32 v46, v0
	v_mov_b32_e32 v47, v0
	v_mov_b32_e32 v56, v0
	v_mov_b32_e32 v57, v0
	v_mov_b32_e32 v58, v0
	v_mov_b32_e32 v59, v0
	v_mov_b32_e32 v60, v0
	v_mov_b32_e32 v61, v0
	v_mov_b32_e32 v62, v0
	v_mov_b32_e32 v63, v0
	v_mov_b32_e32 v64, v0
	v_mov_b32_e32 v65, v0
	v_mov_b32_e32 v66, v0
	v_mov_b32_e32 v67, v0
	v_mov_b32_e32 v68, v0
	v_mov_b32_e32 v69, v0
	v_mov_b32_e32 v70, v0
	v_mov_b32_e32 v71, v0
	v_mov_b32_e32 v80, v0
	v_mov_b32_e32 v81, v0
	v_mov_b32_e32 v82, v0
	v_mov_b32_e32 v83, v0
	v_mov_b32_e32 v84, v0
	v_mov_b32_e32 v85, v0
	v_mov_b32_e32 v86, v0
	v_mov_b32_e32 v87, v0
	v_mov_b32_e32 v96, v0
	v_mov_b32_e32 v97, v0
	v_mov_b32_e32 v98, v0
	v_mov_b32_e32 v99, v0
	v_mov_b32_e32 v100, v0
	v_mov_b32_e32 v101, v0
	v_mov_b32_e32 v102, v0
	v_mov_b32_e32 v103, v0
	v_mov_b32_e32 v112, v0
	v_mov_b32_e32 v113, v0
	v_mov_b32_e32 v114, v0
	v_mov_b32_e32 v115, v0
	v_mov_b32_e32 v116, v0
	v_mov_b32_e32 v117, v0
	v_mov_b32_e32 v118, v0
	v_mov_b32_e32 v119, v0
	v_mov_b32_e32 v72, v0
	v_mov_b32_e32 v73, v0
	v_mov_b32_e32 v74, v0
	v_mov_b32_e32 v75, v0
	v_mov_b32_e32 v76, v0
	v_mov_b32_e32 v77, v0
	v_mov_b32_e32 v78, v0
	v_mov_b32_e32 v79, v0
	v_mov_b32_e32 v88, v0
	v_mov_b32_e32 v89, v0
	v_mov_b32_e32 v90, v0
	v_mov_b32_e32 v91, v0
	v_mov_b32_e32 v92, v0
	v_mov_b32_e32 v93, v0
	v_mov_b32_e32 v94, v0
	v_mov_b32_e32 v95, v0
	v_mov_b32_e32 v104, v0
	v_mov_b32_e32 v105, v0
	v_mov_b32_e32 v106, v0
	v_mov_b32_e32 v107, v0
	v_mov_b32_e32 v108, v0
	v_mov_b32_e32 v109, v0
	v_mov_b32_e32 v110, v0
	v_mov_b32_e32 v111, v0
	v_mov_b32_e32 v120, v0
	v_mov_b32_e32 v121, v0
	v_mov_b32_e32 v122, v0
	v_mov_b32_e32 v123, v0
	v_mov_b32_e32 v124, v0
	v_mov_b32_e32 v125, v0
	v_mov_b32_e32 v126, v0
	v_mov_b32_e32 v127, v0
	.p2alignl 6, 3212836864
	s_nop 0
	s_nop 0
	s_nop 0
	s_nop 0
	s_nop 0
	s_nop 0
	s_nop 0
	s_nop 0
	s_nop 0
	s_nop 0
	s_nop 0
	s_nop 0
	s_nop 0
	s_nop 0

; #define PG8_STAGE(bufoff, gbase, voff) do { _Pragma("unroll") for (int _i = 0; _i < 2; ++_i) \
;         __builtin_amdgcn_global_load_lds((const unsigned*)((const char*)(gbase) + (voff)[_i]), (LAS unsigned*)(lds + (bufoff) + ldsw + _i * 8192), 16, 0, 0); } while (0)
; #define PG8_LDA(dst, b, h) do { _Pragma("unroll") for (int m = 0; m < 4; ++m) _Pragma("unroll") for (int k = 0; k < 2; ++k) dst[m][k] = *(const LAS bf16x8*)(lds + PG8_SA(b, h) + aoff + m * 2048 + k * 1024); } while (0)
; #define PG8_LDB(dst, b, h) do { _Pragma("unroll") for (int n = 0; n < 2; ++n) _Pragma("unroll") for (int k = 0; k < 2; ++k) dst[n][k] = *(const LAS bf16x8*)(lds + PG8_SB(b, h) + boff + n * 2048 + k * 1024); } while (0)
; #define PG8_MMA(ai, bj, At, Bt) do { __builtin_amdgcn_s_setprio(1); _Pragma("unroll") for (int m = 0; m < 4; ++m) _Pragma("unroll") for (int n = 0; n < 2; ++n) _Pragma("unroll") for (int k = 0; k < 2; ++k) \
;         acc[ai][bj][m][n] = __builtin_amdgcn_mfma_f32_16x16x32_bf16(Bt[n][k], At[m][k], acc[ai][bj][m][n], 0, 0, 0); __builtin_amdgcn_s_setprio(0); } while (0)
; #define PG8_WAIT_V(n) asm volatile("s_waitcnt vmcnt(" #n ")" ::: "memory")
; #define PG8_WAIT_L(n) asm volatile("s_waitcnt lgkmcnt(" #n ")" ::: "memory")
; #define PG8_BAR __builtin_amdgcn_s_barrier()
; template <class EpiT>
; __device__ __forceinline__ void gemm_phase(LAS unsigned char* lds, const Gemm g, const StaticOrder& S, const EpiT& E) {
;     ...
;         for (int t = 0; t < nt; t += 2) {
;             const bool last = (t == nt - 2);
;             const char* a1 = cA + (size_t)(t + 1) * kstep;
;             const char* a2 = last ? nA : cA + (size_t)(t + 2) * kstep; const char* b2 = last ? nB : cB + (size_t)(t + 2) * kstep;
;             const char* a3 = a2 + kstep; const char* b3 = b2 + kstep;
;             PG8_LDB(B0, 0, 0); PG8_LDB(B1, 0, 1); PG8_SCHED; PG8_LDA(At, 0, 0); PG8_STAGE(PG8_SA(1, 1), a1 + hstepA, voffA);
;             PG8_WAIT_V(8); PG8_WAIT_L(0); PG8_BAR; PG8_MMA(0, 0, At, B0); PG8_MMA(0, 1, At, B1); PG8_BAR; PG8_SCHED;
;     ...
; #pragma unroll
;         for (int a = 0; a < 2; ++a)
; #pragma unroll
;             for (int b = 0; b < 2; ++b)
; #pragma unroll
;                 for (int m = 0; m < 4; ++m)
; #pragma unroll
;                     for (int n = 0; n < 2; ++n) acc[a][b][m][n] = (f32x4){0.f, 0.f, 0.f, 0.f};
;         cur = nxt; cA = nA; cB = nB; ++ui;
.LBB0_515:
	s_add_u32 s16, s16, 0x84080
	s_addc_u32 s17, s17, 0
	s_add_u32 s51, s18, 0x100
	v_mov_b32_e32 v0, 0
	s_addc_u32 s52, s19, 0
	s_mov_b32 s53, -2
	v_mov_b32_e32 v1, v0
	v_mov_b32_e32 v2, v0
	v_mov_b32_e32 v3, v0
	v_mov_b32_e32 v4, v0
	v_mov_b32_e32 v5, v0
	v_mov_b32_e32 v6, v0
	v_mov_b32_e32 v7, v0
	v_mov_b32_e32 v16, v0
	v_mov_b32_e32 v17, v0
	v_mov_b32_e32 v18, v0
	v_mov_b32_e32 v19, v0
	v_mov_b32_e32 v20, v0
	v_mov_b32_e32 v21, v0
	v_mov_b32_e32 v22, v0
	v_mov_b32_e32 v23, v0
	v_mov_b32_e32 v32, v0
	v_mov_b32_e32 v33, v0
	v_mov_b32_e32 v34, v0
	v_mov_b32_e32 v35, v0
	v_mov_b32_e32 v36, v0
	v_mov_b32_e32 v37, v0
	v_mov_b32_e32 v38, v0
	v_mov_b32_e32 v39, v0
	v_mov_b32_e32 v48, v0
	v_mov_b32_e32 v49, v0
	v_mov_b32_e32 v50, v0
	v_mov_b32_e32 v51, v0
	v_mov_b32_e32 v52, v0
	v_mov_b32_e32 v53, v0
	v_mov_b32_e32 v54, v0
	v_mov_b32_e32 v55, v0
	v_mov_b32_e32 v8, v0
	v_mov_b32_e32 v9, v0
	v_mov_b32_e32 v10, v0
	v_mov_b32_e32 v11, v0
	v_mov_b32_e32 v12, v0
	v_mov_b32_e32 v13, v0
	v_mov_b32_e32 v14, v0
	v_mov_b32_e32 v15, v0
	v_mov_b32_e32 v24, v0
	v_mov_b32_e32 v25, v0
	v_mov_b32_e32 v26, v0
	v_mov_b32_e32 v27, v0
	v_mov_b32_e32 v28, v0
	v_mov_b32_e32 v29, v0
	v_mov_b32_e32 v30, v0
	v_mov_b32_e32 v31, v0
	v_mov_b32_e32 v40, v0
	v_mov_b32_e32 v41, v0
	v_mov_b32_e32 v42, v0
	v_mov_b32_e32 v43, v0
	v_mov_b32_e32 v44, v0
	v_mov_b32_e32 v45, v0
	v_mov_b32_e32 v46, v0
	v_mov_b32_e32 v47, v0
	v_mov_b32_e32 v56, v0
	v_mov_b32_e32 v57, v0
	v_mov_b32_e32 v58, v0
	v_mov_b32_e32 v59, v0
	v_mov_b32_e32 v60, v0
	v_mov_b32_e32 v61, v0
	v_mov_b32_e32 v62, v0
	v_mov_b32_e32 v63, v0
	v_mov_b32_e32 v64, v0
	v_mov_b32_e32 v65, v0
	v_mov_b32_e32 v66, v0
	v_mov_b32_e32 v67, v0
	v_mov_b32_e32 v68, v0
	v_mov_b32_e32 v69, v0
	v_mov_b32_e32 v70, v0
	v_mov_b32_e32 v71, v0
	v_mov_b32_e32 v80, v0
	v_mov_b32_e32 v81, v0
	v_mov_b32_e32 v82, v0
	v_mov_b32_e32 v83, v0
	v_mov_b32_e32 v84, v0
	v_mov_b32_e32 v85, v0
	v_mov_b32_e32 v86, v0
	v_mov_b32_e32 v87, v0
	v_mov_b32_e32 v96, v0
	v_mov_b32_e32 v97, v0
	v_mov_b32_e32 v98, v0
	v_mov_b32_e32 v99, v0
	v_mov_b32_e32 v100, v0
	v_mov_b32_e32 v101, v0
	v_mov_b32_e32 v102, v0
	v_mov_b32_e32 v103, v0
	v_mov_b32_e32 v112, v0
	v_mov_b32_e32 v113, v0
	v_mov_b32_e32 v114, v0
	v_mov_b32_e32 v115, v0
	v_mov_b32_e32 v116, v0
	v_mov_b32_e32 v117, v0
	v_mov_b32_e32 v118, v0
	v_mov_b32_e32 v119, v0
	v_mov_b32_e32 v72, v0
	v_mov_b32_e32 v73, v0
	v_mov_b32_e32 v74, v0
	v_mov_b32_e32 v75, v0
	v_mov_b32_e32 v76, v0
	v_mov_b32_e32 v77, v0
	v_mov_b32_e32 v78, v0
	v_mov_b32_e32 v79, v0
	v_mov_b32_e32 v88, v0
	v_mov_b32_e32 v89, v0
	v_mov_b32_e32 v90, v0
	v_mov_b32_e32 v91, v0
	v_mov_b32_e32 v92, v0
	v_mov_b32_e32 v93, v0
	v_mov_b32_e32 v94, v0
	v_mov_b32_e32 v95, v0
	v_mov_b32_e32 v104, v0
	v_mov_b32_e32 v105, v0
	v_mov_b32_e32 v106, v0
	v_mov_b32_e32 v107, v0
	v_mov_b32_e32 v108, v0
	v_mov_b32_e32 v109, v0
	v_mov_b32_e32 v110, v0
	v_mov_b32_e32 v111, v0
	v_mov_b32_e32 v120, v0
	v_mov_b32_e32 v121, v0
	v_mov_b32_e32 v122, v0
	v_mov_b32_e32 v123, v0
	v_mov_b32_e32 v124, v0
	v_mov_b32_e32 v125, v0
	v_mov_b32_e32 v126, v0
	v_mov_b32_e32 v127, v0
	.p2alignl 6, 3212836864
	s_nop 0
	s_nop 0
	s_nop 0
	s_nop 0
	s_nop 0
	s_nop 0
	s_nop 0
	s_nop 0
	s_nop 0
	s_nop 0
.LBB0_516:
	ds_read_b128 v[154:157], v150
	ds_read_b128 v[158:161], v150 offset:1024
	ds_read_b128 v[170:173], v150 offset:2048
	ds_read_b128 v[174:177], v150 offset:3072
	ds_read_b128 v[178:181], v151
	ds_read_b128 v[182:185], v151 offset:1024
	ds_read_b128 v[186:189], v151 offset:2048
	ds_read_b128 v[190:193], v151 offset:3072
	s_add_u32 s18, s16, 0xfff7c080
	s_addc_u32 s19, s17, -1
	s_cmp_eq_u32 s53, 28
	s_cselect_b32 s21, s3, s19
	s_cselect_b32 s20, s2, s18
	s_cselect_b32 s19, s15, s52
	s_cselect_b32 s18, s14, s51
	v_lshl_add_u64 v[144:145], s[16:17], 0, v[136:137]
	s_add_i32 m0, s36, 0xc000
	ds_read_b128 v[194:197], v152
	ds_read_b128 v[198:201], v152 offset:1024
	ds_read_b128 v[202:205], v152 offset:2048
	ds_read_b128 v[206:209], v152 offset:3072
	ds_read_b128 v[210:213], v152 offset:4096
	ds_read_b128 v[214:217], v152 offset:5120
	ds_read_b128 v[218:221], v152 offset:6144
	ds_read_b128 v[222:225], v152 offset:7168
	global_load_lds_dwordx4 v[144:145], off
	v_lshl_add_u64 v[144:145], s[16:17], 0, v[138:139]
	s_add_i32 m0, s36, 0xe000
	s_nop 0
	global_load_lds_dwordx4 v[144:145], off
	s_waitcnt vmcnt(8)
	s_waitcnt lgkmcnt(0)
	s_barrier
	s_setprio 1
	s_waitcnt lgkmcnt(0)
	v_mfma_f32_16x16x32_bf16 v[124:127], v[154:157], v[194:197], v[124:127]
	v_mfma_f32_16x16x32_bf16 v[120:123], v[170:173], v[194:197], v[120:123]
	v_mfma_f32_16x16x32_bf16 v[108:111], v[154:157], v[202:205], v[108:111]
	v_mfma_f32_16x16x32_bf16 v[104:107], v[170:173], v[202:205], v[104:107]
	v_mfma_f32_16x16x32_bf16 v[92:95], v[154:157], v[210:213], v[92:95]
	v_mfma_f32_16x16x32_bf16 v[88:91], v[170:173], v[210:213], v[88:91]
	v_mfma_f32_16x16x32_bf16 v[76:79], v[154:157], v[218:221], v[76:79]
	v_mfma_f32_16x16x32_bf16 v[72:75], v[170:173], v[218:221], v[72:75]
	v_mfma_f32_16x16x32_bf16 v[124:127], v[158:161], v[198:201], v[124:127]
	v_mfma_f32_16x16x32_bf16 v[120:123], v[174:177], v[198:201], v[120:123]
	v_mfma_f32_16x16x32_bf16 v[108:111], v[158:161], v[206:209], v[108:111]
	v_mfma_f32_16x16x32_bf16 v[104:107], v[174:177], v[206:209], v[104:107]
	v_mfma_f32_16x16x32_bf16 v[92:95], v[158:161], v[214:217], v[92:95]
	v_mfma_f32_16x16x32_bf16 v[88:91], v[174:177], v[214:217], v[88:91]
	v_mfma_f32_16x16x32_bf16 v[76:79], v[158:161], v[222:225], v[76:79]
	v_mfma_f32_16x16x32_bf16 v[72:75], v[174:177], v[222:225], v[72:75]
	s_setprio 0
	s_setprio 1
	v_mfma_f32_16x16x32_bf16 v[116:119], v[178:181], v[194:197], v[116:119]
	v_mfma_f32_16x16x32_bf16 v[112:115], v[186:189], v[194:197], v[112:115]
	v_mfma_f32_16x16x32_bf16 v[100:103], v[178:181], v[202:205], v[100:103]
	v_mfma_f32_16x16x32_bf16 v[96:99], v[186:189], v[202:205], v[96:99]
	v_mfma_f32_16x16x32_bf16 v[84:87], v[178:181], v[210:213], v[84:87]
	v_mfma_f32_16x16x32_bf16 v[80:83], v[186:189], v[210:213], v[80:83]
	v_mfma_f32_16x16x32_bf16 v[68:71], v[178:181], v[218:221], v[68:71]
	v_mfma_f32_16x16x32_bf16 v[64:67], v[186:189], v[218:221], v[64:67]
	v_mfma_f32_16x16x32_bf16 v[116:119], v[182:185], v[198:201], v[116:119]
	v_mfma_f32_16x16x32_bf16 v[112:115], v[190:193], v[198:201], v[112:115]
	v_mfma_f32_16x16x32_bf16 v[100:103], v[182:185], v[206:209], v[100:103]
	v_mfma_f32_16x16x32_bf16 v[96:99], v[190:193], v[206:209], v[96:99]
	v_mfma_f32_16x16x32_bf16 v[84:87], v[182:185], v[214:217], v[84:87]
	v_mfma_f32_16x16x32_bf16 v[80:83], v[190:193], v[214:217], v[80:83]
	v_mfma_f32_16x16x32_bf16 v[68:71], v[182:185], v[222:225], v[68:71]
	v_mfma_f32_16x16x32_bf16 v[64:67], v[190:193], v[222:225], v[64:67]
	s_setprio 0
	s_barrier
; #define PG8_STAGE(bufoff, gbase, voff) do { _Pragma("unroll") for (int _i = 0; _i < 2; ++_i) \
;         __builtin_amdgcn_global_load_lds((const unsigned*)((const char*)(gbase) + (voff)[_i]), (LAS unsigned*)(lds + (bufoff) + ldsw + _i * 8192), 16, 0, 0); } while (0)
; #define PG8_LDA(dst, b, h) do { _Pragma("unroll") for (int m = 0; m < 4; ++m) _Pragma("unroll") for (int k = 0; k < 2; ++k) dst[m][k] = *(const LAS bf16x8*)(lds + PG8_SA(b, h) + aoff + m * 2048 + k * 1024); } while (0)
; #define PG8_LDB(dst, b, h) do { _Pragma("unroll") for (int n = 0; n < 2; ++n) _Pragma("unroll") for (int k = 0; k < 2; ++k) dst[n][k] = *(const LAS bf16x8*)(lds + PG8_SB(b, h) + boff + n * 2048 + k * 1024); } while (0)
; #define PG8_MMA(ai, bj, At, Bt) do { __builtin_amdgcn_s_setprio(1); _Pragma("unroll") for (int m = 0; m < 4; ++m) _Pragma("unroll") for (int n = 0; n < 2; ++n) _Pragma("unroll") for (int k = 0; k < 2; ++k) \
;         acc[ai][bj][m][n] = __builtin_amdgcn_mfma_f32_16x16x32_bf16(Bt[n][k], At[m][k], acc[ai][bj][m][n], 0, 0, 0); __builtin_amdgcn_s_setprio(0); } while (0)
; #define PG8_WAIT_V(n) asm volatile("s_waitcnt vmcnt(" #n ")" ::: "memory")
; #define PG8_WAIT_L(n) asm volatile("s_waitcnt lgkmcnt(" #n ")" ::: "memory")
; #define PG8_BAR __builtin_amdgcn_s_barrier()
; #define PG8_SCHED __builtin_amdgcn_sched_barrier(0)
; template <class EpiT>
; __device__ __forceinline__ void gemm_phase(LAS unsigned char* lds, const Gemm g, const StaticOrder& S, const EpiT& E) {
;     ...
;             PG8_LDA(At, 0, 1); PG8_STAGE(PG8_SB(0, 0), b2, voffB); PG8_STAGE(PG8_SB(0, 1), b2 + hstepB, voffB); PG8_STAGE(PG8_SA(0, 0), a2, voffA);
;             PG8_WAIT_V(8); PG8_WAIT_L(0); PG8_BAR; PG8_MMA(1, 0, At, B0); PG8_MMA(1, 1, At, B1); PG8_BAR; PG8_SCHED;
;             PG8_LDB(B0, 1, 0); PG8_LDB(B1, 1, 1); PG8_SCHED; PG8_LDA(At, 1, 0); PG8_STAGE(PG8_SA(0, 1), a2 + hstepA, voffA);
;             PG8_WAIT_V(8); PG8_WAIT_L(0); PG8_BAR; PG8_MMA(0, 0, At, B0); PG8_MMA(0, 1, At, B1); PG8_BAR; PG8_SCHED;
	s_add_i32 s54, s44, s27
	v_lshl_add_u64 v[144:145], s[18:19], 0, v[132:133]
	s_mov_b32 m0, s54
	ds_read_b128 v[194:197], v152 offset:16384
	ds_read_b128 v[198:201], v152 offset:17408
	ds_read_b128 v[202:205], v152 offset:18432
	ds_read_b128 v[206:209], v152 offset:19456
	ds_read_b128 v[210:213], v152 offset:20480
	ds_read_b128 v[214:217], v152 offset:21504
	ds_read_b128 v[218:221], v152 offset:22528
	ds_read_b128 v[222:225], v152 offset:23552
	global_load_lds_dwordx4 v[144:145], off
	s_add_i32 m0, s54, 0x2000
	s_add_u32 s54, s18, 0x84000
	v_lshl_add_u64 v[162:163], s[18:19], 0, v[128:129]
	s_addc_u32 s55, s19, 0
	s_add_i32 s56, s45, s27
	global_load_lds_dwordx4 v[162:163], off
	v_lshl_add_u64 v[166:167], s[54:55], 0, v[132:133]
	s_mov_b32 m0, s56
	v_lshl_add_u64 v[226:227], s[20:21], 0, v[130:131]
	global_load_lds_dwordx4 v[166:167], off
	v_lshl_add_u64 v[166:167], s[54:55], 0, v[128:129]
	s_add_i32 m0, s56, 0x2000
	s_nop 0
	global_load_lds_dwordx4 v[166:167], off
	v_lshl_add_u64 v[166:167], s[20:21], 0, v[134:135]
	s_mov_b32 m0, s36
	s_nop 0
	global_load_lds_dwordx4 v[166:167], off
	s_mov_b32 m0, s37
	s_nop 0
	global_load_lds_dwordx4 v[226:227], off
	s_waitcnt vmcnt(8)
	s_waitcnt lgkmcnt(0)
	s_barrier
	s_setprio 1
	s_waitcnt lgkmcnt(0)
	v_mfma_f32_16x16x32_bf16 v[60:63], v[154:157], v[194:197], v[60:63]
	v_mfma_f32_16x16x32_bf16 v[56:59], v[170:173], v[194:197], v[56:59]
	v_mfma_f32_16x16x32_bf16 v[44:47], v[154:157], v[202:205], v[44:47]
	v_mfma_f32_16x16x32_bf16 v[40:43], v[170:173], v[202:205], v[40:43]
	v_mfma_f32_16x16x32_bf16 v[28:31], v[154:157], v[210:213], v[28:31]
	v_mfma_f32_16x16x32_bf16 v[24:27], v[170:173], v[210:213], v[24:27]
	v_mfma_f32_16x16x32_bf16 v[12:15], v[154:157], v[218:221], v[12:15]
	v_mfma_f32_16x16x32_bf16 v[8:11], v[170:173], v[218:221], v[8:11]
	v_mfma_f32_16x16x32_bf16 v[60:63], v[158:161], v[198:201], v[60:63]
	v_mfma_f32_16x16x32_bf16 v[56:59], v[174:177], v[198:201], v[56:59]
	v_mfma_f32_16x16x32_bf16 v[44:47], v[158:161], v[206:209], v[44:47]
	v_mfma_f32_16x16x32_bf16 v[40:43], v[174:177], v[206:209], v[40:43]
	v_mfma_f32_16x16x32_bf16 v[28:31], v[158:161], v[214:217], v[28:31]
	v_mfma_f32_16x16x32_bf16 v[24:27], v[174:177], v[214:217], v[24:27]
	v_mfma_f32_16x16x32_bf16 v[12:15], v[158:161], v[222:225], v[12:15]
	v_mfma_f32_16x16x32_bf16 v[8:11], v[174:177], v[222:225], v[8:11]
	s_setprio 0
	s_setprio 1
	v_mfma_f32_16x16x32_bf16 v[52:55], v[178:181], v[194:197], v[52:55]
	v_mfma_f32_16x16x32_bf16 v[48:51], v[186:189], v[194:197], v[48:51]
	v_mfma_f32_16x16x32_bf16 v[36:39], v[178:181], v[202:205], v[36:39]
	v_mfma_f32_16x16x32_bf16 v[32:35], v[186:189], v[202:205], v[32:35]
	v_mfma_f32_16x16x32_bf16 v[20:23], v[178:181], v[210:213], v[20:23]
	v_mfma_f32_16x16x32_bf16 v[16:19], v[186:189], v[210:213], v[16:19]
	v_mfma_f32_16x16x32_bf16 v[4:7], v[178:181], v[218:221], v[4:7]
	v_mfma_f32_16x16x32_bf16 v[0:3], v[186:189], v[218:221], v[0:3]
	v_mfma_f32_16x16x32_bf16 v[52:55], v[182:185], v[198:201], v[52:55]
	v_mfma_f32_16x16x32_bf16 v[48:51], v[190:193], v[198:201], v[48:51]
	v_mfma_f32_16x16x32_bf16 v[36:39], v[182:185], v[206:209], v[36:39]
	v_mfma_f32_16x16x32_bf16 v[32:35], v[190:193], v[206:209], v[32:35]
	v_mfma_f32_16x16x32_bf16 v[20:23], v[182:185], v[214:217], v[20:23]
	v_mfma_f32_16x16x32_bf16 v[16:19], v[190:193], v[214:217], v[16:19]
	v_mfma_f32_16x16x32_bf16 v[4:7], v[182:185], v[222:225], v[4:7]
	v_mfma_f32_16x16x32_bf16 v[0:3], v[190:193], v[222:225], v[0:3]
	s_setprio 0
	s_barrier
	s_add_i32 s54, 0, 0x18000
	v_add_u32_e32 v153, s54, v147
	s_add_i32 s55, 0, 0x1c000
	ds_read_b128 v[154:157], v153
	ds_read_b128 v[158:161], v153 offset:1024
	ds_read_b128 v[170:173], v153 offset:2048
	ds_read_b128 v[174:177], v153 offset:3072
	v_add_u32_e32 v153, s55, v147
	ds_read_b128 v[178:181], v153
	ds_read_b128 v[182:185], v153 offset:1024
	ds_read_b128 v[186:189], v153 offset:2048
	ds_read_b128 v[190:193], v153 offset:3072
	s_add_u32 s20, s20, 0x84000
	s_addc_u32 s21, s21, 0
	s_mov_b32 m0, s38
	v_lshl_add_u64 v[228:229], s[20:21], 0, v[134:135]
	ds_read_b128 v[194:197], v152 offset:32768
	ds_read_b128 v[198:201], v152 offset:33792
	ds_read_b128 v[202:205], v152 offset:34816
	ds_read_b128 v[206:209], v152 offset:35840
	ds_read_b128 v[210:213], v152 offset:36864
	ds_read_b128 v[214:217], v152 offset:37888
	ds_read_b128 v[218:221], v152 offset:38912
	ds_read_b128 v[222:225], v152 offset:39936
	global_load_lds_dwordx4 v[228:229], off
	v_lshl_add_u64 v[228:229], s[20:21], 0, v[130:131]
	s_mov_b32 m0, s39
	s_nop 0
	global_load_lds_dwordx4 v[228:229], off
	s_waitcnt vmcnt(8)
	s_waitcnt lgkmcnt(0)
	s_barrier
; #define PG8_STAGE(bufoff, gbase, voff) do { _Pragma("unroll") for (int _i = 0; _i < 2; ++_i) \
;         __builtin_amdgcn_global_load_lds((const unsigned*)((const char*)(gbase) + (voff)[_i]), (LAS unsigned*)(lds + (bufoff) + ldsw + _i * 8192), 16, 0, 0); } while (0)
; #define PG8_LDA(dst, b, h) do { _Pragma("unroll") for (int m = 0; m < 4; ++m) _Pragma("unroll") for (int k = 0; k < 2; ++k) dst[m][k] = *(const LAS bf16x8*)(lds + PG8_SA(b, h) + aoff + m * 2048 + k * 1024); } while (0)
; #define PG8_MMA(ai, bj, At, Bt) do { __builtin_amdgcn_s_setprio(1); _Pragma("unroll") for (int m = 0; m < 4; ++m) _Pragma("unroll") for (int n = 0; n < 2; ++n) _Pragma("unroll") for (int k = 0; k < 2; ++k) \
;         acc[ai][bj][m][n] = __builtin_amdgcn_mfma_f32_16x16x32_bf16(Bt[n][k], At[m][k], acc[ai][bj][m][n], 0, 0, 0); __builtin_amdgcn_s_setprio(0); } while (0)
; #define PG8_WAIT_V(n) asm volatile("s_waitcnt vmcnt(" #n ")" ::: "memory")
; #define PG8_WAIT_L(n) asm volatile("s_waitcnt lgkmcnt(" #n ")" ::: "memory")
; #define PG8_BAR __builtin_amdgcn_s_barrier()
; #define PG8_SCHED __builtin_amdgcn_sched_barrier(0)
; template <class EpiT>
; __device__ __forceinline__ void gemm_phase(LAS unsigned char* lds, const Gemm g, const StaticOrder& S, const EpiT& E) {
;     ...
;             PG8_WAIT_V(8); PG8_WAIT_L(0); PG8_BAR; PG8_MMA(0, 0, At, B0); PG8_MMA(0, 1, At, B1); PG8_BAR; PG8_SCHED;
;             PG8_LDA(At, 1, 1); PG8_STAGE(PG8_SB(1, 0), b3, voffB); PG8_STAGE(PG8_SB(1, 1), b3 + hstepB, voffB); PG8_STAGE(PG8_SA(1, 0), a3, voffA);
;             PG8_WAIT_V(8); PG8_WAIT_L(0); PG8_BAR; PG8_MMA(1, 0, At, B0); PG8_MMA(1, 1, At, B1); PG8_BAR; PG8_SCHED;
;         }
;         if (wr == 0) PG8_BAR;
	s_setprio 1
	s_waitcnt lgkmcnt(0)
	v_mfma_f32_16x16x32_bf16 v[124:127], v[154:157], v[194:197], v[124:127]
	v_mfma_f32_16x16x32_bf16 v[120:123], v[170:173], v[194:197], v[120:123]
	v_mfma_f32_16x16x32_bf16 v[108:111], v[154:157], v[202:205], v[108:111]
	v_mfma_f32_16x16x32_bf16 v[104:107], v[170:173], v[202:205], v[104:107]
	v_mfma_f32_16x16x32_bf16 v[92:95], v[154:157], v[210:213], v[92:95]
	v_mfma_f32_16x16x32_bf16 v[88:91], v[170:173], v[210:213], v[88:91]
	v_mfma_f32_16x16x32_bf16 v[76:79], v[154:157], v[218:221], v[76:79]
	v_mfma_f32_16x16x32_bf16 v[72:75], v[170:173], v[218:221], v[72:75]
	v_mfma_f32_16x16x32_bf16 v[124:127], v[158:161], v[198:201], v[124:127]
	v_mfma_f32_16x16x32_bf16 v[120:123], v[174:177], v[198:201], v[120:123]
	v_mfma_f32_16x16x32_bf16 v[108:111], v[158:161], v[206:209], v[108:111]
	v_mfma_f32_16x16x32_bf16 v[104:107], v[174:177], v[206:209], v[104:107]
	v_mfma_f32_16x16x32_bf16 v[92:95], v[158:161], v[214:217], v[92:95]
	v_mfma_f32_16x16x32_bf16 v[88:91], v[174:177], v[214:217], v[88:91]
	v_mfma_f32_16x16x32_bf16 v[76:79], v[158:161], v[222:225], v[76:79]
	v_mfma_f32_16x16x32_bf16 v[72:75], v[174:177], v[222:225], v[72:75]
	s_setprio 0
	s_setprio 1
	v_mfma_f32_16x16x32_bf16 v[116:119], v[178:181], v[194:197], v[116:119]
	v_mfma_f32_16x16x32_bf16 v[112:115], v[186:189], v[194:197], v[112:115]
	v_mfma_f32_16x16x32_bf16 v[100:103], v[178:181], v[202:205], v[100:103]
	v_mfma_f32_16x16x32_bf16 v[96:99], v[186:189], v[202:205], v[96:99]
	v_mfma_f32_16x16x32_bf16 v[84:87], v[178:181], v[210:213], v[84:87]
	v_mfma_f32_16x16x32_bf16 v[80:83], v[186:189], v[210:213], v[80:83]
	v_mfma_f32_16x16x32_bf16 v[68:71], v[178:181], v[218:221], v[68:71]
	v_mfma_f32_16x16x32_bf16 v[64:67], v[186:189], v[218:221], v[64:67]
	v_mfma_f32_16x16x32_bf16 v[116:119], v[182:185], v[198:201], v[116:119]
	v_mfma_f32_16x16x32_bf16 v[112:115], v[190:193], v[198:201], v[112:115]
	v_mfma_f32_16x16x32_bf16 v[100:103], v[182:185], v[206:209], v[100:103]
	v_mfma_f32_16x16x32_bf16 v[96:99], v[190:193], v[206:209], v[96:99]
	v_mfma_f32_16x16x32_bf16 v[84:87], v[182:185], v[214:217], v[84:87]
	v_mfma_f32_16x16x32_bf16 v[80:83], v[190:193], v[214:217], v[80:83]
	v_mfma_f32_16x16x32_bf16 v[68:71], v[182:185], v[222:225], v[68:71]
	v_mfma_f32_16x16x32_bf16 v[64:67], v[190:193], v[222:225], v[64:67]
	s_setprio 0
	s_barrier
	s_add_i32 s20, s54, s27
	v_lshl_add_u64 v[144:145], v[144:145], 0, s[10:11]
	s_mov_b32 m0, s20
	ds_read_b128 v[194:197], v152 offset:49152
	ds_read_b128 v[198:201], v152 offset:50176
	ds_read_b128 v[202:205], v152 offset:51200
	ds_read_b128 v[206:209], v152 offset:52224
	ds_read_b128 v[210:213], v152 offset:53248
	ds_read_b128 v[214:217], v152 offset:54272
	ds_read_b128 v[218:221], v152 offset:55296
	ds_read_b128 v[222:225], v152 offset:56320
	global_load_lds_dwordx4 v[144:145], off
	s_add_i32 m0, s20, 0x2000
	s_add_u32 s18, s18, 0x84080
	v_lshl_add_u64 v[144:145], v[162:163], 0, s[10:11]
	s_addc_u32 s19, s19, 0
	s_add_i32 s20, s55, s27
	global_load_lds_dwordx4 v[144:145], off
	v_lshl_add_u64 v[144:145], s[18:19], 0, v[132:133]
	s_mov_b32 m0, s20
	s_nop 0
	global_load_lds_dwordx4 v[144:145], off
	v_lshl_add_u64 v[144:145], s[18:19], 0, v[128:129]
	s_add_i32 m0, s20, 0x2000
	s_nop 0
	global_load_lds_dwordx4 v[144:145], off
	v_lshl_add_u64 v[144:145], v[166:167], 0, s[10:11]
	s_mov_b32 m0, s41
	s_nop 0
	global_load_lds_dwordx4 v[144:145], off
	v_lshl_add_u64 v[144:145], v[226:227], 0, s[10:11]
	s_mov_b32 m0, s42
	s_nop 0
	global_load_lds_dwordx4 v[144:145], off
	s_waitcnt vmcnt(8)
	s_waitcnt lgkmcnt(0)
	s_barrier
	s_setprio 1
	s_waitcnt lgkmcnt(0)
	v_mfma_f32_16x16x32_bf16 v[60:63], v[154:157], v[194:197], v[60:63]
	v_mfma_f32_16x16x32_bf16 v[56:59], v[170:173], v[194:197], v[56:59]
	v_mfma_f32_16x16x32_bf16 v[44:47], v[154:157], v[202:205], v[44:47]
	v_mfma_f32_16x16x32_bf16 v[40:43], v[170:173], v[202:205], v[40:43]
	v_mfma_f32_16x16x32_bf16 v[28:31], v[154:157], v[210:213], v[28:31]
	v_mfma_f32_16x16x32_bf16 v[24:27], v[170:173], v[210:213], v[24:27]
	v_mfma_f32_16x16x32_bf16 v[12:15], v[154:157], v[218:221], v[12:15]
	v_mfma_f32_16x16x32_bf16 v[8:11], v[170:173], v[218:221], v[8:11]
	v_mfma_f32_16x16x32_bf16 v[60:63], v[158:161], v[198:201], v[60:63]
	v_mfma_f32_16x16x32_bf16 v[56:59], v[174:177], v[198:201], v[56:59]
	v_mfma_f32_16x16x32_bf16 v[44:47], v[158:161], v[206:209], v[44:47]
	v_mfma_f32_16x16x32_bf16 v[40:43], v[174:177], v[206:209], v[40:43]
	v_mfma_f32_16x16x32_bf16 v[28:31], v[158:161], v[214:217], v[28:31]
	v_mfma_f32_16x16x32_bf16 v[24:27], v[174:177], v[214:217], v[24:27]
	v_mfma_f32_16x16x32_bf16 v[12:15], v[158:161], v[222:225], v[12:15]
	v_mfma_f32_16x16x32_bf16 v[8:11], v[174:177], v[222:225], v[8:11]
	s_setprio 0
	s_setprio 1
	v_mfma_f32_16x16x32_bf16 v[52:55], v[178:181], v[194:197], v[52:55]
	v_mfma_f32_16x16x32_bf16 v[48:51], v[186:189], v[194:197], v[48:51]
	v_mfma_f32_16x16x32_bf16 v[36:39], v[178:181], v[202:205], v[36:39]
	v_mfma_f32_16x16x32_bf16 v[32:35], v[186:189], v[202:205], v[32:35]
	v_mfma_f32_16x16x32_bf16 v[20:23], v[178:181], v[210:213], v[20:23]
	v_mfma_f32_16x16x32_bf16 v[16:19], v[186:189], v[210:213], v[16:19]
	v_mfma_f32_16x16x32_bf16 v[4:7], v[178:181], v[218:221], v[4:7]
	v_mfma_f32_16x16x32_bf16 v[0:3], v[186:189], v[218:221], v[0:3]
	v_mfma_f32_16x16x32_bf16 v[52:55], v[182:185], v[198:201], v[52:55]
	v_mfma_f32_16x16x32_bf16 v[48:51], v[190:193], v[198:201], v[48:51]
	v_mfma_f32_16x16x32_bf16 v[36:39], v[182:185], v[206:209], v[36:39]
	v_mfma_f32_16x16x32_bf16 v[32:35], v[190:193], v[206:209], v[32:35]
	v_mfma_f32_16x16x32_bf16 v[20:23], v[182:185], v[214:217], v[20:23]
	v_mfma_f32_16x16x32_bf16 v[16:19], v[190:193], v[214:217], v[16:19]
	v_mfma_f32_16x16x32_bf16 v[4:7], v[182:185], v[222:225], v[4:7]
	v_mfma_f32_16x16x32_bf16 v[0:3], v[190:193], v[222:225], v[0:3]
	s_setprio 0
	s_barrier
	s_add_i32 s53, s53, 2
	s_add_u32 s16, s16, 0x100
	s_addc_u32 s17, s17, 0
	s_add_u32 s51, s51, 0x100
	s_addc_u32 s52, s52, 0
	s_cmp_gt_u32 s53, 29
	s_cbranch_scc0 .LBB0_516
	s_and_b64 vcc, exec, s[12:13]
	s_cbranch_vccz .LBB0_519
	s_barrier

; #define PG8_STAGE(bufoff, gbase, voff) do { _Pragma("unroll") for (int _i = 0; _i < 2; ++_i) \
;         __builtin_amdgcn_global_load_lds((const unsigned*)((const char*)(gbase) + (voff)[_i]), (LAS unsigned*)(lds + (bufoff) + ldsw + _i * 8192), 16, 0, 0); } while (0)
; #define PG8_LDA(dst, b, h) do { _Pragma("unroll") for (int m = 0; m < 4; ++m) _Pragma("unroll") for (int k = 0; k < 2; ++k) dst[m][k] = *(const LAS bf16x8*)(lds + PG8_SA(b, h) + aoff + m * 2048 + k * 1024); } while (0)
; #define PG8_LDB(dst, b, h) do { _Pragma("unroll") for (int n = 0; n < 2; ++n) _Pragma("unroll") for (int k = 0; k < 2; ++k) dst[n][k] = *(const LAS bf16x8*)(lds + PG8_SB(b, h) + boff + n * 2048 + k * 1024); } while (0)
; #define PG8_MMA(ai, bj, At, Bt) do { __builtin_amdgcn_s_setprio(1); _Pragma("unroll") for (int m = 0; m < 4; ++m) _Pragma("unroll") for (int n = 0; n < 2; ++n) _Pragma("unroll") for (int k = 0; k < 2; ++k) \
;         acc[ai][bj][m][n] = __builtin_amdgcn_mfma_f32_16x16x32_bf16(Bt[n][k], At[m][k], acc[ai][bj][m][n], 0, 0, 0); __builtin_amdgcn_s_setprio(0); } while (0)
; #define PG8_WAIT_V(n) asm volatile("s_waitcnt vmcnt(" #n ")" ::: "memory")
; #define PG8_WAIT_L(n) asm volatile("s_waitcnt lgkmcnt(" #n ")" ::: "memory")
; #define PG8_BAR __builtin_amdgcn_s_barrier()
; template <class EpiT>
; __device__ __forceinline__ void gemm_phase(LAS unsigned char* lds, const Gemm g, const StaticOrder& S, const EpiT& E) {
;     ...
;         for (int t = 0; t < nt; t += 2) {
;             const bool last = (t == nt - 2);
;             const char* a1 = cA + (size_t)(t + 1) * kstep;
;             const char* a2 = last ? nA : cA + (size_t)(t + 2) * kstep; const char* b2 = last ? nB : cB + (size_t)(t + 2) * kstep;
;             const char* a3 = a2 + kstep; const char* b3 = b2 + kstep;
;             PG8_LDB(B0, 0, 0); PG8_LDB(B1, 0, 1); PG8_SCHED; PG8_LDA(At, 0, 0); PG8_STAGE(PG8_SA(1, 1), a1 + hstepA, voffA);
;             PG8_WAIT_V(8); PG8_WAIT_L(0); PG8_BAR; PG8_MMA(0, 0, At, B0); PG8_MMA(0, 1, At, B1); PG8_BAR; PG8_SCHED;
;     ...
; #pragma unroll
;         for (int a = 0; a < 2; ++a)
; #pragma unroll
;             for (int b = 0; b < 2; ++b)
; #pragma unroll
;                 for (int m = 0; m < 4; ++m)
; #pragma unroll
;                     for (int n = 0; n < 2; ++n) acc[a][b][m][n] = (f32x4){0.f, 0.f, 0.f, 0.f};
;         cur = nxt; cA = nA; cB = nB; ++ui;
.LBB0_594:
	s_add_u32 s18, s18, 0x164080
	s_addc_u32 s19, s19, 0
	s_add_u32 s53, s20, 0x100
	v_mov_b32_e32 v0, 0
	s_addc_u32 s54, s21, 0
	s_mov_b32 s55, -2
	v_mov_b32_e32 v1, v0
	v_mov_b32_e32 v2, v0
	v_mov_b32_e32 v3, v0
	v_mov_b32_e32 v4, v0
	v_mov_b32_e32 v5, v0
	v_mov_b32_e32 v6, v0
	v_mov_b32_e32 v7, v0
	v_mov_b32_e32 v16, v0
	v_mov_b32_e32 v17, v0
	v_mov_b32_e32 v18, v0
	v_mov_b32_e32 v19, v0
	v_mov_b32_e32 v20, v0
	v_mov_b32_e32 v21, v0
	v_mov_b32_e32 v22, v0
	v_mov_b32_e32 v23, v0
	v_mov_b32_e32 v32, v0
	v_mov_b32_e32 v33, v0
	v_mov_b32_e32 v34, v0
	v_mov_b32_e32 v35, v0
	v_mov_b32_e32 v36, v0
	v_mov_b32_e32 v37, v0
	v_mov_b32_e32 v38, v0
	v_mov_b32_e32 v39, v0
	v_mov_b32_e32 v48, v0
	v_mov_b32_e32 v49, v0
	v_mov_b32_e32 v50, v0
	v_mov_b32_e32 v51, v0
	v_mov_b32_e32 v52, v0
	v_mov_b32_e32 v53, v0
	v_mov_b32_e32 v54, v0
	v_mov_b32_e32 v55, v0
	v_mov_b32_e32 v8, v0
	v_mov_b32_e32 v9, v0
	v_mov_b32_e32 v10, v0
	v_mov_b32_e32 v11, v0
	v_mov_b32_e32 v12, v0
	v_mov_b32_e32 v13, v0
	v_mov_b32_e32 v14, v0
	v_mov_b32_e32 v15, v0
	v_mov_b32_e32 v24, v0
	v_mov_b32_e32 v25, v0
	v_mov_b32_e32 v26, v0
	v_mov_b32_e32 v27, v0
	v_mov_b32_e32 v28, v0
	v_mov_b32_e32 v29, v0
	v_mov_b32_e32 v30, v0
	v_mov_b32_e32 v31, v0
	v_mov_b32_e32 v40, v0
	v_mov_b32_e32 v41, v0
	v_mov_b32_e32 v42, v0
	v_mov_b32_e32 v43, v0
	v_mov_b32_e32 v44, v0
	v_mov_b32_e32 v45, v0
	v_mov_b32_e32 v46, v0
	v_mov_b32_e32 v47, v0
	v_mov_b32_e32 v56, v0
	v_mov_b32_e32 v57, v0
	v_mov_b32_e32 v58, v0
	v_mov_b32_e32 v59, v0
	v_mov_b32_e32 v60, v0
	v_mov_b32_e32 v61, v0
	v_mov_b32_e32 v62, v0
	v_mov_b32_e32 v63, v0
	v_mov_b32_e32 v64, v0
	v_mov_b32_e32 v65, v0
	v_mov_b32_e32 v66, v0
	v_mov_b32_e32 v67, v0
	v_mov_b32_e32 v68, v0
	v_mov_b32_e32 v69, v0
	v_mov_b32_e32 v70, v0
	v_mov_b32_e32 v71, v0
	v_mov_b32_e32 v80, v0
	v_mov_b32_e32 v81, v0
	v_mov_b32_e32 v82, v0
	v_mov_b32_e32 v83, v0
	v_mov_b32_e32 v84, v0
	v_mov_b32_e32 v85, v0
	v_mov_b32_e32 v86, v0
	v_mov_b32_e32 v87, v0
	v_mov_b32_e32 v96, v0
	v_mov_b32_e32 v97, v0
	v_mov_b32_e32 v98, v0
	v_mov_b32_e32 v99, v0
	v_mov_b32_e32 v100, v0
	v_mov_b32_e32 v101, v0
	v_mov_b32_e32 v102, v0
	v_mov_b32_e32 v103, v0
	v_mov_b32_e32 v112, v0
	v_mov_b32_e32 v113, v0
	v_mov_b32_e32 v114, v0
	v_mov_b32_e32 v115, v0
	v_mov_b32_e32 v116, v0
	v_mov_b32_e32 v117, v0
	v_mov_b32_e32 v118, v0
	v_mov_b32_e32 v119, v0
	v_mov_b32_e32 v72, v0
	v_mov_b32_e32 v73, v0
	v_mov_b32_e32 v74, v0
	v_mov_b32_e32 v75, v0
	v_mov_b32_e32 v76, v0
	v_mov_b32_e32 v77, v0
	v_mov_b32_e32 v78, v0
	v_mov_b32_e32 v79, v0
	v_mov_b32_e32 v88, v0
	v_mov_b32_e32 v89, v0
	v_mov_b32_e32 v90, v0
	v_mov_b32_e32 v91, v0
	v_mov_b32_e32 v92, v0
	v_mov_b32_e32 v93, v0
	v_mov_b32_e32 v94, v0
	v_mov_b32_e32 v95, v0
	v_mov_b32_e32 v104, v0
	v_mov_b32_e32 v105, v0
	v_mov_b32_e32 v106, v0
	v_mov_b32_e32 v107, v0
	v_mov_b32_e32 v108, v0
	v_mov_b32_e32 v109, v0
	v_mov_b32_e32 v110, v0
	v_mov_b32_e32 v111, v0
	v_mov_b32_e32 v120, v0
	v_mov_b32_e32 v121, v0
	v_mov_b32_e32 v122, v0
	v_mov_b32_e32 v123, v0
	v_mov_b32_e32 v124, v0
	v_mov_b32_e32 v125, v0
	v_mov_b32_e32 v126, v0
	v_mov_b32_e32 v127, v0
	.p2alignl 6, 3212836864
	s_nop 0
	s_nop 0
.LBB0_595:
	ds_read_b128 v[154:157], v150
	ds_read_b128 v[158:161], v150 offset:1024
	ds_read_b128 v[170:173], v150 offset:2048
	ds_read_b128 v[174:177], v150 offset:3072
	ds_read_b128 v[178:181], v151
	ds_read_b128 v[182:185], v151 offset:1024
	ds_read_b128 v[186:189], v151 offset:2048
	ds_read_b128 v[190:193], v151 offset:3072
	s_add_u32 s20, s18, 0xffe9c080
	s_addc_u32 s21, s19, -1
	s_cmpk_eq_i32 s55, 0x54
	s_cselect_b32 s23, s5, s21
	s_cselect_b32 s22, s4, s20
	s_cselect_b32 s21, s17, s54
	s_cselect_b32 s20, s16, s53
	v_lshl_add_u64 v[162:163], s[18:19], 0, v[138:139]
	s_add_i32 m0, s37, 0xc000
	ds_read_b128 v[194:197], v152
	ds_read_b128 v[198:201], v152 offset:1024
	ds_read_b128 v[202:205], v152 offset:2048
	ds_read_b128 v[206:209], v152 offset:3072
	ds_read_b128 v[210:213], v152 offset:4096
	ds_read_b128 v[214:217], v152 offset:5120
	ds_read_b128 v[218:221], v152 offset:6144
	ds_read_b128 v[222:225], v152 offset:7168
	global_load_lds_dwordx4 v[162:163], off
	v_lshl_add_u64 v[162:163], s[18:19], 0, v[140:141]
	s_add_i32 m0, s37, 0xe000
	s_nop 0
	global_load_lds_dwordx4 v[162:163], off
	s_waitcnt vmcnt(8)
	s_waitcnt lgkmcnt(0)
	s_barrier
	s_setprio 1
	s_waitcnt lgkmcnt(0)
	v_mfma_f32_16x16x32_bf16 v[124:127], v[154:157], v[194:197], v[124:127]
	v_mfma_f32_16x16x32_bf16 v[120:123], v[170:173], v[194:197], v[120:123]
	v_mfma_f32_16x16x32_bf16 v[108:111], v[154:157], v[202:205], v[108:111]
	v_mfma_f32_16x16x32_bf16 v[104:107], v[170:173], v[202:205], v[104:107]
	v_mfma_f32_16x16x32_bf16 v[92:95], v[154:157], v[210:213], v[92:95]
	v_mfma_f32_16x16x32_bf16 v[88:91], v[170:173], v[210:213], v[88:91]
	v_mfma_f32_16x16x32_bf16 v[76:79], v[154:157], v[218:221], v[76:79]
	v_mfma_f32_16x16x32_bf16 v[72:75], v[170:173], v[218:221], v[72:75]
	v_mfma_f32_16x16x32_bf16 v[124:127], v[158:161], v[198:201], v[124:127]
	v_mfma_f32_16x16x32_bf16 v[120:123], v[174:177], v[198:201], v[120:123]
	v_mfma_f32_16x16x32_bf16 v[108:111], v[158:161], v[206:209], v[108:111]
	v_mfma_f32_16x16x32_bf16 v[104:107], v[174:177], v[206:209], v[104:107]
	v_mfma_f32_16x16x32_bf16 v[92:95], v[158:161], v[214:217], v[92:95]
	v_mfma_f32_16x16x32_bf16 v[88:91], v[174:177], v[214:217], v[88:91]
	v_mfma_f32_16x16x32_bf16 v[76:79], v[158:161], v[222:225], v[76:79]
	v_mfma_f32_16x16x32_bf16 v[72:75], v[174:177], v[222:225], v[72:75]
	s_setprio 0
	s_setprio 1
	v_mfma_f32_16x16x32_bf16 v[116:119], v[178:181], v[194:197], v[116:119]
	v_mfma_f32_16x16x32_bf16 v[112:115], v[186:189], v[194:197], v[112:115]
	v_mfma_f32_16x16x32_bf16 v[100:103], v[178:181], v[202:205], v[100:103]
	v_mfma_f32_16x16x32_bf16 v[96:99], v[186:189], v[202:205], v[96:99]
	v_mfma_f32_16x16x32_bf16 v[84:87], v[178:181], v[210:213], v[84:87]
	v_mfma_f32_16x16x32_bf16 v[80:83], v[186:189], v[210:213], v[80:83]
	v_mfma_f32_16x16x32_bf16 v[68:71], v[178:181], v[218:221], v[68:71]
	v_mfma_f32_16x16x32_bf16 v[64:67], v[186:189], v[218:221], v[64:67]
	v_mfma_f32_16x16x32_bf16 v[116:119], v[182:185], v[198:201], v[116:119]
	v_mfma_f32_16x16x32_bf16 v[112:115], v[190:193], v[198:201], v[112:115]
	v_mfma_f32_16x16x32_bf16 v[100:103], v[182:185], v[206:209], v[100:103]
	v_mfma_f32_16x16x32_bf16 v[96:99], v[190:193], v[206:209], v[96:99]
	v_mfma_f32_16x16x32_bf16 v[84:87], v[182:185], v[214:217], v[84:87]
	v_mfma_f32_16x16x32_bf16 v[80:83], v[190:193], v[214:217], v[80:83]
	v_mfma_f32_16x16x32_bf16 v[68:71], v[182:185], v[222:225], v[68:71]
	v_mfma_f32_16x16x32_bf16 v[64:67], v[190:193], v[222:225], v[64:67]
	s_setprio 0
	s_barrier
; #define PG8_STAGE(bufoff, gbase, voff) do { _Pragma("unroll") for (int _i = 0; _i < 2; ++_i) \
;         __builtin_amdgcn_global_load_lds((const unsigned*)((const char*)(gbase) + (voff)[_i]), (LAS unsigned*)(lds + (bufoff) + ldsw + _i * 8192), 16, 0, 0); } while (0)
; #define PG8_LDA(dst, b, h) do { _Pragma("unroll") for (int m = 0; m < 4; ++m) _Pragma("unroll") for (int k = 0; k < 2; ++k) dst[m][k] = *(const LAS bf16x8*)(lds + PG8_SA(b, h) + aoff + m * 2048 + k * 1024); } while (0)
; #define PG8_LDB(dst, b, h) do { _Pragma("unroll") for (int n = 0; n < 2; ++n) _Pragma("unroll") for (int k = 0; k < 2; ++k) dst[n][k] = *(const LAS bf16x8*)(lds + PG8_SB(b, h) + boff + n * 2048 + k * 1024); } while (0)
; #define PG8_MMA(ai, bj, At, Bt) do { __builtin_amdgcn_s_setprio(1); _Pragma("unroll") for (int m = 0; m < 4; ++m) _Pragma("unroll") for (int n = 0; n < 2; ++n) _Pragma("unroll") for (int k = 0; k < 2; ++k) \
;         acc[ai][bj][m][n] = __builtin_amdgcn_mfma_f32_16x16x32_bf16(Bt[n][k], At[m][k], acc[ai][bj][m][n], 0, 0, 0); __builtin_amdgcn_s_setprio(0); } while (0)
; #define PG8_WAIT_V(n) asm volatile("s_waitcnt vmcnt(" #n ")" ::: "memory")
; #define PG8_WAIT_L(n) asm volatile("s_waitcnt lgkmcnt(" #n ")" ::: "memory")
; #define PG8_BAR __builtin_amdgcn_s_barrier()
; #define PG8_SCHED __builtin_amdgcn_sched_barrier(0)
; template <class EpiT>
; __device__ __forceinline__ void gemm_phase(LAS unsigned char* lds, const Gemm g, const StaticOrder& S, const EpiT& E) {
;     ...
;             PG8_LDA(At, 0, 1); PG8_STAGE(PG8_SB(0, 0), b2, voffB); PG8_STAGE(PG8_SB(0, 1), b2 + hstepB, voffB); PG8_STAGE(PG8_SA(0, 0), a2, voffA);
;             PG8_WAIT_V(8); PG8_WAIT_L(0); PG8_BAR; PG8_MMA(1, 0, At, B0); PG8_MMA(1, 1, At, B1); PG8_BAR; PG8_SCHED;
;             PG8_LDB(B0, 1, 0); PG8_LDB(B1, 1, 1); PG8_SCHED; PG8_LDA(At, 1, 0); PG8_STAGE(PG8_SA(0, 1), a2 + hstepA, voffA);
;             PG8_WAIT_V(8); PG8_WAIT_L(0); PG8_BAR; PG8_MMA(0, 0, At, B0); PG8_MMA(0, 1, At, B1); PG8_BAR; PG8_SCHED;
	s_add_i32 s56, s46, s36
	v_lshl_add_u64 v[162:163], s[20:21], 0, v[130:131]
	s_mov_b32 m0, s56
	ds_read_b128 v[194:197], v152 offset:16384
	ds_read_b128 v[198:201], v152 offset:17408
	ds_read_b128 v[202:205], v152 offset:18432
	ds_read_b128 v[206:209], v152 offset:19456
	ds_read_b128 v[210:213], v152 offset:20480
	ds_read_b128 v[214:217], v152 offset:21504
	ds_read_b128 v[218:221], v152 offset:22528
	ds_read_b128 v[222:225], v152 offset:23552
	global_load_lds_dwordx4 v[162:163], off
	s_add_i32 m0, s56, 0x2000
	s_add_u32 s56, s20, 0x164000
	v_lshl_add_u64 v[166:167], s[20:21], 0, v[134:135]
	s_addc_u32 s57, s21, 0
	s_add_i32 s58, s47, s36
	global_load_lds_dwordx4 v[166:167], off
	v_lshl_add_u64 v[226:227], s[56:57], 0, v[130:131]
	s_mov_b32 m0, s58
	v_lshl_add_u64 v[228:229], s[22:23], 0, v[132:133]
	global_load_lds_dwordx4 v[226:227], off
	v_lshl_add_u64 v[226:227], s[56:57], 0, v[134:135]
	s_add_i32 m0, s58, 0x2000
	s_nop 0
	global_load_lds_dwordx4 v[226:227], off
	v_lshl_add_u64 v[226:227], s[22:23], 0, v[128:129]
	s_mov_b32 m0, s37
	s_nop 0
	global_load_lds_dwordx4 v[226:227], off
	s_mov_b32 m0, s38
	s_nop 0
	global_load_lds_dwordx4 v[228:229], off
	s_waitcnt vmcnt(8)
	s_waitcnt lgkmcnt(0)
	s_barrier
	s_setprio 1
	s_waitcnt lgkmcnt(0)
	v_mfma_f32_16x16x32_bf16 v[60:63], v[154:157], v[194:197], v[60:63]
	v_mfma_f32_16x16x32_bf16 v[56:59], v[170:173], v[194:197], v[56:59]
	v_mfma_f32_16x16x32_bf16 v[44:47], v[154:157], v[202:205], v[44:47]
	v_mfma_f32_16x16x32_bf16 v[40:43], v[170:173], v[202:205], v[40:43]
	v_mfma_f32_16x16x32_bf16 v[28:31], v[154:157], v[210:213], v[28:31]
	v_mfma_f32_16x16x32_bf16 v[24:27], v[170:173], v[210:213], v[24:27]
	v_mfma_f32_16x16x32_bf16 v[12:15], v[154:157], v[218:221], v[12:15]
	v_mfma_f32_16x16x32_bf16 v[8:11], v[170:173], v[218:221], v[8:11]
	v_mfma_f32_16x16x32_bf16 v[60:63], v[158:161], v[198:201], v[60:63]
	v_mfma_f32_16x16x32_bf16 v[56:59], v[174:177], v[198:201], v[56:59]
	v_mfma_f32_16x16x32_bf16 v[44:47], v[158:161], v[206:209], v[44:47]
	v_mfma_f32_16x16x32_bf16 v[40:43], v[174:177], v[206:209], v[40:43]
	v_mfma_f32_16x16x32_bf16 v[28:31], v[158:161], v[214:217], v[28:31]
	v_mfma_f32_16x16x32_bf16 v[24:27], v[174:177], v[214:217], v[24:27]
	v_mfma_f32_16x16x32_bf16 v[12:15], v[158:161], v[222:225], v[12:15]
	v_mfma_f32_16x16x32_bf16 v[8:11], v[174:177], v[222:225], v[8:11]
	s_setprio 0
	s_setprio 1
	v_mfma_f32_16x16x32_bf16 v[52:55], v[178:181], v[194:197], v[52:55]
	v_mfma_f32_16x16x32_bf16 v[48:51], v[186:189], v[194:197], v[48:51]
	v_mfma_f32_16x16x32_bf16 v[36:39], v[178:181], v[202:205], v[36:39]
	v_mfma_f32_16x16x32_bf16 v[32:35], v[186:189], v[202:205], v[32:35]
	v_mfma_f32_16x16x32_bf16 v[20:23], v[178:181], v[210:213], v[20:23]
	v_mfma_f32_16x16x32_bf16 v[16:19], v[186:189], v[210:213], v[16:19]
	v_mfma_f32_16x16x32_bf16 v[4:7], v[178:181], v[218:221], v[4:7]
	v_mfma_f32_16x16x32_bf16 v[0:3], v[186:189], v[218:221], v[0:3]
	v_mfma_f32_16x16x32_bf16 v[52:55], v[182:185], v[198:201], v[52:55]
	v_mfma_f32_16x16x32_bf16 v[48:51], v[190:193], v[198:201], v[48:51]
	v_mfma_f32_16x16x32_bf16 v[36:39], v[182:185], v[206:209], v[36:39]
	v_mfma_f32_16x16x32_bf16 v[32:35], v[190:193], v[206:209], v[32:35]
	v_mfma_f32_16x16x32_bf16 v[20:23], v[182:185], v[214:217], v[20:23]
	v_mfma_f32_16x16x32_bf16 v[16:19], v[190:193], v[214:217], v[16:19]
	v_mfma_f32_16x16x32_bf16 v[4:7], v[182:185], v[222:225], v[4:7]
	v_mfma_f32_16x16x32_bf16 v[0:3], v[190:193], v[222:225], v[0:3]
	s_setprio 0
	s_barrier
	s_add_i32 s56, 0, 0x18000
	v_add_u32_e32 v165, s56, v146
	s_add_i32 s57, 0, 0x1c000
	ds_read_b128 v[154:157], v165
	ds_read_b128 v[158:161], v165 offset:1024
	ds_read_b128 v[170:173], v165 offset:2048
	ds_read_b128 v[174:177], v165 offset:3072
	v_add_u32_e32 v165, s57, v146
	ds_read_b128 v[178:181], v165
	ds_read_b128 v[182:185], v165 offset:1024
	ds_read_b128 v[186:189], v165 offset:2048
	ds_read_b128 v[190:193], v165 offset:3072
	s_add_u32 s22, s22, 0x164000
	s_addc_u32 s23, s23, 0
	s_mov_b32 m0, s39
	v_lshl_add_u64 v[230:231], s[22:23], 0, v[128:129]
	ds_read_b128 v[194:197], v152 offset:32768
	ds_read_b128 v[198:201], v152 offset:33792
	ds_read_b128 v[202:205], v152 offset:34816
	ds_read_b128 v[206:209], v152 offset:35840
	ds_read_b128 v[210:213], v152 offset:36864
	ds_read_b128 v[214:217], v152 offset:37888
	ds_read_b128 v[218:221], v152 offset:38912
	ds_read_b128 v[222:225], v152 offset:39936
	global_load_lds_dwordx4 v[230:231], off
	v_lshl_add_u64 v[230:231], s[22:23], 0, v[132:133]
	s_mov_b32 m0, s40
	s_nop 0
	global_load_lds_dwordx4 v[230:231], off
	s_waitcnt vmcnt(8)
	s_waitcnt lgkmcnt(0)
	s_barrier
; #define PG8_STAGE(bufoff, gbase, voff) do { _Pragma("unroll") for (int _i = 0; _i < 2; ++_i) \
;         __builtin_amdgcn_global_load_lds((const unsigned*)((const char*)(gbase) + (voff)[_i]), (LAS unsigned*)(lds + (bufoff) + ldsw + _i * 8192), 16, 0, 0); } while (0)
; #define PG8_LDA(dst, b, h) do { _Pragma("unroll") for (int m = 0; m < 4; ++m) _Pragma("unroll") for (int k = 0; k < 2; ++k) dst[m][k] = *(const LAS bf16x8*)(lds + PG8_SA(b, h) + aoff + m * 2048 + k * 1024); } while (0)
; #define PG8_MMA(ai, bj, At, Bt) do { __builtin_amdgcn_s_setprio(1); _Pragma("unroll") for (int m = 0; m < 4; ++m) _Pragma("unroll") for (int n = 0; n < 2; ++n) _Pragma("unroll") for (int k = 0; k < 2; ++k) \
;         acc[ai][bj][m][n] = __builtin_amdgcn_mfma_f32_16x16x32_bf16(Bt[n][k], At[m][k], acc[ai][bj][m][n], 0, 0, 0); __builtin_amdgcn_s_setprio(0); } while (0)
; #define PG8_WAIT_V(n) asm volatile("s_waitcnt vmcnt(" #n ")" ::: "memory")
; #define PG8_WAIT_L(n) asm volatile("s_waitcnt lgkmcnt(" #n ")" ::: "memory")
; #define PG8_BAR __builtin_amdgcn_s_barrier()
; #define PG8_SCHED __builtin_amdgcn_sched_barrier(0)
; template <class EpiT>
; __device__ __forceinline__ void gemm_phase(LAS unsigned char* lds, const Gemm g, const StaticOrder& S, const EpiT& E) {
;     ...
;             PG8_WAIT_V(8); PG8_WAIT_L(0); PG8_BAR; PG8_MMA(0, 0, At, B0); PG8_MMA(0, 1, At, B1); PG8_BAR; PG8_SCHED;
;             PG8_LDA(At, 1, 1); PG8_STAGE(PG8_SB(1, 0), b3, voffB); PG8_STAGE(PG8_SB(1, 1), b3 + hstepB, voffB); PG8_STAGE(PG8_SA(1, 0), a3, voffA);
;             PG8_WAIT_V(8); PG8_WAIT_L(0); PG8_BAR; PG8_MMA(1, 0, At, B0); PG8_MMA(1, 1, At, B1); PG8_BAR; PG8_SCHED;
;         }
;         if (wr == 0) PG8_BAR;
	s_setprio 1
	s_waitcnt lgkmcnt(0)
	v_mfma_f32_16x16x32_bf16 v[124:127], v[154:157], v[194:197], v[124:127]
	v_mfma_f32_16x16x32_bf16 v[120:123], v[170:173], v[194:197], v[120:123]
	v_mfma_f32_16x16x32_bf16 v[108:111], v[154:157], v[202:205], v[108:111]
	v_mfma_f32_16x16x32_bf16 v[104:107], v[170:173], v[202:205], v[104:107]
	v_mfma_f32_16x16x32_bf16 v[92:95], v[154:157], v[210:213], v[92:95]
	v_mfma_f32_16x16x32_bf16 v[88:91], v[170:173], v[210:213], v[88:91]
	v_mfma_f32_16x16x32_bf16 v[76:79], v[154:157], v[218:221], v[76:79]
	v_mfma_f32_16x16x32_bf16 v[72:75], v[170:173], v[218:221], v[72:75]
	v_mfma_f32_16x16x32_bf16 v[124:127], v[158:161], v[198:201], v[124:127]
	v_mfma_f32_16x16x32_bf16 v[120:123], v[174:177], v[198:201], v[120:123]
	v_mfma_f32_16x16x32_bf16 v[108:111], v[158:161], v[206:209], v[108:111]
	v_mfma_f32_16x16x32_bf16 v[104:107], v[174:177], v[206:209], v[104:107]
	v_mfma_f32_16x16x32_bf16 v[92:95], v[158:161], v[214:217], v[92:95]
	v_mfma_f32_16x16x32_bf16 v[88:91], v[174:177], v[214:217], v[88:91]
	v_mfma_f32_16x16x32_bf16 v[76:79], v[158:161], v[222:225], v[76:79]
	v_mfma_f32_16x16x32_bf16 v[72:75], v[174:177], v[222:225], v[72:75]
	s_setprio 0
	s_setprio 1
	v_mfma_f32_16x16x32_bf16 v[116:119], v[178:181], v[194:197], v[116:119]
	v_mfma_f32_16x16x32_bf16 v[112:115], v[186:189], v[194:197], v[112:115]
	v_mfma_f32_16x16x32_bf16 v[100:103], v[178:181], v[202:205], v[100:103]
	v_mfma_f32_16x16x32_bf16 v[96:99], v[186:189], v[202:205], v[96:99]
	v_mfma_f32_16x16x32_bf16 v[84:87], v[178:181], v[210:213], v[84:87]
	v_mfma_f32_16x16x32_bf16 v[80:83], v[186:189], v[210:213], v[80:83]
	v_mfma_f32_16x16x32_bf16 v[68:71], v[178:181], v[218:221], v[68:71]
	v_mfma_f32_16x16x32_bf16 v[64:67], v[186:189], v[218:221], v[64:67]
	v_mfma_f32_16x16x32_bf16 v[116:119], v[182:185], v[198:201], v[116:119]
	v_mfma_f32_16x16x32_bf16 v[112:115], v[190:193], v[198:201], v[112:115]
	v_mfma_f32_16x16x32_bf16 v[100:103], v[182:185], v[206:209], v[100:103]
	v_mfma_f32_16x16x32_bf16 v[96:99], v[190:193], v[206:209], v[96:99]
	v_mfma_f32_16x16x32_bf16 v[84:87], v[182:185], v[214:217], v[84:87]
	v_mfma_f32_16x16x32_bf16 v[80:83], v[190:193], v[214:217], v[80:83]
	v_mfma_f32_16x16x32_bf16 v[68:71], v[182:185], v[222:225], v[68:71]
	v_mfma_f32_16x16x32_bf16 v[64:67], v[190:193], v[222:225], v[64:67]
	s_setprio 0
	s_barrier
	s_add_i32 s22, s56, s36
	v_lshl_add_u64 v[162:163], v[162:163], 0, s[12:13]
	s_mov_b32 m0, s22
	ds_read_b128 v[194:197], v152 offset:49152
	ds_read_b128 v[198:201], v152 offset:50176
	ds_read_b128 v[202:205], v152 offset:51200
	ds_read_b128 v[206:209], v152 offset:52224
	ds_read_b128 v[210:213], v152 offset:53248
	ds_read_b128 v[214:217], v152 offset:54272
	ds_read_b128 v[218:221], v152 offset:55296
	ds_read_b128 v[222:225], v152 offset:56320
	global_load_lds_dwordx4 v[162:163], off
	s_add_i32 m0, s22, 0x2000
	s_add_u32 s20, s20, 0x164080
	v_lshl_add_u64 v[162:163], v[166:167], 0, s[12:13]
	s_addc_u32 s21, s21, 0
	s_add_i32 s22, s57, s36
	global_load_lds_dwordx4 v[162:163], off
	v_lshl_add_u64 v[162:163], s[20:21], 0, v[130:131]
	s_mov_b32 m0, s22
	s_nop 0
	global_load_lds_dwordx4 v[162:163], off
	v_lshl_add_u64 v[162:163], s[20:21], 0, v[134:135]
	s_add_i32 m0, s22, 0x2000
	s_nop 0
	global_load_lds_dwordx4 v[162:163], off
	v_lshl_add_u64 v[162:163], v[226:227], 0, s[12:13]
	s_mov_b32 m0, s42
	s_nop 0
	global_load_lds_dwordx4 v[162:163], off
	v_lshl_add_u64 v[162:163], v[228:229], 0, s[12:13]
	s_mov_b32 m0, s43
	s_nop 0
	global_load_lds_dwordx4 v[162:163], off
	s_waitcnt vmcnt(8)
	s_waitcnt lgkmcnt(0)
	s_barrier
	s_setprio 1
	s_waitcnt lgkmcnt(0)
	v_mfma_f32_16x16x32_bf16 v[60:63], v[154:157], v[194:197], v[60:63]
	v_mfma_f32_16x16x32_bf16 v[56:59], v[170:173], v[194:197], v[56:59]
	v_mfma_f32_16x16x32_bf16 v[44:47], v[154:157], v[202:205], v[44:47]
	v_mfma_f32_16x16x32_bf16 v[40:43], v[170:173], v[202:205], v[40:43]
	v_mfma_f32_16x16x32_bf16 v[28:31], v[154:157], v[210:213], v[28:31]
	v_mfma_f32_16x16x32_bf16 v[24:27], v[170:173], v[210:213], v[24:27]
	v_mfma_f32_16x16x32_bf16 v[12:15], v[154:157], v[218:221], v[12:15]
	v_mfma_f32_16x16x32_bf16 v[8:11], v[170:173], v[218:221], v[8:11]
	v_mfma_f32_16x16x32_bf16 v[60:63], v[158:161], v[198:201], v[60:63]
	v_mfma_f32_16x16x32_bf16 v[56:59], v[174:177], v[198:201], v[56:59]
	v_mfma_f32_16x16x32_bf16 v[44:47], v[158:161], v[206:209], v[44:47]
	v_mfma_f32_16x16x32_bf16 v[40:43], v[174:177], v[206:209], v[40:43]
	v_mfma_f32_16x16x32_bf16 v[28:31], v[158:161], v[214:217], v[28:31]
	v_mfma_f32_16x16x32_bf16 v[24:27], v[174:177], v[214:217], v[24:27]
	v_mfma_f32_16x16x32_bf16 v[12:15], v[158:161], v[222:225], v[12:15]
	v_mfma_f32_16x16x32_bf16 v[8:11], v[174:177], v[222:225], v[8:11]
	s_setprio 0
	s_setprio 1
	v_mfma_f32_16x16x32_bf16 v[52:55], v[178:181], v[194:197], v[52:55]
	v_mfma_f32_16x16x32_bf16 v[48:51], v[186:189], v[194:197], v[48:51]
	v_mfma_f32_16x16x32_bf16 v[36:39], v[178:181], v[202:205], v[36:39]
	v_mfma_f32_16x16x32_bf16 v[32:35], v[186:189], v[202:205], v[32:35]
	v_mfma_f32_16x16x32_bf16 v[20:23], v[178:181], v[210:213], v[20:23]
	v_mfma_f32_16x16x32_bf16 v[16:19], v[186:189], v[210:213], v[16:19]
	v_mfma_f32_16x16x32_bf16 v[4:7], v[178:181], v[218:221], v[4:7]
	v_mfma_f32_16x16x32_bf16 v[0:3], v[186:189], v[218:221], v[0:3]
	v_mfma_f32_16x16x32_bf16 v[52:55], v[182:185], v[198:201], v[52:55]
	v_mfma_f32_16x16x32_bf16 v[48:51], v[190:193], v[198:201], v[48:51]
	v_mfma_f32_16x16x32_bf16 v[36:39], v[182:185], v[206:209], v[36:39]
	v_mfma_f32_16x16x32_bf16 v[32:35], v[190:193], v[206:209], v[32:35]
	v_mfma_f32_16x16x32_bf16 v[20:23], v[182:185], v[214:217], v[20:23]
	v_mfma_f32_16x16x32_bf16 v[16:19], v[190:193], v[214:217], v[16:19]
	v_mfma_f32_16x16x32_bf16 v[4:7], v[182:185], v[222:225], v[4:7]
	v_mfma_f32_16x16x32_bf16 v[0:3], v[190:193], v[222:225], v[0:3]
	s_setprio 0
	s_barrier
	s_add_i32 s55, s55, 2
	s_add_u32 s18, s18, 0x100
	s_addc_u32 s19, s19, 0
	s_add_u32 s53, s53, 0x100
	s_addc_u32 s54, s54, 0
	s_cmpk_gt_u32 s55, 0x55
	s_cbranch_scc0 .LBB0_595
	s_and_b64 vcc, exec, s[14:15]
	s_cbranch_vccz .LBB0_598
	s_barrier

; #define PG8_STAGE(bufoff, gbase, voff) do { _Pragma("unroll") for (int _i = 0; _i < 2; ++_i) \
;         __builtin_amdgcn_global_load_lds((const unsigned*)((const char*)(gbase) + (voff)[_i]), (LAS unsigned*)(lds + (bufoff) + ldsw + _i * 8192), 16, 0, 0); } while (0)
; #define PG8_LDA(dst, b, h) do { _Pragma("unroll") for (int m = 0; m < 4; ++m) _Pragma("unroll") for (int k = 0; k < 2; ++k) dst[m][k] = *(const LAS bf16x8*)(lds + PG8_SA(b, h) + aoff + m * 2048 + k * 1024); } while (0)
; #define PG8_LDB(dst, b, h) do { _Pragma("unroll") for (int n = 0; n < 2; ++n) _Pragma("unroll") for (int k = 0; k < 2; ++k) dst[n][k] = *(const LAS bf16x8*)(lds + PG8_SB(b, h) + boff + n * 2048 + k * 1024); } while (0)
; #define PG8_MMA(ai, bj, At, Bt) do { __builtin_amdgcn_s_setprio(1); _Pragma("unroll") for (int m = 0; m < 4; ++m) _Pragma("unroll") for (int n = 0; n < 2; ++n) _Pragma("unroll") for (int k = 0; k < 2; ++k) \
;         acc[ai][bj][m][n] = __builtin_amdgcn_mfma_f32_16x16x32_bf16(Bt[n][k], At[m][k], acc[ai][bj][m][n], 0, 0, 0); __builtin_amdgcn_s_setprio(0); } while (0)
; #define PG8_WAIT_V(n) asm volatile("s_waitcnt vmcnt(" #n ")" ::: "memory")
; #define PG8_WAIT_L(n) asm volatile("s_waitcnt lgkmcnt(" #n ")" ::: "memory")
; #define PG8_BAR __builtin_amdgcn_s_barrier()
; template <class EpiT>
; __device__ __forceinline__ void gemm_phase(LAS unsigned char* lds, const Gemm g, const StaticOrder& S, const EpiT& E) {
;     ...
;         for (int t = 0; t < nt; t += 2) {
;             const bool last = (t == nt - 2);
;             const char* a1 = cA + (size_t)(t + 1) * kstep;
;             const char* a2 = last ? nA : cA + (size_t)(t + 2) * kstep; const char* b2 = last ? nB : cB + (size_t)(t + 2) * kstep;
;             const char* a3 = a2 + kstep; const char* b3 = b2 + kstep;
;             PG8_LDB(B0, 0, 0); PG8_LDB(B1, 0, 1); PG8_SCHED; PG8_LDA(At, 0, 0); PG8_STAGE(PG8_SA(1, 1), a1 + hstepA, voffA);
;             PG8_WAIT_V(8); PG8_WAIT_L(0); PG8_BAR; PG8_MMA(0, 0, At, B0); PG8_MMA(0, 1, At, B1); PG8_BAR; PG8_SCHED;
;     ...
; #pragma unroll
;         for (int a = 0; a < 2; ++a)
; #pragma unroll
;             for (int b = 0; b < 2; ++b)
; #pragma unroll
;                 for (int m = 0; m < 4; ++m)
; #pragma unroll
;                     for (int n = 0; n < 2; ++n) acc[a][b][m][n] = (f32x4){0.f, 0.f, 0.f, 0.f};
;         cur = nxt; cA = nA; cB = nB; ++ui;
.LBB0_760:
	s_add_u32 s20, s20, 0x84080
	s_addc_u32 s21, s21, 0
	s_add_u32 s8, s22, 0x100
	v_mov_b32_e32 v0, 0
	s_addc_u32 s39, s23, 0
	s_mov_b32 s56, -2
	s_waitcnt lgkmcnt(0)
	v_mov_b32_e32 v1, v0
	v_mov_b32_e32 v2, v0
	v_mov_b32_e32 v3, v0
	v_mov_b32_e32 v4, v0
	v_mov_b32_e32 v5, v0
	v_mov_b32_e32 v6, v0
	v_mov_b32_e32 v7, v0
	v_mov_b32_e32 v16, v0
	v_mov_b32_e32 v17, v0
	v_mov_b32_e32 v18, v0
	v_mov_b32_e32 v19, v0
	v_mov_b32_e32 v20, v0
	v_mov_b32_e32 v21, v0
	v_mov_b32_e32 v22, v0
	v_mov_b32_e32 v23, v0
	v_mov_b32_e32 v32, v0
	v_mov_b32_e32 v33, v0
	v_mov_b32_e32 v34, v0
	v_mov_b32_e32 v35, v0
	v_mov_b32_e32 v36, v0
	v_mov_b32_e32 v37, v0
	v_mov_b32_e32 v38, v0
	v_mov_b32_e32 v39, v0
	v_mov_b32_e32 v48, v0
	v_mov_b32_e32 v49, v0
	v_mov_b32_e32 v50, v0
	v_mov_b32_e32 v51, v0
	v_mov_b32_e32 v52, v0
	v_mov_b32_e32 v53, v0
	v_mov_b32_e32 v54, v0
	v_mov_b32_e32 v55, v0
	v_mov_b32_e32 v8, v0
	v_mov_b32_e32 v9, v0
	v_mov_b32_e32 v10, v0
	v_mov_b32_e32 v11, v0
	v_mov_b32_e32 v12, v0
	v_mov_b32_e32 v13, v0
	v_mov_b32_e32 v14, v0
	v_mov_b32_e32 v15, v0
	v_mov_b32_e32 v24, v0
	v_mov_b32_e32 v25, v0
	v_mov_b32_e32 v26, v0
	v_mov_b32_e32 v27, v0
	v_mov_b32_e32 v28, v0
	v_mov_b32_e32 v29, v0
	v_mov_b32_e32 v30, v0
	v_mov_b32_e32 v31, v0
	v_mov_b32_e32 v40, v0
	v_mov_b32_e32 v41, v0
	v_mov_b32_e32 v42, v0
	v_mov_b32_e32 v43, v0
	v_mov_b32_e32 v44, v0
	v_mov_b32_e32 v45, v0
	v_mov_b32_e32 v46, v0
	v_mov_b32_e32 v47, v0
	v_mov_b32_e32 v56, v0
	v_mov_b32_e32 v57, v0
	v_mov_b32_e32 v58, v0
	v_mov_b32_e32 v59, v0
	v_mov_b32_e32 v60, v0
	v_mov_b32_e32 v61, v0
	v_mov_b32_e32 v62, v0
	v_mov_b32_e32 v63, v0
	v_mov_b32_e32 v64, v0
	v_mov_b32_e32 v65, v0
	v_mov_b32_e32 v66, v0
	v_mov_b32_e32 v67, v0
	v_mov_b32_e32 v68, v0
	v_mov_b32_e32 v69, v0
	v_mov_b32_e32 v70, v0
	v_mov_b32_e32 v71, v0
	v_mov_b32_e32 v80, v0
	v_mov_b32_e32 v81, v0
	v_mov_b32_e32 v82, v0
	v_mov_b32_e32 v83, v0
	v_mov_b32_e32 v84, v0
	v_mov_b32_e32 v85, v0
	v_mov_b32_e32 v86, v0
	v_mov_b32_e32 v87, v0
	v_mov_b32_e32 v96, v0
	v_mov_b32_e32 v97, v0
	v_mov_b32_e32 v98, v0
	v_mov_b32_e32 v99, v0
	v_mov_b32_e32 v100, v0
	v_mov_b32_e32 v101, v0
	v_mov_b32_e32 v102, v0
	v_mov_b32_e32 v103, v0
	v_mov_b32_e32 v112, v0
	v_mov_b32_e32 v113, v0
	v_mov_b32_e32 v114, v0
	v_mov_b32_e32 v115, v0
	v_mov_b32_e32 v116, v0
	v_mov_b32_e32 v117, v0
	v_mov_b32_e32 v118, v0
	v_mov_b32_e32 v119, v0
	v_mov_b32_e32 v72, v0
	v_mov_b32_e32 v73, v0
	v_mov_b32_e32 v74, v0
	v_mov_b32_e32 v75, v0
	v_mov_b32_e32 v76, v0
	v_mov_b32_e32 v77, v0
	v_mov_b32_e32 v78, v0
	v_mov_b32_e32 v79, v0
	v_mov_b32_e32 v88, v0
	v_mov_b32_e32 v89, v0
	v_mov_b32_e32 v90, v0
	v_mov_b32_e32 v91, v0
	v_mov_b32_e32 v92, v0
	v_mov_b32_e32 v93, v0
	v_mov_b32_e32 v94, v0
	v_mov_b32_e32 v95, v0
	v_mov_b32_e32 v104, v0
	v_mov_b32_e32 v105, v0
	v_mov_b32_e32 v106, v0
	v_mov_b32_e32 v107, v0
	v_mov_b32_e32 v108, v0
	v_mov_b32_e32 v109, v0
	v_mov_b32_e32 v110, v0
	v_mov_b32_e32 v111, v0
	v_mov_b32_e32 v120, v0
	v_mov_b32_e32 v121, v0
	v_mov_b32_e32 v122, v0
	v_mov_b32_e32 v123, v0
	v_mov_b32_e32 v124, v0
	v_mov_b32_e32 v125, v0
	v_mov_b32_e32 v126, v0
	v_mov_b32_e32 v127, v0
	.p2alignl 6, 3212836864
.LBB0_761:
	ds_read_b128 v[156:159], v160
	ds_read_b128 v[164:167], v160 offset:1024
	ds_read_b128 v[170:173], v160 offset:2048
	ds_read_b128 v[174:177], v160 offset:3072
	ds_read_b128 v[178:181], v161
	ds_read_b128 v[182:185], v161 offset:1024
	ds_read_b128 v[186:189], v161 offset:2048
	ds_read_b128 v[190:193], v161 offset:3072
	s_add_u32 s22, s20, 0xfff7c080
	s_addc_u32 s23, s21, -1
	s_cmp_eq_u32 s56, 28
	s_cselect_b32 s25, s5, s23
	s_cselect_b32 s24, s4, s22
	s_cselect_b32 s23, s19, s39
	s_cselect_b32 s22, s18, s8
	v_lshl_add_u64 v[226:227], s[20:21], 0, v[146:147]
	s_add_i32 m0, s40, 0xc000
	ds_read_b128 v[194:197], v162
	ds_read_b128 v[198:201], v162 offset:1024
	ds_read_b128 v[202:205], v162 offset:2048
	ds_read_b128 v[206:209], v162 offset:3072
	ds_read_b128 v[210:213], v162 offset:4096
	ds_read_b128 v[214:217], v162 offset:5120
	ds_read_b128 v[218:221], v162 offset:6144
	ds_read_b128 v[222:225], v162 offset:7168
	global_load_lds_dwordx4 v[226:227], off
	v_lshl_add_u64 v[226:227], s[20:21], 0, v[150:151]
	s_add_i32 m0, s40, 0xe000
	s_nop 0
	global_load_lds_dwordx4 v[226:227], off
	s_waitcnt vmcnt(8)
	s_waitcnt lgkmcnt(0)
	s_barrier
	s_setprio 1
	s_waitcnt lgkmcnt(0)
	v_mfma_f32_16x16x32_bf16 v[124:127], v[156:159], v[194:197], v[124:127]
	v_mfma_f32_16x16x32_bf16 v[120:123], v[170:173], v[194:197], v[120:123]
	v_mfma_f32_16x16x32_bf16 v[108:111], v[156:159], v[202:205], v[108:111]
	v_mfma_f32_16x16x32_bf16 v[104:107], v[170:173], v[202:205], v[104:107]
	v_mfma_f32_16x16x32_bf16 v[92:95], v[156:159], v[210:213], v[92:95]
	v_mfma_f32_16x16x32_bf16 v[88:91], v[170:173], v[210:213], v[88:91]
	v_mfma_f32_16x16x32_bf16 v[76:79], v[156:159], v[218:221], v[76:79]
	v_mfma_f32_16x16x32_bf16 v[72:75], v[170:173], v[218:221], v[72:75]
	v_mfma_f32_16x16x32_bf16 v[124:127], v[164:167], v[198:201], v[124:127]
	v_mfma_f32_16x16x32_bf16 v[120:123], v[174:177], v[198:201], v[120:123]
	v_mfma_f32_16x16x32_bf16 v[108:111], v[164:167], v[206:209], v[108:111]
	v_mfma_f32_16x16x32_bf16 v[104:107], v[174:177], v[206:209], v[104:107]
	v_mfma_f32_16x16x32_bf16 v[92:95], v[164:167], v[214:217], v[92:95]
	v_mfma_f32_16x16x32_bf16 v[88:91], v[174:177], v[214:217], v[88:91]
	v_mfma_f32_16x16x32_bf16 v[76:79], v[164:167], v[222:225], v[76:79]
	v_mfma_f32_16x16x32_bf16 v[72:75], v[174:177], v[222:225], v[72:75]
	s_setprio 0
	s_setprio 1
	v_mfma_f32_16x16x32_bf16 v[116:119], v[178:181], v[194:197], v[116:119]
	v_mfma_f32_16x16x32_bf16 v[112:115], v[186:189], v[194:197], v[112:115]
	v_mfma_f32_16x16x32_bf16 v[100:103], v[178:181], v[202:205], v[100:103]
	v_mfma_f32_16x16x32_bf16 v[96:99], v[186:189], v[202:205], v[96:99]
	v_mfma_f32_16x16x32_bf16 v[84:87], v[178:181], v[210:213], v[84:87]
	v_mfma_f32_16x16x32_bf16 v[80:83], v[186:189], v[210:213], v[80:83]
	v_mfma_f32_16x16x32_bf16 v[68:71], v[178:181], v[218:221], v[68:71]
	v_mfma_f32_16x16x32_bf16 v[64:67], v[186:189], v[218:221], v[64:67]
	v_mfma_f32_16x16x32_bf16 v[116:119], v[182:185], v[198:201], v[116:119]
	v_mfma_f32_16x16x32_bf16 v[112:115], v[190:193], v[198:201], v[112:115]
	v_mfma_f32_16x16x32_bf16 v[100:103], v[182:185], v[206:209], v[100:103]
	v_mfma_f32_16x16x32_bf16 v[96:99], v[190:193], v[206:209], v[96:99]
	v_mfma_f32_16x16x32_bf16 v[84:87], v[182:185], v[214:217], v[84:87]
	v_mfma_f32_16x16x32_bf16 v[80:83], v[190:193], v[214:217], v[80:83]
	v_mfma_f32_16x16x32_bf16 v[68:71], v[182:185], v[222:225], v[68:71]
	v_mfma_f32_16x16x32_bf16 v[64:67], v[190:193], v[222:225], v[64:67]
	s_setprio 0
	s_barrier
; #define PG8_STAGE(bufoff, gbase, voff) do { _Pragma("unroll") for (int _i = 0; _i < 2; ++_i) \
;         __builtin_amdgcn_global_load_lds((const unsigned*)((const char*)(gbase) + (voff)[_i]), (LAS unsigned*)(lds + (bufoff) + ldsw + _i * 8192), 16, 0, 0); } while (0)
; #define PG8_LDA(dst, b, h) do { _Pragma("unroll") for (int m = 0; m < 4; ++m) _Pragma("unroll") for (int k = 0; k < 2; ++k) dst[m][k] = *(const LAS bf16x8*)(lds + PG8_SA(b, h) + aoff + m * 2048 + k * 1024); } while (0)
; #define PG8_LDB(dst, b, h) do { _Pragma("unroll") for (int n = 0; n < 2; ++n) _Pragma("unroll") for (int k = 0; k < 2; ++k) dst[n][k] = *(const LAS bf16x8*)(lds + PG8_SB(b, h) + boff + n * 2048 + k * 1024); } while (0)
; #define PG8_MMA(ai, bj, At, Bt) do { __builtin_amdgcn_s_setprio(1); _Pragma("unroll") for (int m = 0; m < 4; ++m) _Pragma("unroll") for (int n = 0; n < 2; ++n) _Pragma("unroll") for (int k = 0; k < 2; ++k) \
;         acc[ai][bj][m][n] = __builtin_amdgcn_mfma_f32_16x16x32_bf16(Bt[n][k], At[m][k], acc[ai][bj][m][n], 0, 0, 0); __builtin_amdgcn_s_setprio(0); } while (0)
; #define PG8_WAIT_V(n) asm volatile("s_waitcnt vmcnt(" #n ")" ::: "memory")
; #define PG8_WAIT_L(n) asm volatile("s_waitcnt lgkmcnt(" #n ")" ::: "memory")
; #define PG8_BAR __builtin_amdgcn_s_barrier()
; #define PG8_SCHED __builtin_amdgcn_sched_barrier(0)
; template <class EpiT>
; __device__ __forceinline__ void gemm_phase(LAS unsigned char* lds, const Gemm g, const StaticOrder& S, const EpiT& E) {
;     ...
;             PG8_LDA(At, 0, 1); PG8_STAGE(PG8_SB(0, 0), b2, voffB); PG8_STAGE(PG8_SB(0, 1), b2 + hstepB, voffB); PG8_STAGE(PG8_SA(0, 0), a2, voffA);
;             PG8_WAIT_V(8); PG8_WAIT_L(0); PG8_BAR; PG8_MMA(1, 0, At, B0); PG8_MMA(1, 1, At, B1); PG8_BAR; PG8_SCHED;
;             PG8_LDB(B0, 1, 0); PG8_LDB(B1, 1, 1); PG8_SCHED; PG8_LDA(At, 1, 0); PG8_STAGE(PG8_SA(0, 1), a2 + hstepA, voffA);
;             PG8_WAIT_V(8); PG8_WAIT_L(0); PG8_BAR; PG8_MMA(0, 0, At, B0); PG8_MMA(0, 1, At, B1); PG8_BAR; PG8_SCHED;
	s_add_i32 s57, s49, s37
	v_lshl_add_u64 v[226:227], s[22:23], 0, v[130:131]
	s_mov_b32 m0, s57
	ds_read_b128 v[194:197], v162 offset:16384
	ds_read_b128 v[198:201], v162 offset:17408
	ds_read_b128 v[202:205], v162 offset:18432
	ds_read_b128 v[206:209], v162 offset:19456
	ds_read_b128 v[210:213], v162 offset:20480
	ds_read_b128 v[214:217], v162 offset:21504
	ds_read_b128 v[218:221], v162 offset:22528
	ds_read_b128 v[222:225], v162 offset:23552
	global_load_lds_dwordx4 v[226:227], off
	s_add_i32 m0, s57, 0x2000
	s_add_u32 s58, s22, 0x84000
	v_lshl_add_u64 v[228:229], s[22:23], 0, v[134:135]
	s_addc_u32 s59, s23, 0
	s_add_i32 s57, s50, s37
	global_load_lds_dwordx4 v[228:229], off
	v_lshl_add_u64 v[230:231], s[58:59], 0, v[130:131]
	s_mov_b32 m0, s57
	v_lshl_add_u64 v[232:233], s[24:25], 0, v[132:133]
	global_load_lds_dwordx4 v[230:231], off
	v_lshl_add_u64 v[230:231], s[58:59], 0, v[134:135]
	s_add_i32 m0, s57, 0x2000
	s_nop 0
	global_load_lds_dwordx4 v[230:231], off
	v_lshl_add_u64 v[230:231], s[24:25], 0, v[128:129]
	s_mov_b32 m0, s40
	s_nop 0
	global_load_lds_dwordx4 v[230:231], off
	s_mov_b32 m0, s41
	s_nop 0
	global_load_lds_dwordx4 v[232:233], off
	s_waitcnt vmcnt(8)
	s_waitcnt lgkmcnt(0)
	s_barrier
	s_setprio 1
	s_waitcnt lgkmcnt(0)
	v_mfma_f32_16x16x32_bf16 v[60:63], v[156:159], v[194:197], v[60:63]
	v_mfma_f32_16x16x32_bf16 v[56:59], v[170:173], v[194:197], v[56:59]
	v_mfma_f32_16x16x32_bf16 v[44:47], v[156:159], v[202:205], v[44:47]
	v_mfma_f32_16x16x32_bf16 v[40:43], v[170:173], v[202:205], v[40:43]
	v_mfma_f32_16x16x32_bf16 v[28:31], v[156:159], v[210:213], v[28:31]
	v_mfma_f32_16x16x32_bf16 v[24:27], v[170:173], v[210:213], v[24:27]
	v_mfma_f32_16x16x32_bf16 v[12:15], v[156:159], v[218:221], v[12:15]
	v_mfma_f32_16x16x32_bf16 v[8:11], v[170:173], v[218:221], v[8:11]
	v_mfma_f32_16x16x32_bf16 v[60:63], v[164:167], v[198:201], v[60:63]
	v_mfma_f32_16x16x32_bf16 v[56:59], v[174:177], v[198:201], v[56:59]
	v_mfma_f32_16x16x32_bf16 v[44:47], v[164:167], v[206:209], v[44:47]
	v_mfma_f32_16x16x32_bf16 v[40:43], v[174:177], v[206:209], v[40:43]
	v_mfma_f32_16x16x32_bf16 v[28:31], v[164:167], v[214:217], v[28:31]
	v_mfma_f32_16x16x32_bf16 v[24:27], v[174:177], v[214:217], v[24:27]
	v_mfma_f32_16x16x32_bf16 v[12:15], v[164:167], v[222:225], v[12:15]
	v_mfma_f32_16x16x32_bf16 v[8:11], v[174:177], v[222:225], v[8:11]
	s_setprio 0
	s_setprio 1
	v_mfma_f32_16x16x32_bf16 v[52:55], v[178:181], v[194:197], v[52:55]
	v_mfma_f32_16x16x32_bf16 v[48:51], v[186:189], v[194:197], v[48:51]
	v_mfma_f32_16x16x32_bf16 v[36:39], v[178:181], v[202:205], v[36:39]
	v_mfma_f32_16x16x32_bf16 v[32:35], v[186:189], v[202:205], v[32:35]
	v_mfma_f32_16x16x32_bf16 v[20:23], v[178:181], v[210:213], v[20:23]
	v_mfma_f32_16x16x32_bf16 v[16:19], v[186:189], v[210:213], v[16:19]
	v_mfma_f32_16x16x32_bf16 v[4:7], v[178:181], v[218:221], v[4:7]
	v_mfma_f32_16x16x32_bf16 v[0:3], v[186:189], v[218:221], v[0:3]
	v_mfma_f32_16x16x32_bf16 v[52:55], v[182:185], v[198:201], v[52:55]
	v_mfma_f32_16x16x32_bf16 v[48:51], v[190:193], v[198:201], v[48:51]
	v_mfma_f32_16x16x32_bf16 v[36:39], v[182:185], v[206:209], v[36:39]
	v_mfma_f32_16x16x32_bf16 v[32:35], v[190:193], v[206:209], v[32:35]
	v_mfma_f32_16x16x32_bf16 v[20:23], v[182:185], v[214:217], v[20:23]
	v_mfma_f32_16x16x32_bf16 v[16:19], v[190:193], v[214:217], v[16:19]
	v_mfma_f32_16x16x32_bf16 v[4:7], v[182:185], v[222:225], v[4:7]
	v_mfma_f32_16x16x32_bf16 v[0:3], v[190:193], v[222:225], v[0:3]
	s_setprio 0
	s_barrier
	s_add_i32 s57, 0, 0x18000
	v_add_u32_e32 v136, s57, v149
	s_add_i32 s58, 0, 0x1c000
	ds_read_b128 v[156:159], v136
	ds_read_b128 v[164:167], v136 offset:1024
	ds_read_b128 v[170:173], v136 offset:2048
	ds_read_b128 v[174:177], v136 offset:3072
	v_add_u32_e32 v136, s58, v149
	ds_read_b128 v[178:181], v136
	ds_read_b128 v[182:185], v136 offset:1024
	ds_read_b128 v[186:189], v136 offset:2048
	ds_read_b128 v[190:193], v136 offset:3072
	s_add_u32 s24, s24, 0x84000
	s_addc_u32 s25, s25, 0
	s_mov_b32 m0, s42
	v_lshl_add_u64 v[234:235], s[24:25], 0, v[128:129]
	ds_read_b128 v[194:197], v162 offset:32768
	ds_read_b128 v[198:201], v162 offset:33792
	ds_read_b128 v[202:205], v162 offset:34816
	ds_read_b128 v[206:209], v162 offset:35840
	ds_read_b128 v[210:213], v162 offset:36864
	ds_read_b128 v[214:217], v162 offset:37888
	ds_read_b128 v[218:221], v162 offset:38912
	ds_read_b128 v[222:225], v162 offset:39936
	global_load_lds_dwordx4 v[234:235], off
	v_lshl_add_u64 v[234:235], s[24:25], 0, v[132:133]
	s_mov_b32 m0, s43
	s_nop 0
	global_load_lds_dwordx4 v[234:235], off
	s_waitcnt vmcnt(8)
	s_waitcnt lgkmcnt(0)
	s_barrier
; #define PG8_STAGE(bufoff, gbase, voff) do { _Pragma("unroll") for (int _i = 0; _i < 2; ++_i) \
;         __builtin_amdgcn_global_load_lds((const unsigned*)((const char*)(gbase) + (voff)[_i]), (LAS unsigned*)(lds + (bufoff) + ldsw + _i * 8192), 16, 0, 0); } while (0)
; #define PG8_LDA(dst, b, h) do { _Pragma("unroll") for (int m = 0; m < 4; ++m) _Pragma("unroll") for (int k = 0; k < 2; ++k) dst[m][k] = *(const LAS bf16x8*)(lds + PG8_SA(b, h) + aoff + m * 2048 + k * 1024); } while (0)
; #define PG8_MMA(ai, bj, At, Bt) do { __builtin_amdgcn_s_setprio(1); _Pragma("unroll") for (int m = 0; m < 4; ++m) _Pragma("unroll") for (int n = 0; n < 2; ++n) _Pragma("unroll") for (int k = 0; k < 2; ++k) \
;         acc[ai][bj][m][n] = __builtin_amdgcn_mfma_f32_16x16x32_bf16(Bt[n][k], At[m][k], acc[ai][bj][m][n], 0, 0, 0); __builtin_amdgcn_s_setprio(0); } while (0)
; #define PG8_WAIT_V(n) asm volatile("s_waitcnt vmcnt(" #n ")" ::: "memory")
; #define PG8_WAIT_L(n) asm volatile("s_waitcnt lgkmcnt(" #n ")" ::: "memory")
; #define PG8_BAR __builtin_amdgcn_s_barrier()
; #define PG8_SCHED __builtin_amdgcn_sched_barrier(0)
; template <class EpiT>
; __device__ __forceinline__ void gemm_phase(LAS unsigned char* lds, const Gemm g, const StaticOrder& S, const EpiT& E) {
;     ...
;             PG8_WAIT_V(8); PG8_WAIT_L(0); PG8_BAR; PG8_MMA(0, 0, At, B0); PG8_MMA(0, 1, At, B1); PG8_BAR; PG8_SCHED;
;             PG8_LDA(At, 1, 1); PG8_STAGE(PG8_SB(1, 0), b3, voffB); PG8_STAGE(PG8_SB(1, 1), b3 + hstepB, voffB); PG8_STAGE(PG8_SA(1, 0), a3, voffA);
;             PG8_WAIT_V(8); PG8_WAIT_L(0); PG8_BAR; PG8_MMA(1, 0, At, B0); PG8_MMA(1, 1, At, B1); PG8_BAR; PG8_SCHED;
;         }
;         if (wr == 0) PG8_BAR;
	s_setprio 1
	s_waitcnt lgkmcnt(0)
	v_mfma_f32_16x16x32_bf16 v[124:127], v[156:159], v[194:197], v[124:127]
	v_mfma_f32_16x16x32_bf16 v[120:123], v[170:173], v[194:197], v[120:123]
	v_mfma_f32_16x16x32_bf16 v[108:111], v[156:159], v[202:205], v[108:111]
	v_mfma_f32_16x16x32_bf16 v[104:107], v[170:173], v[202:205], v[104:107]
	v_mfma_f32_16x16x32_bf16 v[92:95], v[156:159], v[210:213], v[92:95]
	v_mfma_f32_16x16x32_bf16 v[88:91], v[170:173], v[210:213], v[88:91]
	v_mfma_f32_16x16x32_bf16 v[76:79], v[156:159], v[218:221], v[76:79]
	v_mfma_f32_16x16x32_bf16 v[72:75], v[170:173], v[218:221], v[72:75]
	v_mfma_f32_16x16x32_bf16 v[124:127], v[164:167], v[198:201], v[124:127]
	v_mfma_f32_16x16x32_bf16 v[120:123], v[174:177], v[198:201], v[120:123]
	v_mfma_f32_16x16x32_bf16 v[108:111], v[164:167], v[206:209], v[108:111]
	v_mfma_f32_16x16x32_bf16 v[104:107], v[174:177], v[206:209], v[104:107]
	v_mfma_f32_16x16x32_bf16 v[92:95], v[164:167], v[214:217], v[92:95]
	v_mfma_f32_16x16x32_bf16 v[88:91], v[174:177], v[214:217], v[88:91]
	v_mfma_f32_16x16x32_bf16 v[76:79], v[164:167], v[222:225], v[76:79]
	v_mfma_f32_16x16x32_bf16 v[72:75], v[174:177], v[222:225], v[72:75]
	s_setprio 0
	s_setprio 1
	v_mfma_f32_16x16x32_bf16 v[116:119], v[178:181], v[194:197], v[116:119]
	v_mfma_f32_16x16x32_bf16 v[112:115], v[186:189], v[194:197], v[112:115]
	v_mfma_f32_16x16x32_bf16 v[100:103], v[178:181], v[202:205], v[100:103]
	v_mfma_f32_16x16x32_bf16 v[96:99], v[186:189], v[202:205], v[96:99]
	v_mfma_f32_16x16x32_bf16 v[84:87], v[178:181], v[210:213], v[84:87]
	v_mfma_f32_16x16x32_bf16 v[80:83], v[186:189], v[210:213], v[80:83]
	v_mfma_f32_16x16x32_bf16 v[68:71], v[178:181], v[218:221], v[68:71]
	v_mfma_f32_16x16x32_bf16 v[64:67], v[186:189], v[218:221], v[64:67]
	v_mfma_f32_16x16x32_bf16 v[116:119], v[182:185], v[198:201], v[116:119]
	v_mfma_f32_16x16x32_bf16 v[112:115], v[190:193], v[198:201], v[112:115]
	v_mfma_f32_16x16x32_bf16 v[100:103], v[182:185], v[206:209], v[100:103]
	v_mfma_f32_16x16x32_bf16 v[96:99], v[190:193], v[206:209], v[96:99]
	v_mfma_f32_16x16x32_bf16 v[84:87], v[182:185], v[214:217], v[84:87]
	v_mfma_f32_16x16x32_bf16 v[80:83], v[190:193], v[214:217], v[80:83]
	v_mfma_f32_16x16x32_bf16 v[68:71], v[182:185], v[222:225], v[68:71]
	v_mfma_f32_16x16x32_bf16 v[64:67], v[190:193], v[222:225], v[64:67]
	s_setprio 0
	s_barrier
	s_add_i32 s24, s57, s37
	v_lshl_add_u64 v[226:227], v[226:227], 0, s[14:15]
	s_mov_b32 m0, s24
	ds_read_b128 v[194:197], v162 offset:49152
	ds_read_b128 v[198:201], v162 offset:50176
	ds_read_b128 v[202:205], v162 offset:51200
	ds_read_b128 v[206:209], v162 offset:52224
	ds_read_b128 v[210:213], v162 offset:53248
	ds_read_b128 v[214:217], v162 offset:54272
	ds_read_b128 v[218:221], v162 offset:55296
	ds_read_b128 v[222:225], v162 offset:56320
	global_load_lds_dwordx4 v[226:227], off
	s_add_i32 m0, s24, 0x2000
	s_add_u32 s22, s22, 0x84080
	v_lshl_add_u64 v[226:227], v[228:229], 0, s[14:15]
	s_addc_u32 s23, s23, 0
	s_add_i32 s24, s58, s37
	global_load_lds_dwordx4 v[226:227], off
	v_lshl_add_u64 v[226:227], s[22:23], 0, v[130:131]
	s_mov_b32 m0, s24
	s_nop 0
	global_load_lds_dwordx4 v[226:227], off
	v_lshl_add_u64 v[226:227], s[22:23], 0, v[134:135]
	s_add_i32 m0, s24, 0x2000
	s_nop 0
	global_load_lds_dwordx4 v[226:227], off
	v_lshl_add_u64 v[226:227], v[230:231], 0, s[14:15]
	s_mov_b32 m0, s44
	s_nop 0
	global_load_lds_dwordx4 v[226:227], off
	v_lshl_add_u64 v[226:227], v[232:233], 0, s[14:15]
	s_mov_b32 m0, s45
	s_nop 0
	global_load_lds_dwordx4 v[226:227], off
	s_waitcnt vmcnt(8)
	s_waitcnt lgkmcnt(0)
	s_barrier
	s_setprio 1
	s_waitcnt lgkmcnt(0)
	v_mfma_f32_16x16x32_bf16 v[60:63], v[156:159], v[194:197], v[60:63]
	v_mfma_f32_16x16x32_bf16 v[56:59], v[170:173], v[194:197], v[56:59]
	v_mfma_f32_16x16x32_bf16 v[44:47], v[156:159], v[202:205], v[44:47]
	v_mfma_f32_16x16x32_bf16 v[40:43], v[170:173], v[202:205], v[40:43]
	v_mfma_f32_16x16x32_bf16 v[28:31], v[156:159], v[210:213], v[28:31]
	v_mfma_f32_16x16x32_bf16 v[24:27], v[170:173], v[210:213], v[24:27]
	v_mfma_f32_16x16x32_bf16 v[12:15], v[156:159], v[218:221], v[12:15]
	v_mfma_f32_16x16x32_bf16 v[8:11], v[170:173], v[218:221], v[8:11]
	v_mfma_f32_16x16x32_bf16 v[60:63], v[164:167], v[198:201], v[60:63]
	v_mfma_f32_16x16x32_bf16 v[56:59], v[174:177], v[198:201], v[56:59]
	v_mfma_f32_16x16x32_bf16 v[44:47], v[164:167], v[206:209], v[44:47]
	v_mfma_f32_16x16x32_bf16 v[40:43], v[174:177], v[206:209], v[40:43]
	v_mfma_f32_16x16x32_bf16 v[28:31], v[164:167], v[214:217], v[28:31]
	v_mfma_f32_16x16x32_bf16 v[24:27], v[174:177], v[214:217], v[24:27]
	v_mfma_f32_16x16x32_bf16 v[12:15], v[164:167], v[222:225], v[12:15]
	v_mfma_f32_16x16x32_bf16 v[8:11], v[174:177], v[222:225], v[8:11]
	s_setprio 0
	s_setprio 1
	v_mfma_f32_16x16x32_bf16 v[52:55], v[178:181], v[194:197], v[52:55]
	v_mfma_f32_16x16x32_bf16 v[48:51], v[186:189], v[194:197], v[48:51]
	v_mfma_f32_16x16x32_bf16 v[36:39], v[178:181], v[202:205], v[36:39]
	v_mfma_f32_16x16x32_bf16 v[32:35], v[186:189], v[202:205], v[32:35]
	v_mfma_f32_16x16x32_bf16 v[20:23], v[178:181], v[210:213], v[20:23]
	v_mfma_f32_16x16x32_bf16 v[16:19], v[186:189], v[210:213], v[16:19]
	v_mfma_f32_16x16x32_bf16 v[4:7], v[178:181], v[218:221], v[4:7]
	v_mfma_f32_16x16x32_bf16 v[0:3], v[186:189], v[218:221], v[0:3]
	v_mfma_f32_16x16x32_bf16 v[52:55], v[182:185], v[198:201], v[52:55]
	v_mfma_f32_16x16x32_bf16 v[48:51], v[190:193], v[198:201], v[48:51]
	v_mfma_f32_16x16x32_bf16 v[36:39], v[182:185], v[206:209], v[36:39]
	v_mfma_f32_16x16x32_bf16 v[32:35], v[190:193], v[206:209], v[32:35]
	v_mfma_f32_16x16x32_bf16 v[20:23], v[182:185], v[214:217], v[20:23]
	v_mfma_f32_16x16x32_bf16 v[16:19], v[190:193], v[214:217], v[16:19]
	v_mfma_f32_16x16x32_bf16 v[4:7], v[182:185], v[222:225], v[4:7]
	v_mfma_f32_16x16x32_bf16 v[0:3], v[190:193], v[222:225], v[0:3]
	s_setprio 0
	s_barrier
	s_add_i32 s56, s56, 2
	s_add_u32 s20, s20, 0x100
	s_addc_u32 s21, s21, 0
	s_add_u32 s8, s8, 0x100
	s_addc_u32 s39, s39, 0
	s_cmp_gt_u32 s56, 29
	s_cbranch_scc0 .LBB0_761
	s_and_b64 vcc, exec, s[16:17]
	s_cbranch_vccz .LBB0_764
	s_barrier

; #define LAS __attribute__((address_space(3)))
; template <int MODE> ...
;     ...
;         if constexpr (MODE == SB) { if (it > 0) {
;             const u32x4 d0 = *(const LAS u32x4*)(lds + DONE_OFF + ((it - 1) & 1) * 32), d1 = *(const LAS u32x4*)(lds + DONE_OFF + ((it - 1) & 1) * 32 + 16);
;             if ((d0.x & d0.y & d0.z & d0.w & d1.x & d1.y & d1.z & d1.w) != 0u) break; } }
.LBB0_866:
	v_not_b32_e32 v132, v199
	v_and_b32_e32 v132, 32, v132
	v_add_u32_e32 v132, 0, v132
	v_add_u32_e32 v136, 0x21400, v132
	ds_read_b128 v[132:135], v136
	ds_read_b128 v[136:139], v136 offset:16
	s_waitcnt lgkmcnt(1)
	v_and_b32_e32 v132, v132, v133
	v_and_b32_e32 v132, v132, v134
	v_and_b32_e32 v132, v132, v135
	s_waitcnt lgkmcnt(0)
	v_and_b32_e32 v132, v132, v136
	v_and_b32_e32 v132, v132, v137
	v_and_b32_e32 v132, v132, v138
	v_and_b32_e32 v132, v132, v139
	v_cmp_eq_u32_e64 s[12:13], 0, v132
	.p2alignl 6, 3212836864
	s_nop 0
	s_nop 0
	s_nop 0
	s_nop 0
	s_nop 0
	s_nop 0
	s_nop 0
	s_nop 0
	s_nop 0
	s_nop 0
	s_nop 0
	s_nop 0

; #define LAS __attribute__((address_space(3)))
; #define ATT_LOAD(kp0_) do { _Pragma("unroll") for (int _i = 0; _i < 2; ++_i) { const int _grow = rowbase + ((kp0_) + srow + 32 * _i) * rowstride; \
;         kr[_i] = *(const u32x4*)(Kp + (size_t)_grow * ld + sch * 8); vr[_i] = *(const u32x4*)(Vp + (size_t)_grow * ld + sch * 8); } } while (0)
; template <int MODE> ...
;     ...
;     const int tid = tid_, lane = tid & 63, wid = __builtin_amdgcn_readfirstlane(tid >> 6), c15 = lane & 15, g = lane >> 4;
;     const int qw0 = q0 + 32 * wid;
;     const bool hiw = wid >= 4;
;     bf16x8 qf[2][4];
; #pragma unroll
;     for (int qt = 0; qt < 2; ++qt) { const int qrow = rowbase + (qw0 + 16 * qt + c15) * rowstride;
; #pragma unroll
;         for (int ks = 0; ks < 4; ++ks) qf[qt][ks] = *(const bf16x8*)(Qp + (size_t)qrow * ld + 32 * ks + 8 * g); }
;     f32x4 o[2][8];
; #pragma unroll
;     for (int qt = 0; qt < 2; ++qt)
; #pragma unroll
;         for (int dt = 0; dt < 8; ++dt) o[qt][dt] = (f32x4){0.f, 0.f, 0.f, 0.f};
;     float mrun[2] = {-1e30f, -1e30f}, lrun[2] = {0.f, 0.f}, Rrun[2] = {1.f, 1.f};
;     const int srow = tid >> 4, sch = tid & 15;
;     ...
;     bf16x8 pf[2][2]; bool pend = false; int bcur = 0, bprev = 0;
;     if (!pre) ATT_LOAD(ATT_KP0(0));
; #pragma unroll
;     for (int i = 0; i < 2; ++i) { *(LAS u32x4*)(lds + KOFF + (srow + 32 * i) * ROWB + sch * 16) = kr[i]; *(LAS u32x4*)(lds + VOFF + (srow + 32 * i) * ROWB + sch * 16) = vr[i]; }
;     __syncthreads();
.LBB0_909:
	s_or_b64 exec, exec, s[4:5]
	v_mov_b32_e32 v7, v168
	s_waitcnt lgkmcnt(0)
	s_barrier
	s_mov_b32 s80, 0
	v_readfirstlane_b32 s2, v7
	s_ashr_i32 s4, s2, 6
	s_lshl_b32 s38, s4, 5
	v_and_b32_e32 v24, 15, v7
	s_add_i32 s38, s38, s36
	v_bfe_u32 v25, v7, 4, 2
	v_or_b32_e32 v189, s38, v24
	v_add_u32_e32 v156, s40, v189
	v_lshlrev_b32_e32 v0, 4, v25
	v_lshl_add_u64 v[2:3], s[46:47], 0, v[0:1]
	v_or_b32_e32 v6, 16, v156
	v_mad_i64_i32 v[4:5], s[2:3], v156, s94, v[2:3]
	v_mad_i64_i32 v[2:3], s[2:3], v6, s94, v[2:3]
	global_load_dwordx4 v[112:115], v[4:5], off
	global_load_dwordx4 v[104:107], v[4:5], off offset:64
	global_load_dwordx4 v[92:95], v[4:5], off offset:128
	global_load_dwordx4 v[88:91], v[4:5], off offset:192
	global_load_dwordx4 v[116:119], v[2:3], off
	global_load_dwordx4 v[108:111], v[2:3], off offset:64
	global_load_dwordx4 v[96:99], v[2:3], off offset:128
	global_load_dwordx4 v[84:87], v[2:3], off offset:192
	v_ashrrev_i32_e32 v157, 4, v7
	s_cmp_gt_i32 s4, 3
	v_lshlrev_b32_e32 v2, 4, v24
	v_mul_lo_u32 v3, v157, s95
	s_cselect_b64 s[56:57], -1, 0
	s_cmp_lt_i32 s4, 4
	v_add3_u32 v194, 0, v2, v3
	s_cselect_b64 s[66:67], -1, 0
	s_lshl_b32 s2, s4, 7
	v_mov_b32_e32 v3, v1
	s_add_i32 s2, s2, 0
	v_lshl_add_u64 v[160:161], s[42:43], 0, v[2:3]
	v_lshl_add_u64 v[158:159], s[44:45], 0, v[2:3]
	v_lshlrev_b32_e32 v153, 2, v25
	v_bfe_u32 v2, v7, 2, 2
	s_add_i32 s2, s2, 0x21000
	v_or_b32_e32 v2, v153, v2
	v_lshlrev_b32_e32 v3, 3, v7
	v_mov_b32_e32 v4, v1
	v_mov_b32_e32 v5, v1
	v_lshl_add_u32 v195, v24, 2, s2
	v_and_b32_e32 v166, 24, v3
	v_mul_u32_u24_e32 v193, 0x120, v24
	v_mul_u32_u24_e32 v167, 0x120, v2
	v_mov_b32_e32 v2, v1
	v_mov_b32_e32 v3, v1
	v_mov_b64_e32 v[26:27], v[4:5]
	v_mov_b64_e32 v[30:31], v[4:5]
	v_mov_b64_e32 v[34:35], v[4:5]
	v_mov_b64_e32 v[38:39], v[4:5]
	v_mov_b64_e32 v[42:43], v[4:5]
	v_mov_b64_e32 v[46:47], v[4:5]
	v_mov_b64_e32 v[50:51], v[4:5]
	v_mov_b64_e32 v[54:55], v[4:5]
	v_mov_b64_e32 v[58:59], v[4:5]
	v_mov_b64_e32 v[62:63], v[4:5]
	v_mov_b64_e32 v[66:67], v[4:5]
	v_mov_b64_e32 v[70:71], v[4:5]
	v_mov_b64_e32 v[74:75], v[4:5]
	v_mov_b64_e32 v[78:79], v[4:5]
	v_mov_b64_e32 v[82:83], v[4:5]
	v_add_u32_e32 v165, s40, v157
	s_or_b32 s39, s38, 31
	v_or_b32_e32 v192, 16, v189
	v_add_u32_e32 v191, 14, v189
	v_add_u32_e32 v190, 13, v189
	v_add3_u32 v196, 0, v166, v167
	s_add_i32 s37, s36, 0xc0
	s_mov_b64 s[68:69], 0
	v_mov_b32_e32 v7, 0
	v_mov_b32_e32 v198, 0xf149f2ca
	v_mov_b64_e32 v[24:25], v[2:3]
	v_mov_b64_e32 v[28:29], v[2:3]
	v_mov_b64_e32 v[32:33], v[2:3]
	v_mov_b64_e32 v[36:37], v[2:3]
	v_mov_b64_e32 v[40:41], v[2:3]
	v_mov_b64_e32 v[44:45], v[2:3]
	v_mov_b64_e32 v[48:49], v[2:3]
	v_mov_b64_e32 v[52:53], v[2:3]
	v_mov_b64_e32 v[56:57], v[2:3]
	v_mov_b64_e32 v[60:61], v[2:3]
	v_mov_b64_e32 v[64:65], v[2:3]
	v_mov_b64_e32 v[68:69], v[2:3]
	v_mov_b64_e32 v[72:73], v[2:3]
	v_mov_b64_e32 v[76:77], v[2:3]
	v_mov_b64_e32 v[80:81], v[2:3]
	v_mov_b32_e32 v199, 0xf149f2ca
	v_mov_b32_e32 v164, 0
	s_mov_b32 s2, 0
	s_mov_b32 s3, 0
	ds_write_b128 v194, v[8:11]
	ds_write_b128 v194, v[16:19] offset:18432
	ds_write_b128 v194, v[12:15] offset:9216
	ds_write_b128 v194, v[20:23] offset:27648
	s_waitcnt lgkmcnt(0)
	s_barrier
	.p2alignl 6, 3212836864
	s_nop 0
	s_nop 0
	s_nop 0
	s_nop 0
	s_nop 0
	s_nop 0
	s_nop 0
	s_nop 0
	s_nop 0
	s_nop 0
	s_nop 0
	s_nop 0
	s_nop 0
	s_nop 0

; #define PG8_STAGE(bufoff, gbase, voff) do { _Pragma("unroll") for (int _i = 0; _i < 2; ++_i) \
;         __builtin_amdgcn_global_load_lds((const unsigned*)((const char*)(gbase) + (voff)[_i]), (LAS unsigned*)(lds + (bufoff) + ldsw + _i * 8192), 16, 0, 0); } while (0)
; #define PG8_LDA(dst, b, h) do { _Pragma("unroll") for (int m = 0; m < 4; ++m) _Pragma("unroll") for (int k = 0; k < 2; ++k) dst[m][k] = *(const LAS bf16x8*)(lds + PG8_SA(b, h) + aoff + m * 2048 + k * 1024); } while (0)
; #define PG8_LDB(dst, b, h) do { _Pragma("unroll") for (int n = 0; n < 2; ++n) _Pragma("unroll") for (int k = 0; k < 2; ++k) dst[n][k] = *(const LAS bf16x8*)(lds + PG8_SB(b, h) + boff + n * 2048 + k * 1024); } while (0)
; #define PG8_MMA(ai, bj, At, Bt) do { __builtin_amdgcn_s_setprio(1); _Pragma("unroll") for (int m = 0; m < 4; ++m) _Pragma("unroll") for (int n = 0; n < 2; ++n) _Pragma("unroll") for (int k = 0; k < 2; ++k) \
;         acc[ai][bj][m][n] = __builtin_amdgcn_mfma_f32_16x16x32_bf16(Bt[n][k], At[m][k], acc[ai][bj][m][n], 0, 0, 0); __builtin_amdgcn_s_setprio(0); } while (0)
; #define PG8_WAIT_V(n) asm volatile("s_waitcnt vmcnt(" #n ")" ::: "memory")
; #define PG8_WAIT_L(n) asm volatile("s_waitcnt lgkmcnt(" #n ")" ::: "memory")
; #define PG8_BAR __builtin_amdgcn_s_barrier()
; template <class EpiT>
; __device__ __forceinline__ void gemm_phase(LAS unsigned char* lds, const Gemm g, const StaticOrder& S, const EpiT& E) {
;     ...
;         for (int t = 0; t < nt; t += 2) {
;             const bool last = (t == nt - 2);
;             const char* a1 = cA + (size_t)(t + 1) * kstep;
;             const char* a2 = last ? nA : cA + (size_t)(t + 2) * kstep; const char* b2 = last ? nB : cB + (size_t)(t + 2) * kstep;
;             const char* a3 = a2 + kstep; const char* b3 = b2 + kstep;
;             PG8_LDB(B0, 0, 0); PG8_LDB(B1, 0, 1); PG8_SCHED; PG8_LDA(At, 0, 0); PG8_STAGE(PG8_SA(1, 1), a1 + hstepA, voffA);
;             PG8_WAIT_V(8); PG8_WAIT_L(0); PG8_BAR; PG8_MMA(0, 0, At, B0); PG8_MMA(0, 1, At, B1); PG8_BAR; PG8_SCHED;
;     ...
; #pragma unroll
;         for (int a = 0; a < 2; ++a)
; #pragma unroll
;             for (int b = 0; b < 2; ++b)
; #pragma unroll
;                 for (int m = 0; m < 4; ++m)
; #pragma unroll
;                     for (int n = 0; n < 2; ++n) acc[a][b][m][n] = (f32x4){0.f, 0.f, 0.f, 0.f};
;         cur = nxt; cA = nA; cB = nB; ++ui;
.LBB0_1031:
	s_add_u32 s18, s18, 0x84080
	s_addc_u32 s19, s19, 0
	s_add_u32 s53, s20, 0x100
	v_mov_b32_e32 v0, 0
	s_addc_u32 s54, s21, 0
	s_mov_b32 s55, -2
	v_mov_b32_e32 v1, v0
	v_mov_b32_e32 v2, v0
	v_mov_b32_e32 v3, v0
	v_mov_b32_e32 v4, v0
	v_mov_b32_e32 v5, v0
	v_mov_b32_e32 v6, v0
	v_mov_b32_e32 v7, v0
	v_mov_b32_e32 v16, v0
	v_mov_b32_e32 v17, v0
	v_mov_b32_e32 v18, v0
	v_mov_b32_e32 v19, v0
	v_mov_b32_e32 v20, v0
	v_mov_b32_e32 v21, v0
	v_mov_b32_e32 v22, v0
	v_mov_b32_e32 v23, v0
	v_mov_b32_e32 v32, v0
	v_mov_b32_e32 v33, v0
	v_mov_b32_e32 v34, v0
	v_mov_b32_e32 v35, v0
	v_mov_b32_e32 v36, v0
	v_mov_b32_e32 v37, v0
	v_mov_b32_e32 v38, v0
	v_mov_b32_e32 v39, v0
	v_mov_b32_e32 v48, v0
	v_mov_b32_e32 v49, v0
	v_mov_b32_e32 v50, v0
	v_mov_b32_e32 v51, v0
	v_mov_b32_e32 v52, v0
	v_mov_b32_e32 v53, v0
	v_mov_b32_e32 v54, v0
	v_mov_b32_e32 v55, v0
	v_mov_b32_e32 v8, v0
	v_mov_b32_e32 v9, v0
	v_mov_b32_e32 v10, v0
	v_mov_b32_e32 v11, v0
	v_mov_b32_e32 v12, v0
	v_mov_b32_e32 v13, v0
	v_mov_b32_e32 v14, v0
	v_mov_b32_e32 v15, v0
	v_mov_b32_e32 v24, v0
	v_mov_b32_e32 v25, v0
	v_mov_b32_e32 v26, v0
	v_mov_b32_e32 v27, v0
	v_mov_b32_e32 v28, v0
	v_mov_b32_e32 v29, v0
	v_mov_b32_e32 v30, v0
	v_mov_b32_e32 v31, v0
	v_mov_b32_e32 v40, v0
	v_mov_b32_e32 v41, v0
	v_mov_b32_e32 v42, v0
	v_mov_b32_e32 v43, v0
	v_mov_b32_e32 v44, v0
	v_mov_b32_e32 v45, v0
	v_mov_b32_e32 v46, v0
	v_mov_b32_e32 v47, v0
	v_mov_b32_e32 v56, v0
	v_mov_b32_e32 v57, v0
	v_mov_b32_e32 v58, v0
	v_mov_b32_e32 v59, v0
	v_mov_b32_e32 v60, v0
	v_mov_b32_e32 v61, v0
	v_mov_b32_e32 v62, v0
	v_mov_b32_e32 v63, v0
	v_mov_b32_e32 v64, v0
	v_mov_b32_e32 v65, v0
	v_mov_b32_e32 v66, v0
	v_mov_b32_e32 v67, v0
	v_mov_b32_e32 v68, v0
	v_mov_b32_e32 v69, v0
	v_mov_b32_e32 v70, v0
	v_mov_b32_e32 v71, v0
	v_mov_b32_e32 v80, v0
	v_mov_b32_e32 v81, v0
	v_mov_b32_e32 v82, v0
	v_mov_b32_e32 v83, v0
	v_mov_b32_e32 v84, v0
	v_mov_b32_e32 v85, v0
	v_mov_b32_e32 v86, v0
	v_mov_b32_e32 v87, v0
	v_mov_b32_e32 v96, v0
	v_mov_b32_e32 v97, v0
	v_mov_b32_e32 v98, v0
	v_mov_b32_e32 v99, v0
	v_mov_b32_e32 v100, v0
	v_mov_b32_e32 v101, v0
	v_mov_b32_e32 v102, v0
	v_mov_b32_e32 v103, v0
	v_mov_b32_e32 v112, v0
	v_mov_b32_e32 v113, v0
	v_mov_b32_e32 v114, v0
	v_mov_b32_e32 v115, v0
	v_mov_b32_e32 v116, v0
	v_mov_b32_e32 v117, v0
	v_mov_b32_e32 v118, v0
	v_mov_b32_e32 v119, v0
	v_mov_b32_e32 v72, v0
	v_mov_b32_e32 v73, v0
	v_mov_b32_e32 v74, v0
	v_mov_b32_e32 v75, v0
	v_mov_b32_e32 v76, v0
	v_mov_b32_e32 v77, v0
	v_mov_b32_e32 v78, v0
	v_mov_b32_e32 v79, v0
	v_mov_b32_e32 v88, v0
	v_mov_b32_e32 v89, v0
	v_mov_b32_e32 v90, v0
	v_mov_b32_e32 v91, v0
	v_mov_b32_e32 v92, v0
	v_mov_b32_e32 v93, v0
	v_mov_b32_e32 v94, v0
	v_mov_b32_e32 v95, v0
	v_mov_b32_e32 v104, v0
	v_mov_b32_e32 v105, v0
	v_mov_b32_e32 v106, v0
	v_mov_b32_e32 v107, v0
	v_mov_b32_e32 v108, v0
	v_mov_b32_e32 v109, v0
	v_mov_b32_e32 v110, v0
	v_mov_b32_e32 v111, v0
	v_mov_b32_e32 v120, v0
	v_mov_b32_e32 v121, v0
	v_mov_b32_e32 v122, v0
	v_mov_b32_e32 v123, v0
	v_mov_b32_e32 v124, v0
	v_mov_b32_e32 v125, v0
	v_mov_b32_e32 v126, v0
	v_mov_b32_e32 v127, v0
	.p2alignl 6, 3212836864
	s_nop 0
	s_nop 0
	s_nop 0
	s_nop 0
	s_nop 0
	s_nop 0
	s_nop 0
	s_nop 0
	s_nop 0
	s_nop 0
.LBB0_1032:
	ds_read_b128 v[154:157], v150
	ds_read_b128 v[158:161], v150 offset:1024
	ds_read_b128 v[162:165], v150 offset:2048
	ds_read_b128 v[170:173], v150 offset:3072
	ds_read_b128 v[174:177], v151
	ds_read_b128 v[178:181], v151 offset:1024
	ds_read_b128 v[182:185], v151 offset:2048
	ds_read_b128 v[186:189], v151 offset:3072
	s_add_u32 s20, s18, 0xfff7c080
	s_addc_u32 s21, s19, -1
	s_cmp_eq_u32 s55, 28
	s_cselect_b32 s23, s5, s21
	s_cselect_b32 s22, s4, s20
	s_cselect_b32 s21, s17, s54
	s_cselect_b32 s20, s16, s53
	v_lshl_add_u64 v[166:167], s[18:19], 0, v[138:139]
	s_add_i32 m0, s37, 0xc000
	ds_read_b128 v[190:193], v152
	ds_read_b128 v[194:197], v152 offset:1024
	ds_read_b128 v[198:201], v152 offset:2048
	ds_read_b128 v[202:205], v152 offset:3072
	ds_read_b128 v[206:209], v152 offset:4096
	ds_read_b128 v[210:213], v152 offset:5120
	ds_read_b128 v[214:217], v152 offset:6144
	ds_read_b128 v[218:221], v152 offset:7168
	global_load_lds_dwordx4 v[166:167], off
	v_lshl_add_u64 v[166:167], s[18:19], 0, v[140:141]
	s_add_i32 m0, s37, 0xe000
	s_nop 0
	global_load_lds_dwordx4 v[166:167], off
	s_waitcnt vmcnt(8)
	s_waitcnt lgkmcnt(0)
	s_barrier
	s_setprio 1
	s_waitcnt lgkmcnt(0)
	v_mfma_f32_16x16x32_bf16 v[124:127], v[154:157], v[190:193], v[124:127]
	v_mfma_f32_16x16x32_bf16 v[120:123], v[162:165], v[190:193], v[120:123]
	v_mfma_f32_16x16x32_bf16 v[108:111], v[154:157], v[198:201], v[108:111]
	v_mfma_f32_16x16x32_bf16 v[104:107], v[162:165], v[198:201], v[104:107]
	v_mfma_f32_16x16x32_bf16 v[92:95], v[154:157], v[206:209], v[92:95]
	v_mfma_f32_16x16x32_bf16 v[88:91], v[162:165], v[206:209], v[88:91]
	v_mfma_f32_16x16x32_bf16 v[76:79], v[154:157], v[214:217], v[76:79]
	v_mfma_f32_16x16x32_bf16 v[72:75], v[162:165], v[214:217], v[72:75]
	v_mfma_f32_16x16x32_bf16 v[124:127], v[158:161], v[194:197], v[124:127]
	v_mfma_f32_16x16x32_bf16 v[120:123], v[170:173], v[194:197], v[120:123]
	v_mfma_f32_16x16x32_bf16 v[108:111], v[158:161], v[202:205], v[108:111]
	v_mfma_f32_16x16x32_bf16 v[104:107], v[170:173], v[202:205], v[104:107]
	v_mfma_f32_16x16x32_bf16 v[92:95], v[158:161], v[210:213], v[92:95]
	v_mfma_f32_16x16x32_bf16 v[88:91], v[170:173], v[210:213], v[88:91]
	v_mfma_f32_16x16x32_bf16 v[76:79], v[158:161], v[218:221], v[76:79]
	v_mfma_f32_16x16x32_bf16 v[72:75], v[170:173], v[218:221], v[72:75]
	s_setprio 0
	s_setprio 1
	v_mfma_f32_16x16x32_bf16 v[116:119], v[174:177], v[190:193], v[116:119]
	v_mfma_f32_16x16x32_bf16 v[112:115], v[182:185], v[190:193], v[112:115]
	v_mfma_f32_16x16x32_bf16 v[100:103], v[174:177], v[198:201], v[100:103]
	v_mfma_f32_16x16x32_bf16 v[96:99], v[182:185], v[198:201], v[96:99]
	v_mfma_f32_16x16x32_bf16 v[84:87], v[174:177], v[206:209], v[84:87]
	v_mfma_f32_16x16x32_bf16 v[80:83], v[182:185], v[206:209], v[80:83]
	v_mfma_f32_16x16x32_bf16 v[68:71], v[174:177], v[214:217], v[68:71]
	v_mfma_f32_16x16x32_bf16 v[64:67], v[182:185], v[214:217], v[64:67]
	v_mfma_f32_16x16x32_bf16 v[116:119], v[178:181], v[194:197], v[116:119]
	v_mfma_f32_16x16x32_bf16 v[112:115], v[186:189], v[194:197], v[112:115]
	v_mfma_f32_16x16x32_bf16 v[100:103], v[178:181], v[202:205], v[100:103]
	v_mfma_f32_16x16x32_bf16 v[96:99], v[186:189], v[202:205], v[96:99]
	v_mfma_f32_16x16x32_bf16 v[84:87], v[178:181], v[210:213], v[84:87]
	v_mfma_f32_16x16x32_bf16 v[80:83], v[186:189], v[210:213], v[80:83]
	v_mfma_f32_16x16x32_bf16 v[68:71], v[178:181], v[218:221], v[68:71]
	v_mfma_f32_16x16x32_bf16 v[64:67], v[186:189], v[218:221], v[64:67]
	s_setprio 0
	s_barrier
; #define PG8_STAGE(bufoff, gbase, voff) do { _Pragma("unroll") for (int _i = 0; _i < 2; ++_i) \
;         __builtin_amdgcn_global_load_lds((const unsigned*)((const char*)(gbase) + (voff)[_i]), (LAS unsigned*)(lds + (bufoff) + ldsw + _i * 8192), 16, 0, 0); } while (0)
; #define PG8_LDA(dst, b, h) do { _Pragma("unroll") for (int m = 0; m < 4; ++m) _Pragma("unroll") for (int k = 0; k < 2; ++k) dst[m][k] = *(const LAS bf16x8*)(lds + PG8_SA(b, h) + aoff + m * 2048 + k * 1024); } while (0)
; #define PG8_LDB(dst, b, h) do { _Pragma("unroll") for (int n = 0; n < 2; ++n) _Pragma("unroll") for (int k = 0; k < 2; ++k) dst[n][k] = *(const LAS bf16x8*)(lds + PG8_SB(b, h) + boff + n * 2048 + k * 1024); } while (0)
; #define PG8_MMA(ai, bj, At, Bt) do { __builtin_amdgcn_s_setprio(1); _Pragma("unroll") for (int m = 0; m < 4; ++m) _Pragma("unroll") for (int n = 0; n < 2; ++n) _Pragma("unroll") for (int k = 0; k < 2; ++k) \
;         acc[ai][bj][m][n] = __builtin_amdgcn_mfma_f32_16x16x32_bf16(Bt[n][k], At[m][k], acc[ai][bj][m][n], 0, 0, 0); __builtin_amdgcn_s_setprio(0); } while (0)
; #define PG8_WAIT_V(n) asm volatile("s_waitcnt vmcnt(" #n ")" ::: "memory")
; #define PG8_WAIT_L(n) asm volatile("s_waitcnt lgkmcnt(" #n ")" ::: "memory")
; #define PG8_BAR __builtin_amdgcn_s_barrier()
; #define PG8_SCHED __builtin_amdgcn_sched_barrier(0)
; template <class EpiT>
; __device__ __forceinline__ void gemm_phase(LAS unsigned char* lds, const Gemm g, const StaticOrder& S, const EpiT& E) {
;     ...
;             PG8_LDA(At, 0, 1); PG8_STAGE(PG8_SB(0, 0), b2, voffB); PG8_STAGE(PG8_SB(0, 1), b2 + hstepB, voffB); PG8_STAGE(PG8_SA(0, 0), a2, voffA);
;             PG8_WAIT_V(8); PG8_WAIT_L(0); PG8_BAR; PG8_MMA(1, 0, At, B0); PG8_MMA(1, 1, At, B1); PG8_BAR; PG8_SCHED;
;             PG8_LDB(B0, 1, 0); PG8_LDB(B1, 1, 1); PG8_SCHED; PG8_LDA(At, 1, 0); PG8_STAGE(PG8_SA(0, 1), a2 + hstepA, voffA);
;             PG8_WAIT_V(8); PG8_WAIT_L(0); PG8_BAR; PG8_MMA(0, 0, At, B0); PG8_MMA(0, 1, At, B1); PG8_BAR; PG8_SCHED;
	s_add_i32 s56, s46, s36
	v_lshl_add_u64 v[166:167], s[20:21], 0, v[130:131]
	s_mov_b32 m0, s56
	ds_read_b128 v[190:193], v152 offset:16384
	ds_read_b128 v[194:197], v152 offset:17408
	ds_read_b128 v[198:201], v152 offset:18432
	ds_read_b128 v[202:205], v152 offset:19456
	ds_read_b128 v[206:209], v152 offset:20480
	ds_read_b128 v[210:213], v152 offset:21504
	ds_read_b128 v[214:217], v152 offset:22528
	ds_read_b128 v[218:221], v152 offset:23552
	global_load_lds_dwordx4 v[166:167], off
	s_add_i32 m0, s56, 0x2000
	s_add_u32 s56, s20, 0x84000
	v_lshl_add_u64 v[222:223], s[20:21], 0, v[134:135]
	s_addc_u32 s57, s21, 0
	s_add_i32 s58, s47, s36
	global_load_lds_dwordx4 v[222:223], off
	v_lshl_add_u64 v[224:225], s[56:57], 0, v[130:131]
	s_mov_b32 m0, s58
	v_lshl_add_u64 v[226:227], s[22:23], 0, v[132:133]
	global_load_lds_dwordx4 v[224:225], off
	v_lshl_add_u64 v[224:225], s[56:57], 0, v[134:135]
	s_add_i32 m0, s58, 0x2000
	s_nop 0
	global_load_lds_dwordx4 v[224:225], off
	v_lshl_add_u64 v[224:225], s[22:23], 0, v[128:129]
	s_mov_b32 m0, s37
	s_nop 0
	global_load_lds_dwordx4 v[224:225], off
	s_mov_b32 m0, s38
	s_nop 0
	global_load_lds_dwordx4 v[226:227], off
	s_waitcnt vmcnt(8)
	s_waitcnt lgkmcnt(0)
	s_barrier
	s_setprio 1
	s_waitcnt lgkmcnt(0)
	v_mfma_f32_16x16x32_bf16 v[60:63], v[154:157], v[190:193], v[60:63]
	v_mfma_f32_16x16x32_bf16 v[56:59], v[162:165], v[190:193], v[56:59]
	v_mfma_f32_16x16x32_bf16 v[44:47], v[154:157], v[198:201], v[44:47]
	v_mfma_f32_16x16x32_bf16 v[40:43], v[162:165], v[198:201], v[40:43]
	v_mfma_f32_16x16x32_bf16 v[28:31], v[154:157], v[206:209], v[28:31]
	v_mfma_f32_16x16x32_bf16 v[24:27], v[162:165], v[206:209], v[24:27]
	v_mfma_f32_16x16x32_bf16 v[12:15], v[154:157], v[214:217], v[12:15]
	v_mfma_f32_16x16x32_bf16 v[8:11], v[162:165], v[214:217], v[8:11]
	v_mfma_f32_16x16x32_bf16 v[60:63], v[158:161], v[194:197], v[60:63]
	v_mfma_f32_16x16x32_bf16 v[56:59], v[170:173], v[194:197], v[56:59]
	v_mfma_f32_16x16x32_bf16 v[44:47], v[158:161], v[202:205], v[44:47]
	v_mfma_f32_16x16x32_bf16 v[40:43], v[170:173], v[202:205], v[40:43]
	v_mfma_f32_16x16x32_bf16 v[28:31], v[158:161], v[210:213], v[28:31]
	v_mfma_f32_16x16x32_bf16 v[24:27], v[170:173], v[210:213], v[24:27]
	v_mfma_f32_16x16x32_bf16 v[12:15], v[158:161], v[218:221], v[12:15]
	v_mfma_f32_16x16x32_bf16 v[8:11], v[170:173], v[218:221], v[8:11]
	s_setprio 0
	s_setprio 1
	v_mfma_f32_16x16x32_bf16 v[52:55], v[174:177], v[190:193], v[52:55]
	v_mfma_f32_16x16x32_bf16 v[48:51], v[182:185], v[190:193], v[48:51]
	v_mfma_f32_16x16x32_bf16 v[36:39], v[174:177], v[198:201], v[36:39]
	v_mfma_f32_16x16x32_bf16 v[32:35], v[182:185], v[198:201], v[32:35]
	v_mfma_f32_16x16x32_bf16 v[20:23], v[174:177], v[206:209], v[20:23]
	v_mfma_f32_16x16x32_bf16 v[16:19], v[182:185], v[206:209], v[16:19]
	v_mfma_f32_16x16x32_bf16 v[4:7], v[174:177], v[214:217], v[4:7]
	v_mfma_f32_16x16x32_bf16 v[0:3], v[182:185], v[214:217], v[0:3]
	v_mfma_f32_16x16x32_bf16 v[52:55], v[178:181], v[194:197], v[52:55]
	v_mfma_f32_16x16x32_bf16 v[48:51], v[186:189], v[194:197], v[48:51]
	v_mfma_f32_16x16x32_bf16 v[36:39], v[178:181], v[202:205], v[36:39]
	v_mfma_f32_16x16x32_bf16 v[32:35], v[186:189], v[202:205], v[32:35]
	v_mfma_f32_16x16x32_bf16 v[20:23], v[178:181], v[210:213], v[20:23]
	v_mfma_f32_16x16x32_bf16 v[16:19], v[186:189], v[210:213], v[16:19]
	v_mfma_f32_16x16x32_bf16 v[4:7], v[178:181], v[218:221], v[4:7]
	v_mfma_f32_16x16x32_bf16 v[0:3], v[186:189], v[218:221], v[0:3]
	s_setprio 0
	s_barrier
	s_add_i32 s56, 0, 0x18000
	s_add_i32 s57, 0, 0x1c000
	v_add_u32_e32 v170, s56, v146
	v_add_u32_e32 v186, s57, v146
	ds_read_b128 v[154:157], v170
	ds_read_b128 v[158:161], v170 offset:1024
	ds_read_b128 v[162:165], v170 offset:2048
	ds_read_b128 v[170:173], v170 offset:3072
	ds_read_b128 v[174:177], v186
	ds_read_b128 v[178:181], v186 offset:1024
	ds_read_b128 v[182:185], v186 offset:2048
	ds_read_b128 v[186:189], v186 offset:3072
	s_add_u32 s22, s22, 0x84000
	s_addc_u32 s23, s23, 0
	s_mov_b32 m0, s39
	v_lshl_add_u64 v[228:229], s[22:23], 0, v[128:129]
	ds_read_b128 v[190:193], v152 offset:32768
	ds_read_b128 v[194:197], v152 offset:33792
	ds_read_b128 v[198:201], v152 offset:34816
	ds_read_b128 v[202:205], v152 offset:35840
	ds_read_b128 v[206:209], v152 offset:36864
	ds_read_b128 v[210:213], v152 offset:37888
	ds_read_b128 v[214:217], v152 offset:38912
	ds_read_b128 v[218:221], v152 offset:39936
	global_load_lds_dwordx4 v[228:229], off
	v_lshl_add_u64 v[228:229], s[22:23], 0, v[132:133]
	s_mov_b32 m0, s40
	s_nop 0
	global_load_lds_dwordx4 v[228:229], off
	s_waitcnt vmcnt(8)
	s_waitcnt lgkmcnt(0)
	s_barrier
; #define PG8_STAGE(bufoff, gbase, voff) do { _Pragma("unroll") for (int _i = 0; _i < 2; ++_i) \
;         __builtin_amdgcn_global_load_lds((const unsigned*)((const char*)(gbase) + (voff)[_i]), (LAS unsigned*)(lds + (bufoff) + ldsw + _i * 8192), 16, 0, 0); } while (0)
; #define PG8_LDA(dst, b, h) do { _Pragma("unroll") for (int m = 0; m < 4; ++m) _Pragma("unroll") for (int k = 0; k < 2; ++k) dst[m][k] = *(const LAS bf16x8*)(lds + PG8_SA(b, h) + aoff + m * 2048 + k * 1024); } while (0)
; #define PG8_MMA(ai, bj, At, Bt) do { __builtin_amdgcn_s_setprio(1); _Pragma("unroll") for (int m = 0; m < 4; ++m) _Pragma("unroll") for (int n = 0; n < 2; ++n) _Pragma("unroll") for (int k = 0; k < 2; ++k) \
;         acc[ai][bj][m][n] = __builtin_amdgcn_mfma_f32_16x16x32_bf16(Bt[n][k], At[m][k], acc[ai][bj][m][n], 0, 0, 0); __builtin_amdgcn_s_setprio(0); } while (0)
; #define PG8_WAIT_V(n) asm volatile("s_waitcnt vmcnt(" #n ")" ::: "memory")
; #define PG8_WAIT_L(n) asm volatile("s_waitcnt lgkmcnt(" #n ")" ::: "memory")
; #define PG8_BAR __builtin_amdgcn_s_barrier()
; #define PG8_SCHED __builtin_amdgcn_sched_barrier(0)
; template <class EpiT>
; __device__ __forceinline__ void gemm_phase(LAS unsigned char* lds, const Gemm g, const StaticOrder& S, const EpiT& E) {
;     ...
;             PG8_WAIT_V(8); PG8_WAIT_L(0); PG8_BAR; PG8_MMA(0, 0, At, B0); PG8_MMA(0, 1, At, B1); PG8_BAR; PG8_SCHED;
;             PG8_LDA(At, 1, 1); PG8_STAGE(PG8_SB(1, 0), b3, voffB); PG8_STAGE(PG8_SB(1, 1), b3 + hstepB, voffB); PG8_STAGE(PG8_SA(1, 0), a3, voffA);
;             PG8_WAIT_V(8); PG8_WAIT_L(0); PG8_BAR; PG8_MMA(1, 0, At, B0); PG8_MMA(1, 1, At, B1); PG8_BAR; PG8_SCHED;
;         }
;         if (wr == 0) PG8_BAR;
	s_setprio 1
	s_waitcnt lgkmcnt(0)
	v_mfma_f32_16x16x32_bf16 v[124:127], v[154:157], v[190:193], v[124:127]
	v_mfma_f32_16x16x32_bf16 v[120:123], v[162:165], v[190:193], v[120:123]
	v_mfma_f32_16x16x32_bf16 v[108:111], v[154:157], v[198:201], v[108:111]
	v_mfma_f32_16x16x32_bf16 v[104:107], v[162:165], v[198:201], v[104:107]
	v_mfma_f32_16x16x32_bf16 v[92:95], v[154:157], v[206:209], v[92:95]
	v_mfma_f32_16x16x32_bf16 v[88:91], v[162:165], v[206:209], v[88:91]
	v_mfma_f32_16x16x32_bf16 v[76:79], v[154:157], v[214:217], v[76:79]
	v_mfma_f32_16x16x32_bf16 v[72:75], v[162:165], v[214:217], v[72:75]
	v_mfma_f32_16x16x32_bf16 v[124:127], v[158:161], v[194:197], v[124:127]
	v_mfma_f32_16x16x32_bf16 v[120:123], v[170:173], v[194:197], v[120:123]
	v_mfma_f32_16x16x32_bf16 v[108:111], v[158:161], v[202:205], v[108:111]
	v_mfma_f32_16x16x32_bf16 v[104:107], v[170:173], v[202:205], v[104:107]
	v_mfma_f32_16x16x32_bf16 v[92:95], v[158:161], v[210:213], v[92:95]
	v_mfma_f32_16x16x32_bf16 v[88:91], v[170:173], v[210:213], v[88:91]
	v_mfma_f32_16x16x32_bf16 v[76:79], v[158:161], v[218:221], v[76:79]
	v_mfma_f32_16x16x32_bf16 v[72:75], v[170:173], v[218:221], v[72:75]
	s_setprio 0
	s_setprio 1
	v_mfma_f32_16x16x32_bf16 v[116:119], v[174:177], v[190:193], v[116:119]
	v_mfma_f32_16x16x32_bf16 v[112:115], v[182:185], v[190:193], v[112:115]
	v_mfma_f32_16x16x32_bf16 v[100:103], v[174:177], v[198:201], v[100:103]
	v_mfma_f32_16x16x32_bf16 v[96:99], v[182:185], v[198:201], v[96:99]
	v_mfma_f32_16x16x32_bf16 v[84:87], v[174:177], v[206:209], v[84:87]
	v_mfma_f32_16x16x32_bf16 v[80:83], v[182:185], v[206:209], v[80:83]
	v_mfma_f32_16x16x32_bf16 v[68:71], v[174:177], v[214:217], v[68:71]
	v_mfma_f32_16x16x32_bf16 v[64:67], v[182:185], v[214:217], v[64:67]
	v_mfma_f32_16x16x32_bf16 v[116:119], v[178:181], v[194:197], v[116:119]
	v_mfma_f32_16x16x32_bf16 v[112:115], v[186:189], v[194:197], v[112:115]
	v_mfma_f32_16x16x32_bf16 v[100:103], v[178:181], v[202:205], v[100:103]
	v_mfma_f32_16x16x32_bf16 v[96:99], v[186:189], v[202:205], v[96:99]
	v_mfma_f32_16x16x32_bf16 v[84:87], v[178:181], v[210:213], v[84:87]
	v_mfma_f32_16x16x32_bf16 v[80:83], v[186:189], v[210:213], v[80:83]
	v_mfma_f32_16x16x32_bf16 v[68:71], v[178:181], v[218:221], v[68:71]
	v_mfma_f32_16x16x32_bf16 v[64:67], v[186:189], v[218:221], v[64:67]
	s_setprio 0
	s_barrier
	s_add_i32 s22, s56, s36
	v_lshl_add_u64 v[166:167], v[166:167], 0, s[12:13]
	s_mov_b32 m0, s22
	ds_read_b128 v[190:193], v152 offset:49152
	ds_read_b128 v[194:197], v152 offset:50176
	ds_read_b128 v[198:201], v152 offset:51200
	ds_read_b128 v[202:205], v152 offset:52224
	ds_read_b128 v[206:209], v152 offset:53248
	ds_read_b128 v[210:213], v152 offset:54272
	ds_read_b128 v[214:217], v152 offset:55296
	ds_read_b128 v[218:221], v152 offset:56320
	global_load_lds_dwordx4 v[166:167], off
	s_add_i32 m0, s22, 0x2000
	s_add_u32 s20, s20, 0x84080
	v_lshl_add_u64 v[166:167], v[222:223], 0, s[12:13]
	s_addc_u32 s21, s21, 0
	s_add_i32 s22, s57, s36
	global_load_lds_dwordx4 v[166:167], off
	v_lshl_add_u64 v[166:167], s[20:21], 0, v[130:131]
	s_mov_b32 m0, s22
	s_nop 0
	global_load_lds_dwordx4 v[166:167], off
	v_lshl_add_u64 v[166:167], s[20:21], 0, v[134:135]
	s_add_i32 m0, s22, 0x2000
	s_nop 0
	global_load_lds_dwordx4 v[166:167], off
	v_lshl_add_u64 v[166:167], v[224:225], 0, s[12:13]
	s_mov_b32 m0, s42
	s_nop 0
	global_load_lds_dwordx4 v[166:167], off
	v_lshl_add_u64 v[166:167], v[226:227], 0, s[12:13]
	s_mov_b32 m0, s43
	s_nop 0
	global_load_lds_dwordx4 v[166:167], off
	s_waitcnt vmcnt(8)
	s_waitcnt lgkmcnt(0)
	s_barrier
	s_setprio 1
	s_waitcnt lgkmcnt(0)
	v_mfma_f32_16x16x32_bf16 v[60:63], v[154:157], v[190:193], v[60:63]
	v_mfma_f32_16x16x32_bf16 v[56:59], v[162:165], v[190:193], v[56:59]
	v_mfma_f32_16x16x32_bf16 v[44:47], v[154:157], v[198:201], v[44:47]
	v_mfma_f32_16x16x32_bf16 v[40:43], v[162:165], v[198:201], v[40:43]
	v_mfma_f32_16x16x32_bf16 v[28:31], v[154:157], v[206:209], v[28:31]
	v_mfma_f32_16x16x32_bf16 v[24:27], v[162:165], v[206:209], v[24:27]
	v_mfma_f32_16x16x32_bf16 v[12:15], v[154:157], v[214:217], v[12:15]
	v_mfma_f32_16x16x32_bf16 v[8:11], v[162:165], v[214:217], v[8:11]
	v_mfma_f32_16x16x32_bf16 v[60:63], v[158:161], v[194:197], v[60:63]
	v_mfma_f32_16x16x32_bf16 v[56:59], v[170:173], v[194:197], v[56:59]
	v_mfma_f32_16x16x32_bf16 v[44:47], v[158:161], v[202:205], v[44:47]
	v_mfma_f32_16x16x32_bf16 v[40:43], v[170:173], v[202:205], v[40:43]
	v_mfma_f32_16x16x32_bf16 v[28:31], v[158:161], v[210:213], v[28:31]
	v_mfma_f32_16x16x32_bf16 v[24:27], v[170:173], v[210:213], v[24:27]
	v_mfma_f32_16x16x32_bf16 v[12:15], v[158:161], v[218:221], v[12:15]
	v_mfma_f32_16x16x32_bf16 v[8:11], v[170:173], v[218:221], v[8:11]
	s_setprio 0
	s_setprio 1
	v_mfma_f32_16x16x32_bf16 v[52:55], v[174:177], v[190:193], v[52:55]
	v_mfma_f32_16x16x32_bf16 v[48:51], v[182:185], v[190:193], v[48:51]
	v_mfma_f32_16x16x32_bf16 v[36:39], v[174:177], v[198:201], v[36:39]
	v_mfma_f32_16x16x32_bf16 v[32:35], v[182:185], v[198:201], v[32:35]
	v_mfma_f32_16x16x32_bf16 v[20:23], v[174:177], v[206:209], v[20:23]
	v_mfma_f32_16x16x32_bf16 v[16:19], v[182:185], v[206:209], v[16:19]
	v_mfma_f32_16x16x32_bf16 v[4:7], v[174:177], v[214:217], v[4:7]
	v_mfma_f32_16x16x32_bf16 v[0:3], v[182:185], v[214:217], v[0:3]
	v_mfma_f32_16x16x32_bf16 v[52:55], v[178:181], v[194:197], v[52:55]
	v_mfma_f32_16x16x32_bf16 v[48:51], v[186:189], v[194:197], v[48:51]
	v_mfma_f32_16x16x32_bf16 v[36:39], v[178:181], v[202:205], v[36:39]
	v_mfma_f32_16x16x32_bf16 v[32:35], v[186:189], v[202:205], v[32:35]
	v_mfma_f32_16x16x32_bf16 v[20:23], v[178:181], v[210:213], v[20:23]
	v_mfma_f32_16x16x32_bf16 v[16:19], v[186:189], v[210:213], v[16:19]
	v_mfma_f32_16x16x32_bf16 v[4:7], v[178:181], v[218:221], v[4:7]
	v_mfma_f32_16x16x32_bf16 v[0:3], v[186:189], v[218:221], v[0:3]
	s_setprio 0
	s_barrier
	s_add_i32 s55, s55, 2
	s_add_u32 s18, s18, 0x100
	s_addc_u32 s19, s19, 0
	s_add_u32 s53, s53, 0x100
	s_addc_u32 s54, s54, 0
	s_cmp_gt_u32 s55, 29
	s_cbranch_scc0 .LBB0_1032
	s_and_b64 vcc, exec, s[14:15]
	s_cbranch_vccz .LBB0_1035
	s_barrier

; #define PG8_STAGE(bufoff, gbase, voff) do { _Pragma("unroll") for (int _i = 0; _i < 2; ++_i) \
;         __builtin_amdgcn_global_load_lds((const unsigned*)((const char*)(gbase) + (voff)[_i]), (LAS unsigned*)(lds + (bufoff) + ldsw + _i * 8192), 16, 0, 0); } while (0)
; #define PG8_LDA(dst, b, h) do { _Pragma("unroll") for (int m = 0; m < 4; ++m) _Pragma("unroll") for (int k = 0; k < 2; ++k) dst[m][k] = *(const LAS bf16x8*)(lds + PG8_SA(b, h) + aoff + m * 2048 + k * 1024); } while (0)
; #define PG8_LDB(dst, b, h) do { _Pragma("unroll") for (int n = 0; n < 2; ++n) _Pragma("unroll") for (int k = 0; k < 2; ++k) dst[n][k] = *(const LAS bf16x8*)(lds + PG8_SB(b, h) + boff + n * 2048 + k * 1024); } while (0)
; #define PG8_MMA(ai, bj, At, Bt) do { __builtin_amdgcn_s_setprio(1); _Pragma("unroll") for (int m = 0; m < 4; ++m) _Pragma("unroll") for (int n = 0; n < 2; ++n) _Pragma("unroll") for (int k = 0; k < 2; ++k) \
;         acc[ai][bj][m][n] = __builtin_amdgcn_mfma_f32_16x16x32_bf16(Bt[n][k], At[m][k], acc[ai][bj][m][n], 0, 0, 0); __builtin_amdgcn_s_setprio(0); } while (0)
; #define PG8_WAIT_V(n) asm volatile("s_waitcnt vmcnt(" #n ")" ::: "memory")
; #define PG8_WAIT_L(n) asm volatile("s_waitcnt lgkmcnt(" #n ")" ::: "memory")
; #define PG8_BAR __builtin_amdgcn_s_barrier()
; template <class EpiT>
; __device__ __forceinline__ void gemm_phase(LAS unsigned char* lds, const Gemm g, const StaticOrder& S, const EpiT& E) {
;     ...
;         for (int t = 0; t < nt; t += 2) {
;             const bool last = (t == nt - 2);
;             const char* a1 = cA + (size_t)(t + 1) * kstep;
;             const char* a2 = last ? nA : cA + (size_t)(t + 2) * kstep; const char* b2 = last ? nB : cB + (size_t)(t + 2) * kstep;
;             const char* a3 = a2 + kstep; const char* b3 = b2 + kstep;
;             PG8_LDB(B0, 0, 0); PG8_LDB(B1, 0, 1); PG8_SCHED; PG8_LDA(At, 0, 0); PG8_STAGE(PG8_SA(1, 1), a1 + hstepA, voffA);
;             PG8_WAIT_V(8); PG8_WAIT_L(0); PG8_BAR; PG8_MMA(0, 0, At, B0); PG8_MMA(0, 1, At, B1); PG8_BAR; PG8_SCHED;
;     ...
; #pragma unroll
;         for (int a = 0; a < 2; ++a)
; #pragma unroll
;             for (int b = 0; b < 2; ++b)
; #pragma unroll
;                 for (int m = 0; m < 4; ++m)
; #pragma unroll
;                     for (int n = 0; n < 2; ++n) acc[a][b][m][n] = (f32x4){0.f, 0.f, 0.f, 0.f};
;         cur = nxt; cA = nA; cB = nB; ++ui;
.LBB0_1155:
	s_add_u32 s16, s16, 0x84080
	s_addc_u32 s17, s17, 0
	s_add_u32 s51, s18, 0x100
	v_mov_b32_e32 v0, 0
	s_addc_u32 s52, s19, 0
	s_mov_b32 s53, -2
	v_mov_b32_e32 v1, v0
	v_mov_b32_e32 v2, v0
	v_mov_b32_e32 v3, v0
	v_mov_b32_e32 v4, v0
	v_mov_b32_e32 v5, v0
	v_mov_b32_e32 v6, v0
	v_mov_b32_e32 v7, v0
	v_mov_b32_e32 v16, v0
	v_mov_b32_e32 v17, v0
	v_mov_b32_e32 v18, v0
	v_mov_b32_e32 v19, v0
	v_mov_b32_e32 v20, v0
	v_mov_b32_e32 v21, v0
	v_mov_b32_e32 v22, v0
	v_mov_b32_e32 v23, v0
	v_mov_b32_e32 v32, v0
	v_mov_b32_e32 v33, v0
	v_mov_b32_e32 v34, v0
	v_mov_b32_e32 v35, v0
	v_mov_b32_e32 v36, v0
	v_mov_b32_e32 v37, v0
	v_mov_b32_e32 v38, v0
	v_mov_b32_e32 v39, v0
	v_mov_b32_e32 v48, v0
	v_mov_b32_e32 v49, v0
	v_mov_b32_e32 v50, v0
	v_mov_b32_e32 v51, v0
	v_mov_b32_e32 v52, v0
	v_mov_b32_e32 v53, v0
	v_mov_b32_e32 v54, v0
	v_mov_b32_e32 v55, v0
	v_mov_b32_e32 v8, v0
	v_mov_b32_e32 v9, v0
	v_mov_b32_e32 v10, v0
	v_mov_b32_e32 v11, v0
	v_mov_b32_e32 v12, v0
	v_mov_b32_e32 v13, v0
	v_mov_b32_e32 v14, v0
	v_mov_b32_e32 v15, v0
	v_mov_b32_e32 v24, v0
	v_mov_b32_e32 v25, v0
	v_mov_b32_e32 v26, v0
	v_mov_b32_e32 v27, v0
	v_mov_b32_e32 v28, v0
	v_mov_b32_e32 v29, v0
	v_mov_b32_e32 v30, v0
	v_mov_b32_e32 v31, v0
	v_mov_b32_e32 v40, v0
	v_mov_b32_e32 v41, v0
	v_mov_b32_e32 v42, v0
	v_mov_b32_e32 v43, v0
	v_mov_b32_e32 v44, v0
	v_mov_b32_e32 v45, v0
	v_mov_b32_e32 v46, v0
	v_mov_b32_e32 v47, v0
	v_mov_b32_e32 v56, v0
	v_mov_b32_e32 v57, v0
	v_mov_b32_e32 v58, v0
	v_mov_b32_e32 v59, v0
	v_mov_b32_e32 v60, v0
	v_mov_b32_e32 v61, v0
	v_mov_b32_e32 v62, v0
	v_mov_b32_e32 v63, v0
	v_mov_b32_e32 v64, v0
	v_mov_b32_e32 v65, v0
	v_mov_b32_e32 v66, v0
	v_mov_b32_e32 v67, v0
	v_mov_b32_e32 v68, v0
	v_mov_b32_e32 v69, v0
	v_mov_b32_e32 v70, v0
	v_mov_b32_e32 v71, v0
	v_mov_b32_e32 v80, v0
	v_mov_b32_e32 v81, v0
	v_mov_b32_e32 v82, v0
	v_mov_b32_e32 v83, v0
	v_mov_b32_e32 v84, v0
	v_mov_b32_e32 v85, v0
	v_mov_b32_e32 v86, v0
	v_mov_b32_e32 v87, v0
	v_mov_b32_e32 v96, v0
	v_mov_b32_e32 v97, v0
	v_mov_b32_e32 v98, v0
	v_mov_b32_e32 v99, v0
	v_mov_b32_e32 v100, v0
	v_mov_b32_e32 v101, v0
	v_mov_b32_e32 v102, v0
	v_mov_b32_e32 v103, v0
	v_mov_b32_e32 v112, v0
	v_mov_b32_e32 v113, v0
	v_mov_b32_e32 v114, v0
	v_mov_b32_e32 v115, v0
	v_mov_b32_e32 v116, v0
	v_mov_b32_e32 v117, v0
	v_mov_b32_e32 v118, v0
	v_mov_b32_e32 v119, v0
	v_mov_b32_e32 v72, v0
	v_mov_b32_e32 v73, v0
	v_mov_b32_e32 v74, v0
	v_mov_b32_e32 v75, v0
	v_mov_b32_e32 v76, v0
	v_mov_b32_e32 v77, v0
	v_mov_b32_e32 v78, v0
	v_mov_b32_e32 v79, v0
	v_mov_b32_e32 v88, v0
	v_mov_b32_e32 v89, v0
	v_mov_b32_e32 v90, v0
	v_mov_b32_e32 v91, v0
	v_mov_b32_e32 v92, v0
	v_mov_b32_e32 v93, v0
	v_mov_b32_e32 v94, v0
	v_mov_b32_e32 v95, v0
	v_mov_b32_e32 v104, v0
	v_mov_b32_e32 v105, v0
	v_mov_b32_e32 v106, v0
	v_mov_b32_e32 v107, v0
	v_mov_b32_e32 v108, v0
	v_mov_b32_e32 v109, v0
	v_mov_b32_e32 v110, v0
	v_mov_b32_e32 v111, v0
	v_mov_b32_e32 v120, v0
	v_mov_b32_e32 v121, v0
	v_mov_b32_e32 v122, v0
	v_mov_b32_e32 v123, v0
	v_mov_b32_e32 v124, v0
	v_mov_b32_e32 v125, v0
	v_mov_b32_e32 v126, v0
	v_mov_b32_e32 v127, v0
	.p2alignl 6, 3212836864
	s_nop 0
	s_nop 0
	s_nop 0
.LBB0_1156:
	ds_read_b128 v[154:157], v150
	ds_read_b128 v[158:161], v150 offset:1024
	ds_read_b128 v[162:165], v150 offset:2048
	ds_read_b128 v[170:173], v150 offset:3072
	ds_read_b128 v[174:177], v151
	ds_read_b128 v[178:181], v151 offset:1024
	ds_read_b128 v[182:185], v151 offset:2048
	ds_read_b128 v[186:189], v151 offset:3072
	s_add_u32 s18, s16, 0xfff7c080
	s_addc_u32 s19, s17, -1
	s_cmp_eq_u32 s53, 28
	s_cselect_b32 s21, s3, s19
	s_cselect_b32 s20, s2, s18
	s_cselect_b32 s19, s15, s52
	s_cselect_b32 s18, s14, s51
	v_lshl_add_u64 v[144:145], s[16:17], 0, v[136:137]
	s_add_i32 m0, s36, 0xc000
	ds_read_b128 v[190:193], v152
	ds_read_b128 v[194:197], v152 offset:1024
	ds_read_b128 v[198:201], v152 offset:2048
	ds_read_b128 v[202:205], v152 offset:3072
	ds_read_b128 v[206:209], v152 offset:4096
	ds_read_b128 v[210:213], v152 offset:5120
	ds_read_b128 v[214:217], v152 offset:6144
	ds_read_b128 v[218:221], v152 offset:7168
	global_load_lds_dwordx4 v[144:145], off
	v_lshl_add_u64 v[144:145], s[16:17], 0, v[138:139]
	s_add_i32 m0, s36, 0xe000
	s_nop 0
	global_load_lds_dwordx4 v[144:145], off
	s_waitcnt vmcnt(8)
	s_waitcnt lgkmcnt(0)
	s_barrier
	s_setprio 1
	s_waitcnt lgkmcnt(0)
	v_mfma_f32_16x16x32_bf16 v[124:127], v[154:157], v[190:193], v[124:127]
	v_mfma_f32_16x16x32_bf16 v[120:123], v[162:165], v[190:193], v[120:123]
	v_mfma_f32_16x16x32_bf16 v[108:111], v[154:157], v[198:201], v[108:111]
	v_mfma_f32_16x16x32_bf16 v[104:107], v[162:165], v[198:201], v[104:107]
	v_mfma_f32_16x16x32_bf16 v[92:95], v[154:157], v[206:209], v[92:95]
	v_mfma_f32_16x16x32_bf16 v[88:91], v[162:165], v[206:209], v[88:91]
	v_mfma_f32_16x16x32_bf16 v[76:79], v[154:157], v[214:217], v[76:79]
	v_mfma_f32_16x16x32_bf16 v[72:75], v[162:165], v[214:217], v[72:75]
	v_mfma_f32_16x16x32_bf16 v[124:127], v[158:161], v[194:197], v[124:127]
	v_mfma_f32_16x16x32_bf16 v[120:123], v[170:173], v[194:197], v[120:123]
	v_mfma_f32_16x16x32_bf16 v[108:111], v[158:161], v[202:205], v[108:111]
	v_mfma_f32_16x16x32_bf16 v[104:107], v[170:173], v[202:205], v[104:107]
	v_mfma_f32_16x16x32_bf16 v[92:95], v[158:161], v[210:213], v[92:95]
	v_mfma_f32_16x16x32_bf16 v[88:91], v[170:173], v[210:213], v[88:91]
	v_mfma_f32_16x16x32_bf16 v[76:79], v[158:161], v[218:221], v[76:79]
	v_mfma_f32_16x16x32_bf16 v[72:75], v[170:173], v[218:221], v[72:75]
	s_setprio 0
	s_setprio 1
	v_mfma_f32_16x16x32_bf16 v[116:119], v[174:177], v[190:193], v[116:119]
	v_mfma_f32_16x16x32_bf16 v[112:115], v[182:185], v[190:193], v[112:115]
	v_mfma_f32_16x16x32_bf16 v[100:103], v[174:177], v[198:201], v[100:103]
	v_mfma_f32_16x16x32_bf16 v[96:99], v[182:185], v[198:201], v[96:99]
	v_mfma_f32_16x16x32_bf16 v[84:87], v[174:177], v[206:209], v[84:87]
	v_mfma_f32_16x16x32_bf16 v[80:83], v[182:185], v[206:209], v[80:83]
	v_mfma_f32_16x16x32_bf16 v[68:71], v[174:177], v[214:217], v[68:71]
	v_mfma_f32_16x16x32_bf16 v[64:67], v[182:185], v[214:217], v[64:67]
	v_mfma_f32_16x16x32_bf16 v[116:119], v[178:181], v[194:197], v[116:119]
	v_mfma_f32_16x16x32_bf16 v[112:115], v[186:189], v[194:197], v[112:115]
	v_mfma_f32_16x16x32_bf16 v[100:103], v[178:181], v[202:205], v[100:103]
	v_mfma_f32_16x16x32_bf16 v[96:99], v[186:189], v[202:205], v[96:99]
	v_mfma_f32_16x16x32_bf16 v[84:87], v[178:181], v[210:213], v[84:87]
	v_mfma_f32_16x16x32_bf16 v[80:83], v[186:189], v[210:213], v[80:83]
	v_mfma_f32_16x16x32_bf16 v[68:71], v[178:181], v[218:221], v[68:71]
	v_mfma_f32_16x16x32_bf16 v[64:67], v[186:189], v[218:221], v[64:67]
	s_setprio 0
	s_barrier
; #define PG8_STAGE(bufoff, gbase, voff) do { _Pragma("unroll") for (int _i = 0; _i < 2; ++_i) \
;         __builtin_amdgcn_global_load_lds((const unsigned*)((const char*)(gbase) + (voff)[_i]), (LAS unsigned*)(lds + (bufoff) + ldsw + _i * 8192), 16, 0, 0); } while (0)
; #define PG8_LDA(dst, b, h) do { _Pragma("unroll") for (int m = 0; m < 4; ++m) _Pragma("unroll") for (int k = 0; k < 2; ++k) dst[m][k] = *(const LAS bf16x8*)(lds + PG8_SA(b, h) + aoff + m * 2048 + k * 1024); } while (0)
; #define PG8_LDB(dst, b, h) do { _Pragma("unroll") for (int n = 0; n < 2; ++n) _Pragma("unroll") for (int k = 0; k < 2; ++k) dst[n][k] = *(const LAS bf16x8*)(lds + PG8_SB(b, h) + boff + n * 2048 + k * 1024); } while (0)
; #define PG8_MMA(ai, bj, At, Bt) do { __builtin_amdgcn_s_setprio(1); _Pragma("unroll") for (int m = 0; m < 4; ++m) _Pragma("unroll") for (int n = 0; n < 2; ++n) _Pragma("unroll") for (int k = 0; k < 2; ++k) \
;         acc[ai][bj][m][n] = __builtin_amdgcn_mfma_f32_16x16x32_bf16(Bt[n][k], At[m][k], acc[ai][bj][m][n], 0, 0, 0); __builtin_amdgcn_s_setprio(0); } while (0)
; #define PG8_WAIT_V(n) asm volatile("s_waitcnt vmcnt(" #n ")" ::: "memory")
; #define PG8_WAIT_L(n) asm volatile("s_waitcnt lgkmcnt(" #n ")" ::: "memory")
; #define PG8_BAR __builtin_amdgcn_s_barrier()
; #define PG8_SCHED __builtin_amdgcn_sched_barrier(0)
; template <class EpiT>
; __device__ __forceinline__ void gemm_phase(LAS unsigned char* lds, const Gemm g, const StaticOrder& S, const EpiT& E) {
;     ...
;             PG8_LDA(At, 0, 1); PG8_STAGE(PG8_SB(0, 0), b2, voffB); PG8_STAGE(PG8_SB(0, 1), b2 + hstepB, voffB); PG8_STAGE(PG8_SA(0, 0), a2, voffA);
;             PG8_WAIT_V(8); PG8_WAIT_L(0); PG8_BAR; PG8_MMA(1, 0, At, B0); PG8_MMA(1, 1, At, B1); PG8_BAR; PG8_SCHED;
;             PG8_LDB(B0, 1, 0); PG8_LDB(B1, 1, 1); PG8_SCHED; PG8_LDA(At, 1, 0); PG8_STAGE(PG8_SA(0, 1), a2 + hstepA, voffA);
;             PG8_WAIT_V(8); PG8_WAIT_L(0); PG8_BAR; PG8_MMA(0, 0, At, B0); PG8_MMA(0, 1, At, B1); PG8_BAR; PG8_SCHED;
	s_add_i32 s54, s44, s27
	v_lshl_add_u64 v[144:145], s[18:19], 0, v[132:133]
	s_mov_b32 m0, s54
	ds_read_b128 v[190:193], v152 offset:16384
	ds_read_b128 v[194:197], v152 offset:17408
	ds_read_b128 v[198:201], v152 offset:18432
	ds_read_b128 v[202:205], v152 offset:19456
	ds_read_b128 v[206:209], v152 offset:20480
	ds_read_b128 v[210:213], v152 offset:21504
	ds_read_b128 v[214:217], v152 offset:22528
	ds_read_b128 v[218:221], v152 offset:23552
	global_load_lds_dwordx4 v[144:145], off
	s_add_i32 m0, s54, 0x2000
	s_add_u32 s54, s18, 0x84000
	v_lshl_add_u64 v[166:167], s[18:19], 0, v[128:129]
	s_addc_u32 s55, s19, 0
	s_add_i32 s56, s45, s27
	global_load_lds_dwordx4 v[166:167], off
	v_lshl_add_u64 v[222:223], s[54:55], 0, v[132:133]
	s_mov_b32 m0, s56
	v_lshl_add_u64 v[224:225], s[20:21], 0, v[130:131]
	global_load_lds_dwordx4 v[222:223], off
	v_lshl_add_u64 v[222:223], s[54:55], 0, v[128:129]
	s_add_i32 m0, s56, 0x2000
	s_nop 0
	global_load_lds_dwordx4 v[222:223], off
	v_lshl_add_u64 v[222:223], s[20:21], 0, v[134:135]
	s_mov_b32 m0, s36
	s_nop 0
	global_load_lds_dwordx4 v[222:223], off
	s_mov_b32 m0, s37
	s_nop 0
	global_load_lds_dwordx4 v[224:225], off
	s_waitcnt vmcnt(8)
	s_waitcnt lgkmcnt(0)
	s_barrier
	s_setprio 1
	s_waitcnt lgkmcnt(0)
	v_mfma_f32_16x16x32_bf16 v[60:63], v[154:157], v[190:193], v[60:63]
	v_mfma_f32_16x16x32_bf16 v[56:59], v[162:165], v[190:193], v[56:59]
	v_mfma_f32_16x16x32_bf16 v[44:47], v[154:157], v[198:201], v[44:47]
	v_mfma_f32_16x16x32_bf16 v[40:43], v[162:165], v[198:201], v[40:43]
	v_mfma_f32_16x16x32_bf16 v[28:31], v[154:157], v[206:209], v[28:31]
	v_mfma_f32_16x16x32_bf16 v[24:27], v[162:165], v[206:209], v[24:27]
	v_mfma_f32_16x16x32_bf16 v[12:15], v[154:157], v[214:217], v[12:15]
	v_mfma_f32_16x16x32_bf16 v[8:11], v[162:165], v[214:217], v[8:11]
	v_mfma_f32_16x16x32_bf16 v[60:63], v[158:161], v[194:197], v[60:63]
	v_mfma_f32_16x16x32_bf16 v[56:59], v[170:173], v[194:197], v[56:59]
	v_mfma_f32_16x16x32_bf16 v[44:47], v[158:161], v[202:205], v[44:47]
	v_mfma_f32_16x16x32_bf16 v[40:43], v[170:173], v[202:205], v[40:43]
	v_mfma_f32_16x16x32_bf16 v[28:31], v[158:161], v[210:213], v[28:31]
	v_mfma_f32_16x16x32_bf16 v[24:27], v[170:173], v[210:213], v[24:27]
	v_mfma_f32_16x16x32_bf16 v[12:15], v[158:161], v[218:221], v[12:15]
	v_mfma_f32_16x16x32_bf16 v[8:11], v[170:173], v[218:221], v[8:11]
	s_setprio 0
	s_setprio 1
	v_mfma_f32_16x16x32_bf16 v[52:55], v[174:177], v[190:193], v[52:55]
	v_mfma_f32_16x16x32_bf16 v[48:51], v[182:185], v[190:193], v[48:51]
	v_mfma_f32_16x16x32_bf16 v[36:39], v[174:177], v[198:201], v[36:39]
	v_mfma_f32_16x16x32_bf16 v[32:35], v[182:185], v[198:201], v[32:35]
	v_mfma_f32_16x16x32_bf16 v[20:23], v[174:177], v[206:209], v[20:23]
	v_mfma_f32_16x16x32_bf16 v[16:19], v[182:185], v[206:209], v[16:19]
	v_mfma_f32_16x16x32_bf16 v[4:7], v[174:177], v[214:217], v[4:7]
	v_mfma_f32_16x16x32_bf16 v[0:3], v[182:185], v[214:217], v[0:3]
	v_mfma_f32_16x16x32_bf16 v[52:55], v[178:181], v[194:197], v[52:55]
	v_mfma_f32_16x16x32_bf16 v[48:51], v[186:189], v[194:197], v[48:51]
	v_mfma_f32_16x16x32_bf16 v[36:39], v[178:181], v[202:205], v[36:39]
	v_mfma_f32_16x16x32_bf16 v[32:35], v[186:189], v[202:205], v[32:35]
	v_mfma_f32_16x16x32_bf16 v[20:23], v[178:181], v[210:213], v[20:23]
	v_mfma_f32_16x16x32_bf16 v[16:19], v[186:189], v[210:213], v[16:19]
	v_mfma_f32_16x16x32_bf16 v[4:7], v[178:181], v[218:221], v[4:7]
	v_mfma_f32_16x16x32_bf16 v[0:3], v[186:189], v[218:221], v[0:3]
	s_setprio 0
	s_barrier
	s_add_i32 s54, 0, 0x18000
	v_add_u32_e32 v153, s54, v147
	s_add_i32 s55, 0, 0x1c000
	ds_read_b128 v[154:157], v153
	ds_read_b128 v[158:161], v153 offset:1024
	ds_read_b128 v[162:165], v153 offset:2048
	ds_read_b128 v[170:173], v153 offset:3072
	v_add_u32_e32 v153, s55, v147
	ds_read_b128 v[174:177], v153
	ds_read_b128 v[178:181], v153 offset:1024
	ds_read_b128 v[182:185], v153 offset:2048
	ds_read_b128 v[186:189], v153 offset:3072
	s_add_u32 s20, s20, 0x84000
	s_addc_u32 s21, s21, 0
	s_mov_b32 m0, s38
	v_lshl_add_u64 v[226:227], s[20:21], 0, v[134:135]
	ds_read_b128 v[190:193], v152 offset:32768
	ds_read_b128 v[194:197], v152 offset:33792
	ds_read_b128 v[198:201], v152 offset:34816
	ds_read_b128 v[202:205], v152 offset:35840
	ds_read_b128 v[206:209], v152 offset:36864
	ds_read_b128 v[210:213], v152 offset:37888
	ds_read_b128 v[214:217], v152 offset:38912
	ds_read_b128 v[218:221], v152 offset:39936
	global_load_lds_dwordx4 v[226:227], off
	v_lshl_add_u64 v[226:227], s[20:21], 0, v[130:131]
	s_mov_b32 m0, s39
	s_nop 0
	global_load_lds_dwordx4 v[226:227], off
	s_waitcnt vmcnt(8)
	s_waitcnt lgkmcnt(0)
	s_barrier
; #define PG8_STAGE(bufoff, gbase, voff) do { _Pragma("unroll") for (int _i = 0; _i < 2; ++_i) \
;         __builtin_amdgcn_global_load_lds((const unsigned*)((const char*)(gbase) + (voff)[_i]), (LAS unsigned*)(lds + (bufoff) + ldsw + _i * 8192), 16, 0, 0); } while (0)
; #define PG8_LDA(dst, b, h) do { _Pragma("unroll") for (int m = 0; m < 4; ++m) _Pragma("unroll") for (int k = 0; k < 2; ++k) dst[m][k] = *(const LAS bf16x8*)(lds + PG8_SA(b, h) + aoff + m * 2048 + k * 1024); } while (0)
; #define PG8_MMA(ai, bj, At, Bt) do { __builtin_amdgcn_s_setprio(1); _Pragma("unroll") for (int m = 0; m < 4; ++m) _Pragma("unroll") for (int n = 0; n < 2; ++n) _Pragma("unroll") for (int k = 0; k < 2; ++k) \
;         acc[ai][bj][m][n] = __builtin_amdgcn_mfma_f32_16x16x32_bf16(Bt[n][k], At[m][k], acc[ai][bj][m][n], 0, 0, 0); __builtin_amdgcn_s_setprio(0); } while (0)
; #define PG8_WAIT_V(n) asm volatile("s_waitcnt vmcnt(" #n ")" ::: "memory")
; #define PG8_WAIT_L(n) asm volatile("s_waitcnt lgkmcnt(" #n ")" ::: "memory")
; #define PG8_BAR __builtin_amdgcn_s_barrier()
; #define PG8_SCHED __builtin_amdgcn_sched_barrier(0)
; template <class EpiT>
; __device__ __forceinline__ void gemm_phase(LAS unsigned char* lds, const Gemm g, const StaticOrder& S, const EpiT& E) {
;     ...
;             PG8_WAIT_V(8); PG8_WAIT_L(0); PG8_BAR; PG8_MMA(0, 0, At, B0); PG8_MMA(0, 1, At, B1); PG8_BAR; PG8_SCHED;
;             PG8_LDA(At, 1, 1); PG8_STAGE(PG8_SB(1, 0), b3, voffB); PG8_STAGE(PG8_SB(1, 1), b3 + hstepB, voffB); PG8_STAGE(PG8_SA(1, 0), a3, voffA);
;             PG8_WAIT_V(8); PG8_WAIT_L(0); PG8_BAR; PG8_MMA(1, 0, At, B0); PG8_MMA(1, 1, At, B1); PG8_BAR; PG8_SCHED;
;         }
;         if (wr == 0) PG8_BAR;
	s_setprio 1
	s_waitcnt lgkmcnt(0)
	v_mfma_f32_16x16x32_bf16 v[124:127], v[154:157], v[190:193], v[124:127]
	v_mfma_f32_16x16x32_bf16 v[120:123], v[162:165], v[190:193], v[120:123]
	v_mfma_f32_16x16x32_bf16 v[108:111], v[154:157], v[198:201], v[108:111]
	v_mfma_f32_16x16x32_bf16 v[104:107], v[162:165], v[198:201], v[104:107]
	v_mfma_f32_16x16x32_bf16 v[92:95], v[154:157], v[206:209], v[92:95]
	v_mfma_f32_16x16x32_bf16 v[88:91], v[162:165], v[206:209], v[88:91]
	v_mfma_f32_16x16x32_bf16 v[76:79], v[154:157], v[214:217], v[76:79]
	v_mfma_f32_16x16x32_bf16 v[72:75], v[162:165], v[214:217], v[72:75]
	v_mfma_f32_16x16x32_bf16 v[124:127], v[158:161], v[194:197], v[124:127]
	v_mfma_f32_16x16x32_bf16 v[120:123], v[170:173], v[194:197], v[120:123]
	v_mfma_f32_16x16x32_bf16 v[108:111], v[158:161], v[202:205], v[108:111]
	v_mfma_f32_16x16x32_bf16 v[104:107], v[170:173], v[202:205], v[104:107]
	v_mfma_f32_16x16x32_bf16 v[92:95], v[158:161], v[210:213], v[92:95]
	v_mfma_f32_16x16x32_bf16 v[88:91], v[170:173], v[210:213], v[88:91]
	v_mfma_f32_16x16x32_bf16 v[76:79], v[158:161], v[218:221], v[76:79]
	v_mfma_f32_16x16x32_bf16 v[72:75], v[170:173], v[218:221], v[72:75]
	s_setprio 0
	s_setprio 1
	v_mfma_f32_16x16x32_bf16 v[116:119], v[174:177], v[190:193], v[116:119]
	v_mfma_f32_16x16x32_bf16 v[112:115], v[182:185], v[190:193], v[112:115]
	v_mfma_f32_16x16x32_bf16 v[100:103], v[174:177], v[198:201], v[100:103]
	v_mfma_f32_16x16x32_bf16 v[96:99], v[182:185], v[198:201], v[96:99]
	v_mfma_f32_16x16x32_bf16 v[84:87], v[174:177], v[206:209], v[84:87]
	v_mfma_f32_16x16x32_bf16 v[80:83], v[182:185], v[206:209], v[80:83]
	v_mfma_f32_16x16x32_bf16 v[68:71], v[174:177], v[214:217], v[68:71]
	v_mfma_f32_16x16x32_bf16 v[64:67], v[182:185], v[214:217], v[64:67]
	v_mfma_f32_16x16x32_bf16 v[116:119], v[178:181], v[194:197], v[116:119]
	v_mfma_f32_16x16x32_bf16 v[112:115], v[186:189], v[194:197], v[112:115]
	v_mfma_f32_16x16x32_bf16 v[100:103], v[178:181], v[202:205], v[100:103]
	v_mfma_f32_16x16x32_bf16 v[96:99], v[186:189], v[202:205], v[96:99]
	v_mfma_f32_16x16x32_bf16 v[84:87], v[178:181], v[210:213], v[84:87]
	v_mfma_f32_16x16x32_bf16 v[80:83], v[186:189], v[210:213], v[80:83]
	v_mfma_f32_16x16x32_bf16 v[68:71], v[178:181], v[218:221], v[68:71]
	v_mfma_f32_16x16x32_bf16 v[64:67], v[186:189], v[218:221], v[64:67]
	s_setprio 0
	s_barrier
	s_add_i32 s20, s54, s27
	v_lshl_add_u64 v[144:145], v[144:145], 0, s[10:11]
	s_mov_b32 m0, s20
	ds_read_b128 v[190:193], v152 offset:49152
	ds_read_b128 v[194:197], v152 offset:50176
	ds_read_b128 v[198:201], v152 offset:51200
	ds_read_b128 v[202:205], v152 offset:52224
	ds_read_b128 v[206:209], v152 offset:53248
	ds_read_b128 v[210:213], v152 offset:54272
	ds_read_b128 v[214:217], v152 offset:55296
	ds_read_b128 v[218:221], v152 offset:56320
	global_load_lds_dwordx4 v[144:145], off
	s_add_i32 m0, s20, 0x2000
	s_add_u32 s18, s18, 0x84080
	v_lshl_add_u64 v[144:145], v[166:167], 0, s[10:11]
	s_addc_u32 s19, s19, 0
	s_add_i32 s20, s55, s27
	global_load_lds_dwordx4 v[144:145], off
	v_lshl_add_u64 v[144:145], s[18:19], 0, v[132:133]
	s_mov_b32 m0, s20
	s_nop 0
	global_load_lds_dwordx4 v[144:145], off
	v_lshl_add_u64 v[144:145], s[18:19], 0, v[128:129]
	s_add_i32 m0, s20, 0x2000
	s_nop 0
	global_load_lds_dwordx4 v[144:145], off
	v_lshl_add_u64 v[144:145], v[222:223], 0, s[10:11]
	s_mov_b32 m0, s41
	s_nop 0
	global_load_lds_dwordx4 v[144:145], off
	v_lshl_add_u64 v[144:145], v[224:225], 0, s[10:11]
	s_mov_b32 m0, s42
	s_nop 0
	global_load_lds_dwordx4 v[144:145], off
	s_waitcnt vmcnt(8)
	s_waitcnt lgkmcnt(0)
	s_barrier
	s_setprio 1
	s_waitcnt lgkmcnt(0)
	v_mfma_f32_16x16x32_bf16 v[60:63], v[154:157], v[190:193], v[60:63]
	v_mfma_f32_16x16x32_bf16 v[56:59], v[162:165], v[190:193], v[56:59]
	v_mfma_f32_16x16x32_bf16 v[44:47], v[154:157], v[198:201], v[44:47]
	v_mfma_f32_16x16x32_bf16 v[40:43], v[162:165], v[198:201], v[40:43]
	v_mfma_f32_16x16x32_bf16 v[28:31], v[154:157], v[206:209], v[28:31]
	v_mfma_f32_16x16x32_bf16 v[24:27], v[162:165], v[206:209], v[24:27]
	v_mfma_f32_16x16x32_bf16 v[12:15], v[154:157], v[214:217], v[12:15]
	v_mfma_f32_16x16x32_bf16 v[8:11], v[162:165], v[214:217], v[8:11]
	v_mfma_f32_16x16x32_bf16 v[60:63], v[158:161], v[194:197], v[60:63]
	v_mfma_f32_16x16x32_bf16 v[56:59], v[170:173], v[194:197], v[56:59]
	v_mfma_f32_16x16x32_bf16 v[44:47], v[158:161], v[202:205], v[44:47]
	v_mfma_f32_16x16x32_bf16 v[40:43], v[170:173], v[202:205], v[40:43]
	v_mfma_f32_16x16x32_bf16 v[28:31], v[158:161], v[210:213], v[28:31]
	v_mfma_f32_16x16x32_bf16 v[24:27], v[170:173], v[210:213], v[24:27]
	v_mfma_f32_16x16x32_bf16 v[12:15], v[158:161], v[218:221], v[12:15]
	v_mfma_f32_16x16x32_bf16 v[8:11], v[170:173], v[218:221], v[8:11]
	s_setprio 0
	s_setprio 1
	v_mfma_f32_16x16x32_bf16 v[52:55], v[174:177], v[190:193], v[52:55]
	v_mfma_f32_16x16x32_bf16 v[48:51], v[182:185], v[190:193], v[48:51]
	v_mfma_f32_16x16x32_bf16 v[36:39], v[174:177], v[198:201], v[36:39]
	v_mfma_f32_16x16x32_bf16 v[32:35], v[182:185], v[198:201], v[32:35]
	v_mfma_f32_16x16x32_bf16 v[20:23], v[174:177], v[206:209], v[20:23]
	v_mfma_f32_16x16x32_bf16 v[16:19], v[182:185], v[206:209], v[16:19]
	v_mfma_f32_16x16x32_bf16 v[4:7], v[174:177], v[214:217], v[4:7]
	v_mfma_f32_16x16x32_bf16 v[0:3], v[182:185], v[214:217], v[0:3]
	v_mfma_f32_16x16x32_bf16 v[52:55], v[178:181], v[194:197], v[52:55]
	v_mfma_f32_16x16x32_bf16 v[48:51], v[186:189], v[194:197], v[48:51]
	v_mfma_f32_16x16x32_bf16 v[36:39], v[178:181], v[202:205], v[36:39]
	v_mfma_f32_16x16x32_bf16 v[32:35], v[186:189], v[202:205], v[32:35]
	v_mfma_f32_16x16x32_bf16 v[20:23], v[178:181], v[210:213], v[20:23]
	v_mfma_f32_16x16x32_bf16 v[16:19], v[186:189], v[210:213], v[16:19]
	v_mfma_f32_16x16x32_bf16 v[4:7], v[178:181], v[218:221], v[4:7]
	v_mfma_f32_16x16x32_bf16 v[0:3], v[186:189], v[218:221], v[0:3]
	s_setprio 0
	s_barrier
	s_add_i32 s53, s53, 2
	s_add_u32 s16, s16, 0x100
	s_addc_u32 s17, s17, 0
	s_add_u32 s51, s51, 0x100
	s_addc_u32 s52, s52, 0
	s_cmp_gt_u32 s53, 29
	s_cbranch_scc0 .LBB0_1156
	s_and_b64 vcc, exec, s[12:13]
	s_cbranch_vccz .LBB0_1159
	s_barrier

; #define PG8_BAR __builtin_amdgcn_s_barrier()
; template <class EpiT>
; __device__ __forceinline__ void gemm_phase(LAS unsigned char* lds, const Gemm g, const StaticOrder& S, const EpiT& E) {
;     ...
; #pragma unroll
;         for (int a = 0; a < 2; ++a)
; #pragma unroll
;             for (int b = 0; b < 2; ++b)
; #pragma unroll
;                 for (int m = 0; m < 4; ++m)
; #pragma unroll
;                     for (int n = 0; n < 2; ++n) acc[a][b][m][n] = (f32x4){0.f, 0.f, 0.f, 0.f};
;         cur = nxt; cA = nA; cB = nB; ++ui;
;         if (wr == 1) PG8_BAR;
.LBB0_1234:
	s_add_u32 s18, s18, 0x164080
	s_addc_u32 s19, s19, 0
	s_add_u32 s53, s20, 0x100
	v_mov_b32_e32 v0, 0
	s_addc_u32 s54, s21, 0
	s_mov_b32 s55, -2
	v_mov_b32_e32 v1, v0
	v_mov_b32_e32 v2, v0
	v_mov_b32_e32 v3, v0
	v_mov_b32_e32 v4, v0
	v_mov_b32_e32 v5, v0
	v_mov_b32_e32 v6, v0
	v_mov_b32_e32 v7, v0
	v_mov_b32_e32 v16, v0
	v_mov_b32_e32 v17, v0
	v_mov_b32_e32 v18, v0
	v_mov_b32_e32 v19, v0
	v_mov_b32_e32 v20, v0
	v_mov_b32_e32 v21, v0
	v_mov_b32_e32 v22, v0
	v_mov_b32_e32 v23, v0
	v_mov_b32_e32 v32, v0
	v_mov_b32_e32 v33, v0
	v_mov_b32_e32 v34, v0
	v_mov_b32_e32 v35, v0
	v_mov_b32_e32 v36, v0
	v_mov_b32_e32 v37, v0
	v_mov_b32_e32 v38, v0
	v_mov_b32_e32 v39, v0
	v_mov_b32_e32 v48, v0
	v_mov_b32_e32 v49, v0
	v_mov_b32_e32 v50, v0
	v_mov_b32_e32 v51, v0
	v_mov_b32_e32 v52, v0
	v_mov_b32_e32 v53, v0
	v_mov_b32_e32 v54, v0
	v_mov_b32_e32 v55, v0
	v_mov_b32_e32 v8, v0
	v_mov_b32_e32 v9, v0
	v_mov_b32_e32 v10, v0
	v_mov_b32_e32 v11, v0
	v_mov_b32_e32 v12, v0
	v_mov_b32_e32 v13, v0
	v_mov_b32_e32 v14, v0
	v_mov_b32_e32 v15, v0
	v_mov_b32_e32 v24, v0
	v_mov_b32_e32 v25, v0
	v_mov_b32_e32 v26, v0
	v_mov_b32_e32 v27, v0
	v_mov_b32_e32 v28, v0
	v_mov_b32_e32 v29, v0
	v_mov_b32_e32 v30, v0
	v_mov_b32_e32 v31, v0
	v_mov_b32_e32 v40, v0
	v_mov_b32_e32 v41, v0
	v_mov_b32_e32 v42, v0
	v_mov_b32_e32 v43, v0
	v_mov_b32_e32 v44, v0
	v_mov_b32_e32 v45, v0
	v_mov_b32_e32 v46, v0
	v_mov_b32_e32 v47, v0
	v_mov_b32_e32 v56, v0
	v_mov_b32_e32 v57, v0
	v_mov_b32_e32 v58, v0
	v_mov_b32_e32 v59, v0
	v_mov_b32_e32 v60, v0
	v_mov_b32_e32 v61, v0
	v_mov_b32_e32 v62, v0
	v_mov_b32_e32 v63, v0
	v_mov_b32_e32 v64, v0
	v_mov_b32_e32 v65, v0
	v_mov_b32_e32 v66, v0
	v_mov_b32_e32 v67, v0
	v_mov_b32_e32 v68, v0
	v_mov_b32_e32 v69, v0
	v_mov_b32_e32 v70, v0
	v_mov_b32_e32 v71, v0
	v_mov_b32_e32 v80, v0
	v_mov_b32_e32 v81, v0
	v_mov_b32_e32 v82, v0
	v_mov_b32_e32 v83, v0
	v_mov_b32_e32 v84, v0
	v_mov_b32_e32 v85, v0
	v_mov_b32_e32 v86, v0
	v_mov_b32_e32 v87, v0
	v_mov_b32_e32 v96, v0
	v_mov_b32_e32 v97, v0
	v_mov_b32_e32 v98, v0
	v_mov_b32_e32 v99, v0
	v_mov_b32_e32 v100, v0
	v_mov_b32_e32 v101, v0
	v_mov_b32_e32 v102, v0
	v_mov_b32_e32 v103, v0
	v_mov_b32_e32 v112, v0
	v_mov_b32_e32 v113, v0
	v_mov_b32_e32 v114, v0
	v_mov_b32_e32 v115, v0
	v_mov_b32_e32 v116, v0
	v_mov_b32_e32 v117, v0
	v_mov_b32_e32 v118, v0
	v_mov_b32_e32 v119, v0
	v_mov_b32_e32 v72, v0
	v_mov_b32_e32 v73, v0
	v_mov_b32_e32 v74, v0
	v_mov_b32_e32 v75, v0
	v_mov_b32_e32 v76, v0
	v_mov_b32_e32 v77, v0
	v_mov_b32_e32 v78, v0
	v_mov_b32_e32 v79, v0
	v_mov_b32_e32 v88, v0
	v_mov_b32_e32 v89, v0
	v_mov_b32_e32 v90, v0
	v_mov_b32_e32 v91, v0
	v_mov_b32_e32 v92, v0
	v_mov_b32_e32 v93, v0
	v_mov_b32_e32 v94, v0
	v_mov_b32_e32 v95, v0
	v_mov_b32_e32 v104, v0
	v_mov_b32_e32 v105, v0
	v_mov_b32_e32 v106, v0
	v_mov_b32_e32 v107, v0
	v_mov_b32_e32 v108, v0
	v_mov_b32_e32 v109, v0
	v_mov_b32_e32 v110, v0
	v_mov_b32_e32 v111, v0
	v_mov_b32_e32 v120, v0
	v_mov_b32_e32 v121, v0
	v_mov_b32_e32 v122, v0
	v_mov_b32_e32 v123, v0
	v_mov_b32_e32 v124, v0
	v_mov_b32_e32 v125, v0
	v_mov_b32_e32 v126, v0
	v_mov_b32_e32 v127, v0
	.p2alignl 6, 3212836864
	s_nop 0
	s_nop 0
	s_nop 0
	s_nop 0
	s_nop 0
	s_nop 0
	s_nop 0
	s_nop 0
	s_nop 0
	s_nop 0
	s_nop 0
	s_nop 0
	s_nop 0
	s_nop 0
